# B-fragment-ordered k-step pairing plus setprio 0/1 toggle after every accumulator pair
# baseline (speedup 1.0000x reference)
.LBB0_257:
	s_or_b64 exec, exec, s[50:51]
	s_add_u32 s0, s12, s6
	ds_read_b128 v[146:149], v137
	ds_read_b128 v[150:153], v137 offset:1024
	ds_read_b128 v[154:157], v137 offset:2048
	ds_read_b128 v[158:161], v137 offset:3072
	ds_read_b128 v[162:165], v138
	ds_read_b128 v[166:169], v138 offset:1024
	ds_read_b128 v[170:173], v138 offset:2048
	ds_read_b128 v[174:177], v138 offset:3072
	s_addc_u32 s1, s13, s7
	s_add_u32 s50, s0, 0x20000
	s_addc_u32 s51, s1, 0
	s_add_u32 s52, s93, s6
	s_addc_u32 s53, s94, s7
	s_cmp_eq_u32 s6, 0x60000
	s_cselect_b32 s62, s95, s50
	s_cselect_b32 s63, s31, s51
	s_cselect_b32 s51, s29, s53
	s_cselect_b32 s50, s96, s52
	s_add_u32 s52, s62, 0x8000
	s_addc_u32 s53, s63, 0
	s_add_u32 s54, s50, 0x8000
	s_addc_u32 s55, s51, 0
	ds_read_b128 v[178:181], v139
	ds_read_b128 v[182:185], v139 offset:1024
	ds_read_b128 v[186:189], v139 offset:2048
	ds_read_b128 v[190:193], v139 offset:3072
	ds_read_b128 v[198:201], v139 offset:4096
	ds_read_b128 v[202:205], v139 offset:5120
	ds_read_b128 v[206:209], v139 offset:6144
	ds_read_b128 v[212:215], v139 offset:7168
	s_add_u32 s0, s0, 0x1c000
	s_addc_u32 s1, s1, 0
	s_mov_b32 m0, s78
	s_nop 0
	global_load_lds_dwordx4 v134, s[0:1]
	s_add_u32 m0, s78, 0x2000
	s_nop 0
	global_load_lds_dwordx4 v135, s[0:1]
	s_waitcnt vmcnt(8)
	s_waitcnt lgkmcnt(0)
	s_setprio 1
	s_barrier
	v_mfma_f32_16x16x32_bf16 v[122:125], v[146:149], v[178:181], v[122:125]
	v_mfma_f32_16x16x32_bf16 v[122:125], v[150:153], v[182:185], v[122:125]
	s_waitcnt lgkmcnt(5)
	s_setprio 0
	s_setprio 1
	v_mfma_f32_16x16x32_bf16 v[106:109], v[146:149], v[186:189], v[106:109]
	v_mfma_f32_16x16x32_bf16 v[106:109], v[150:153], v[190:193], v[106:109]
	s_waitcnt lgkmcnt(3)
	s_setprio 0
	s_setprio 1
	v_mfma_f32_16x16x32_bf16 v[90:93], v[146:149], v[198:201], v[90:93]
	v_mfma_f32_16x16x32_bf16 v[90:93], v[150:153], v[202:205], v[90:93]
	s_waitcnt lgkmcnt(1)
	s_setprio 0
	s_setprio 1
	v_mfma_f32_16x16x32_bf16 v[74:77], v[146:149], v[206:209], v[74:77]
	v_mfma_f32_16x16x32_bf16 v[74:77], v[150:153], v[212:215], v[74:77]
	s_setprio 0
	s_setprio 1
	v_mfma_f32_16x16x32_bf16 v[114:117], v[154:157], v[178:181], v[114:117]
	v_mfma_f32_16x16x32_bf16 v[114:117], v[158:161], v[182:185], v[114:117]
	s_setprio 0
	s_setprio 1
	v_mfma_f32_16x16x32_bf16 v[98:101], v[154:157], v[186:189], v[98:101]
	v_mfma_f32_16x16x32_bf16 v[98:101], v[158:161], v[190:193], v[98:101]
	s_setprio 0
	s_setprio 1
	v_mfma_f32_16x16x32_bf16 v[82:85], v[154:157], v[198:201], v[82:85]
	v_mfma_f32_16x16x32_bf16 v[82:85], v[158:161], v[202:205], v[82:85]
	s_waitcnt lgkmcnt(0)
	s_setprio 0
	s_setprio 1
	v_mfma_f32_16x16x32_bf16 v[66:69], v[154:157], v[206:209], v[66:69]
	v_mfma_f32_16x16x32_bf16 v[66:69], v[158:161], v[212:215], v[66:69]
	s_setprio 0
	s_setprio 1
	v_mfma_f32_16x16x32_bf16 v[126:129], v[162:165], v[178:181], v[126:129]
	v_mfma_f32_16x16x32_bf16 v[126:129], v[166:169], v[182:185], v[126:129]
	s_setprio 0
	s_setprio 1
	v_mfma_f32_16x16x32_bf16 v[110:113], v[162:165], v[186:189], v[110:113]
	v_mfma_f32_16x16x32_bf16 v[110:113], v[166:169], v[190:193], v[110:113]
	s_setprio 0
	s_setprio 1
	v_mfma_f32_16x16x32_bf16 v[94:97], v[162:165], v[198:201], v[94:97]
	v_mfma_f32_16x16x32_bf16 v[94:97], v[166:169], v[202:205], v[94:97]
	s_setprio 0
	s_setprio 1
	v_mfma_f32_16x16x32_bf16 v[78:81], v[162:165], v[206:209], v[78:81]
	v_mfma_f32_16x16x32_bf16 v[78:81], v[166:169], v[212:215], v[78:81]
	s_setprio 0
	s_setprio 1
	v_mfma_f32_16x16x32_bf16 v[118:121], v[170:173], v[178:181], v[118:121]
	v_mfma_f32_16x16x32_bf16 v[118:121], v[174:177], v[182:185], v[118:121]
	s_setprio 0
	s_setprio 1
	v_mfma_f32_16x16x32_bf16 v[102:105], v[170:173], v[186:189], v[102:105]
	v_mfma_f32_16x16x32_bf16 v[102:105], v[174:177], v[190:193], v[102:105]
	s_setprio 0
	s_setprio 1
	v_mfma_f32_16x16x32_bf16 v[86:89], v[170:173], v[198:201], v[86:89]
	v_mfma_f32_16x16x32_bf16 v[86:89], v[174:177], v[202:205], v[86:89]
	s_setprio 2
	s_barrier
	v_mfma_f32_16x16x32_bf16 v[70:73], v[170:173], v[206:209], v[70:73]
	v_mfma_f32_16x16x32_bf16 v[70:73], v[174:177], v[212:215], v[70:73]
	s_setprio 0
	s_nop 0
	ds_read_b128 v[178:181], v139 offset:16384
	ds_read_b128 v[182:185], v139 offset:17408
	ds_read_b128 v[186:189], v139 offset:18432
	ds_read_b128 v[190:193], v139 offset:19456
	ds_read_b128 v[198:201], v139 offset:20480
	ds_read_b128 v[202:205], v139 offset:21504
	ds_read_b128 v[206:209], v139 offset:22528
	ds_read_b128 v[212:215], v139 offset:23552
	s_mov_b32 m0, s11
	s_nop 0
	global_load_lds_dwordx4 v134, s[50:51]
	s_add_u32 m0, s11, 0x2000
	s_nop 0
	global_load_lds_dwordx4 v135, s[50:51]
	s_add_u32 s0, s50, 0x4000
	s_addc_u32 s1, s51, 0
	s_mov_b32 m0, s68
	s_nop 0
	global_load_lds_dwordx4 v134, s[0:1]
	s_add_u32 m0, s68, 0x2000
	s_nop 0
	global_load_lds_dwordx4 v135, s[0:1]
	s_nop 0
	s_mov_b32 m0, s65
	s_nop 0
	global_load_lds_dwordx4 v134, s[62:63]
	s_add_u32 m0, s65, 0x2000
	s_nop 0
	global_load_lds_dwordx4 v135, s[62:63]
	s_waitcnt vmcnt(8)
	s_waitcnt lgkmcnt(0)
	s_setprio 1
	s_barrier
	v_mfma_f32_16x16x32_bf16 v[58:61], v[146:149], v[178:181], v[58:61]
	v_mfma_f32_16x16x32_bf16 v[58:61], v[150:153], v[182:185], v[58:61]
	s_waitcnt lgkmcnt(5)
	s_setprio 0
	s_setprio 1
	v_mfma_f32_16x16x32_bf16 v[42:45], v[146:149], v[186:189], v[42:45]
	v_mfma_f32_16x16x32_bf16 v[42:45], v[150:153], v[190:193], v[42:45]
	s_waitcnt lgkmcnt(3)
	s_setprio 0
	s_setprio 1
	v_mfma_f32_16x16x32_bf16 v[26:29], v[146:149], v[198:201], v[26:29]
	v_mfma_f32_16x16x32_bf16 v[26:29], v[150:153], v[202:205], v[26:29]
	s_waitcnt lgkmcnt(1)
	s_setprio 0
	s_setprio 1
	v_mfma_f32_16x16x32_bf16 v[10:13], v[146:149], v[206:209], v[10:13]
	v_mfma_f32_16x16x32_bf16 v[10:13], v[150:153], v[212:215], v[10:13]
	s_setprio 0
	s_setprio 1
	v_mfma_f32_16x16x32_bf16 v[50:53], v[154:157], v[178:181], v[50:53]
	v_mfma_f32_16x16x32_bf16 v[50:53], v[158:161], v[182:185], v[50:53]
	s_setprio 0
	s_setprio 1
	v_mfma_f32_16x16x32_bf16 v[34:37], v[154:157], v[186:189], v[34:37]
	v_mfma_f32_16x16x32_bf16 v[34:37], v[158:161], v[190:193], v[34:37]
	s_setprio 0
	s_setprio 1
	v_mfma_f32_16x16x32_bf16 v[18:21], v[154:157], v[198:201], v[18:21]
	v_mfma_f32_16x16x32_bf16 v[18:21], v[158:161], v[202:205], v[18:21]
	s_waitcnt lgkmcnt(0)
	s_setprio 0
	s_setprio 1
	v_mfma_f32_16x16x32_bf16 v[2:5], v[154:157], v[206:209], v[2:5]
	v_mfma_f32_16x16x32_bf16 v[2:5], v[158:161], v[212:215], v[2:5]
	s_setprio 0
	s_setprio 1
	v_mfma_f32_16x16x32_bf16 v[62:65], v[162:165], v[178:181], v[62:65]
	v_mfma_f32_16x16x32_bf16 v[62:65], v[166:169], v[182:185], v[62:65]
	s_setprio 0
	s_setprio 1
	v_mfma_f32_16x16x32_bf16 v[46:49], v[162:165], v[186:189], v[46:49]
	v_mfma_f32_16x16x32_bf16 v[46:49], v[166:169], v[190:193], v[46:49]
	s_setprio 0
	s_setprio 1
	v_mfma_f32_16x16x32_bf16 v[30:33], v[162:165], v[198:201], v[30:33]
	v_mfma_f32_16x16x32_bf16 v[30:33], v[166:169], v[202:205], v[30:33]
	s_setprio 0
	s_setprio 1
	v_mfma_f32_16x16x32_bf16 v[14:17], v[162:165], v[206:209], v[14:17]
	v_mfma_f32_16x16x32_bf16 v[14:17], v[166:169], v[212:215], v[14:17]
	s_setprio 0
	s_setprio 1
	v_mfma_f32_16x16x32_bf16 v[54:57], v[170:173], v[178:181], v[54:57]
	v_mfma_f32_16x16x32_bf16 v[54:57], v[174:177], v[182:185], v[54:57]
	s_setprio 0
	s_setprio 1
	v_mfma_f32_16x16x32_bf16 v[38:41], v[170:173], v[186:189], v[38:41]
	v_mfma_f32_16x16x32_bf16 v[38:41], v[174:177], v[190:193], v[38:41]
	s_setprio 0
	s_setprio 1
	v_mfma_f32_16x16x32_bf16 v[22:25], v[170:173], v[198:201], v[22:25]
	v_mfma_f32_16x16x32_bf16 v[22:25], v[174:177], v[202:205], v[22:25]
	s_setprio 2
	s_barrier
	v_mfma_f32_16x16x32_bf16 v[6:9], v[170:173], v[206:209], v[6:9]
	v_mfma_f32_16x16x32_bf16 v[6:9], v[174:177], v[212:215], v[6:9]
	s_setprio 0
	s_nop 0
	ds_read_b128 v[146:149], v140
	ds_read_b128 v[150:153], v140 offset:1024
	ds_read_b128 v[154:157], v140 offset:2048
	ds_read_b128 v[158:161], v140 offset:3072
	ds_read_b128 v[162:165], v141
	ds_read_b128 v[166:169], v141 offset:1024
	ds_read_b128 v[170:173], v141 offset:2048
	ds_read_b128 v[174:177], v141 offset:3072
	ds_read_b128 v[178:181], v139 offset:32768
	ds_read_b128 v[182:185], v139 offset:33792
	ds_read_b128 v[186:189], v139 offset:34816
	ds_read_b128 v[190:193], v139 offset:35840
	ds_read_b128 v[198:201], v139 offset:36864
	ds_read_b128 v[202:205], v139 offset:37888
	ds_read_b128 v[206:209], v139 offset:38912
	ds_read_b128 v[212:215], v139 offset:39936
	s_add_u32 s0, s62, 0x4000
	s_addc_u32 s1, s63, 0
	s_mov_b32 m0, s69
	s_nop 0
	global_load_lds_dwordx4 v134, s[0:1]
	s_add_u32 m0, s69, 0x2000
	s_nop 0
	global_load_lds_dwordx4 v135, s[0:1]
	s_waitcnt vmcnt(8)
	s_waitcnt lgkmcnt(0)
	s_setprio 1
	s_barrier
	v_mfma_f32_16x16x32_bf16 v[122:125], v[146:149], v[178:181], v[122:125]
	v_mfma_f32_16x16x32_bf16 v[122:125], v[150:153], v[182:185], v[122:125]
	s_waitcnt lgkmcnt(5)
	s_setprio 0
	s_setprio 1
	v_mfma_f32_16x16x32_bf16 v[106:109], v[146:149], v[186:189], v[106:109]
	v_mfma_f32_16x16x32_bf16 v[106:109], v[150:153], v[190:193], v[106:109]
	s_waitcnt lgkmcnt(3)
	s_setprio 0
	s_setprio 1
	v_mfma_f32_16x16x32_bf16 v[90:93], v[146:149], v[198:201], v[90:93]
	v_mfma_f32_16x16x32_bf16 v[90:93], v[150:153], v[202:205], v[90:93]
	s_waitcnt lgkmcnt(1)
	s_setprio 0
	s_setprio 1
	v_mfma_f32_16x16x32_bf16 v[74:77], v[146:149], v[206:209], v[74:77]
	v_mfma_f32_16x16x32_bf16 v[74:77], v[150:153], v[212:215], v[74:77]
	s_setprio 0
	s_setprio 1
	v_mfma_f32_16x16x32_bf16 v[114:117], v[154:157], v[178:181], v[114:117]
	v_mfma_f32_16x16x32_bf16 v[114:117], v[158:161], v[182:185], v[114:117]
	s_setprio 0
	s_setprio 1
	v_mfma_f32_16x16x32_bf16 v[98:101], v[154:157], v[186:189], v[98:101]
	v_mfma_f32_16x16x32_bf16 v[98:101], v[158:161], v[190:193], v[98:101]
	s_setprio 0
	s_setprio 1
	v_mfma_f32_16x16x32_bf16 v[82:85], v[154:157], v[198:201], v[82:85]
	v_mfma_f32_16x16x32_bf16 v[82:85], v[158:161], v[202:205], v[82:85]
	s_waitcnt lgkmcnt(0)
	s_setprio 0
	s_setprio 1
	v_mfma_f32_16x16x32_bf16 v[66:69], v[154:157], v[206:209], v[66:69]
	v_mfma_f32_16x16x32_bf16 v[66:69], v[158:161], v[212:215], v[66:69]
	s_setprio 0
	s_setprio 1
	v_mfma_f32_16x16x32_bf16 v[126:129], v[162:165], v[178:181], v[126:129]
	v_mfma_f32_16x16x32_bf16 v[126:129], v[166:169], v[182:185], v[126:129]
	s_setprio 0
	s_setprio 1
	v_mfma_f32_16x16x32_bf16 v[110:113], v[162:165], v[186:189], v[110:113]
	v_mfma_f32_16x16x32_bf16 v[110:113], v[166:169], v[190:193], v[110:113]
	s_setprio 0
	s_setprio 1
	v_mfma_f32_16x16x32_bf16 v[94:97], v[162:165], v[198:201], v[94:97]
	v_mfma_f32_16x16x32_bf16 v[94:97], v[166:169], v[202:205], v[94:97]
	s_setprio 0
	s_setprio 1
	v_mfma_f32_16x16x32_bf16 v[78:81], v[162:165], v[206:209], v[78:81]
	v_mfma_f32_16x16x32_bf16 v[78:81], v[166:169], v[212:215], v[78:81]
	s_setprio 0
	s_setprio 1
	v_mfma_f32_16x16x32_bf16 v[118:121], v[170:173], v[178:181], v[118:121]
	v_mfma_f32_16x16x32_bf16 v[118:121], v[174:177], v[182:185], v[118:121]
	s_setprio 0
	s_setprio 1
	v_mfma_f32_16x16x32_bf16 v[102:105], v[170:173], v[186:189], v[102:105]
	v_mfma_f32_16x16x32_bf16 v[102:105], v[174:177], v[190:193], v[102:105]
	s_setprio 0
	s_setprio 1
	v_mfma_f32_16x16x32_bf16 v[86:89], v[170:173], v[198:201], v[86:89]
	v_mfma_f32_16x16x32_bf16 v[86:89], v[174:177], v[202:205], v[86:89]
	s_setprio 2
	s_barrier
	v_mfma_f32_16x16x32_bf16 v[70:73], v[170:173], v[206:209], v[70:73]
	v_mfma_f32_16x16x32_bf16 v[70:73], v[174:177], v[212:215], v[70:73]
	s_setprio 0
	s_nop 0
	ds_read_b128 v[178:181], v139 offset:49152
	ds_read_b128 v[182:185], v139 offset:50176
	ds_read_b128 v[186:189], v139 offset:51200
	ds_read_b128 v[190:193], v139 offset:52224
	ds_read_b128 v[198:201], v139 offset:53248
	ds_read_b128 v[202:205], v139 offset:54272
	ds_read_b128 v[206:209], v139 offset:55296
	ds_read_b128 v[212:215], v139 offset:56320
	s_mov_b32 m0, s74
	s_nop 0
	global_load_lds_dwordx4 v134, s[54:55]
	s_add_u32 m0, s74, 0x2000
	s_nop 0
	global_load_lds_dwordx4 v135, s[54:55]
	s_add_u32 s0, s50, 0xc000
	s_addc_u32 s1, s51, 0
	s_mov_b32 m0, s77
	s_nop 0
	global_load_lds_dwordx4 v134, s[0:1]
	s_add_u32 m0, s77, 0x2000
	s_nop 0
	global_load_lds_dwordx4 v135, s[0:1]
	s_nop 0
	s_mov_b32 m0, s76
	s_nop 0
	global_load_lds_dwordx4 v134, s[52:53]
	s_add_u32 m0, s76, 0x2000
	s_nop 0
	global_load_lds_dwordx4 v135, s[52:53]
	s_waitcnt vmcnt(8)
	s_waitcnt lgkmcnt(0)
	s_setprio 1
	s_barrier
	v_mfma_f32_16x16x32_bf16 v[58:61], v[146:149], v[178:181], v[58:61]
	v_mfma_f32_16x16x32_bf16 v[58:61], v[150:153], v[182:185], v[58:61]
	s_waitcnt lgkmcnt(5)
	s_setprio 0
	s_setprio 1
	v_mfma_f32_16x16x32_bf16 v[42:45], v[146:149], v[186:189], v[42:45]
	v_mfma_f32_16x16x32_bf16 v[42:45], v[150:153], v[190:193], v[42:45]
	s_waitcnt lgkmcnt(3)
	s_setprio 0
	s_setprio 1
	v_mfma_f32_16x16x32_bf16 v[26:29], v[146:149], v[198:201], v[26:29]
	v_mfma_f32_16x16x32_bf16 v[26:29], v[150:153], v[202:205], v[26:29]
	s_waitcnt lgkmcnt(1)
	s_setprio 0
	s_setprio 1
	v_mfma_f32_16x16x32_bf16 v[10:13], v[146:149], v[206:209], v[10:13]
	v_mfma_f32_16x16x32_bf16 v[10:13], v[150:153], v[212:215], v[10:13]
	s_setprio 0
	s_setprio 1
	v_mfma_f32_16x16x32_bf16 v[50:53], v[154:157], v[178:181], v[50:53]
	v_mfma_f32_16x16x32_bf16 v[50:53], v[158:161], v[182:185], v[50:53]
	s_setprio 0
	s_setprio 1
	v_mfma_f32_16x16x32_bf16 v[34:37], v[154:157], v[186:189], v[34:37]
	v_mfma_f32_16x16x32_bf16 v[34:37], v[158:161], v[190:193], v[34:37]
	s_setprio 0
	s_setprio 1
	v_mfma_f32_16x16x32_bf16 v[18:21], v[154:157], v[198:201], v[18:21]
	v_mfma_f32_16x16x32_bf16 v[18:21], v[158:161], v[202:205], v[18:21]
	s_waitcnt lgkmcnt(0)
	s_setprio 0
	s_setprio 1
	v_mfma_f32_16x16x32_bf16 v[2:5], v[154:157], v[206:209], v[2:5]
	v_mfma_f32_16x16x32_bf16 v[2:5], v[158:161], v[212:215], v[2:5]
	s_setprio 0
	s_setprio 1
	v_mfma_f32_16x16x32_bf16 v[62:65], v[162:165], v[178:181], v[62:65]
	v_mfma_f32_16x16x32_bf16 v[62:65], v[166:169], v[182:185], v[62:65]
	s_setprio 0
	s_setprio 1
	v_mfma_f32_16x16x32_bf16 v[46:49], v[162:165], v[186:189], v[46:49]
	v_mfma_f32_16x16x32_bf16 v[46:49], v[166:169], v[190:193], v[46:49]
	s_setprio 0
	s_setprio 1
	v_mfma_f32_16x16x32_bf16 v[30:33], v[162:165], v[198:201], v[30:33]
	v_mfma_f32_16x16x32_bf16 v[30:33], v[166:169], v[202:205], v[30:33]
	s_setprio 0
	s_setprio 1
	v_mfma_f32_16x16x32_bf16 v[14:17], v[162:165], v[206:209], v[14:17]
	v_mfma_f32_16x16x32_bf16 v[14:17], v[166:169], v[212:215], v[14:17]
	s_setprio 0
	s_setprio 1
	v_mfma_f32_16x16x32_bf16 v[54:57], v[170:173], v[178:181], v[54:57]
	v_mfma_f32_16x16x32_bf16 v[54:57], v[174:177], v[182:185], v[54:57]
	s_setprio 0
	s_setprio 1
	v_mfma_f32_16x16x32_bf16 v[38:41], v[170:173], v[186:189], v[38:41]
	v_mfma_f32_16x16x32_bf16 v[38:41], v[174:177], v[190:193], v[38:41]
	s_setprio 0
	s_setprio 1
	v_mfma_f32_16x16x32_bf16 v[22:25], v[170:173], v[198:201], v[22:25]
	v_mfma_f32_16x16x32_bf16 v[22:25], v[174:177], v[202:205], v[22:25]
	s_setprio 2
	s_barrier
	v_mfma_f32_16x16x32_bf16 v[6:9], v[170:173], v[206:209], v[6:9]
	v_mfma_f32_16x16x32_bf16 v[6:9], v[174:177], v[212:215], v[6:9]
	s_setprio 0
	s_nop 0
	s_add_i32 s97, s97, 2
	s_add_u32 s6, s6, 0x10000
	s_addc_u32 s7, s7, 0
	s_cmp_gt_u32 s97, 13
	s_cbranch_scc1 .LBB0_259
	v_mov_b32_e32 v145, v130
	s_branch .LBB0_255

.LBB0_364:
	s_add_i32 s26, s93, 2
	s_lshl_b64 s[62:63], s[26:27], 15
	s_add_u32 s64, s18, s62
	s_addc_u32 s65, s19, s63
	s_and_b64 s[52:53], s[50:51], exec
	s_cselect_b32 s53, s65, s39
	s_cselect_b32 s52, s64, s38
	s_add_u32 s62, s20, s62
	s_waitcnt vmcnt(8)
	s_addc_u32 s63, s21, s63
	s_waitcnt lgkmcnt(0)
	s_and_b64 s[50:51], s[50:51], exec
	s_cselect_b32 s51, s63, s49
	s_cselect_b32 s50, s62, s48
	s_setprio 1
	s_barrier
	v_mfma_f32_16x16x32_bf16 v[126:129], v[146:149], v[186:189], v[126:129]
	v_mfma_f32_16x16x32_bf16 v[126:129], v[150:153], v[190:193], v[126:129]
	s_waitcnt lgkmcnt(5)
	s_setprio 0
	s_setprio 1
	v_mfma_f32_16x16x32_bf16 v[118:121], v[146:149], v[178:181], v[118:121]
	v_mfma_f32_16x16x32_bf16 v[118:121], v[150:153], v[182:185], v[118:121]
	s_waitcnt lgkmcnt(3)
	s_setprio 0
	s_setprio 1
	v_mfma_f32_16x16x32_bf16 v[110:113], v[146:149], v[170:173], v[110:113]
	v_mfma_f32_16x16x32_bf16 v[110:113], v[150:153], v[174:177], v[110:113]
	s_waitcnt lgkmcnt(1)
	s_setprio 0
	s_setprio 1
	v_mfma_f32_16x16x32_bf16 v[102:105], v[146:149], v[162:165], v[102:105]
	v_mfma_f32_16x16x32_bf16 v[102:105], v[150:153], v[166:169], v[102:105]
	s_setprio 0
	s_setprio 1
	v_mfma_f32_16x16x32_bf16 v[122:125], v[154:157], v[186:189], v[122:125]
	v_mfma_f32_16x16x32_bf16 v[122:125], v[158:161], v[190:193], v[122:125]
	s_setprio 0
	s_setprio 1
	v_mfma_f32_16x16x32_bf16 v[114:117], v[154:157], v[178:181], v[114:117]
	v_mfma_f32_16x16x32_bf16 v[114:117], v[158:161], v[182:185], v[114:117]
	s_setprio 0
	s_setprio 1
	v_mfma_f32_16x16x32_bf16 v[106:109], v[154:157], v[170:173], v[106:109]
	v_mfma_f32_16x16x32_bf16 v[106:109], v[158:161], v[174:177], v[106:109]
	s_waitcnt lgkmcnt(0)
	s_setprio 0
	s_setprio 1
	v_mfma_f32_16x16x32_bf16 v[98:101], v[154:157], v[162:165], v[98:101]
	v_mfma_f32_16x16x32_bf16 v[98:101], v[158:161], v[166:169], v[98:101]
	s_setprio 0
	s_setprio 1
	v_mfma_f32_16x16x32_bf16 v[94:97], v[130:133], v[186:189], v[94:97]
	v_mfma_f32_16x16x32_bf16 v[94:97], v[134:137], v[190:193], v[94:97]
	s_setprio 0
	s_setprio 1
	v_mfma_f32_16x16x32_bf16 v[86:89], v[130:133], v[178:181], v[86:89]
	v_mfma_f32_16x16x32_bf16 v[86:89], v[134:137], v[182:185], v[86:89]
	s_setprio 0
	s_setprio 1
	v_mfma_f32_16x16x32_bf16 v[78:81], v[130:133], v[170:173], v[78:81]
	v_mfma_f32_16x16x32_bf16 v[78:81], v[134:137], v[174:177], v[78:81]
	s_setprio 0
	s_setprio 1
	v_mfma_f32_16x16x32_bf16 v[70:73], v[130:133], v[162:165], v[70:73]
	v_mfma_f32_16x16x32_bf16 v[70:73], v[134:137], v[166:169], v[70:73]
	s_setprio 0
	s_setprio 1
	v_mfma_f32_16x16x32_bf16 v[90:93], v[138:141], v[186:189], v[90:93]
	v_mfma_f32_16x16x32_bf16 v[90:93], v[142:145], v[190:193], v[90:93]
	s_setprio 0
	s_setprio 1
	v_mfma_f32_16x16x32_bf16 v[82:85], v[138:141], v[178:181], v[82:85]
	v_mfma_f32_16x16x32_bf16 v[82:85], v[142:145], v[182:185], v[82:85]
	s_setprio 0
	s_setprio 1
	v_mfma_f32_16x16x32_bf16 v[74:77], v[138:141], v[170:173], v[74:77]
	v_mfma_f32_16x16x32_bf16 v[74:77], v[142:145], v[174:177], v[74:77]
	s_setprio 2
	s_barrier
	v_mfma_f32_16x16x32_bf16 v[66:69], v[138:141], v[162:165], v[66:69]
	v_mfma_f32_16x16x32_bf16 v[66:69], v[142:145], v[166:169], v[66:69]
	s_setprio 0
	s_nop 0
	ds_read_b128 v[186:189], v219 offset:16384
	ds_read_b128 v[190:193], v219 offset:17408
	ds_read_b128 v[178:181], v219 offset:18432
	ds_read_b128 v[182:185], v219 offset:19456
	ds_read_b128 v[170:173], v219 offset:20480
	ds_read_b128 v[174:177], v219 offset:21504
	ds_read_b128 v[162:165], v219 offset:22528
	ds_read_b128 v[166:169], v219 offset:23552
	s_mov_b32 m0, s74
	s_nop 0
	global_load_lds_dwordx4 v195, s[50:51]
	s_add_u32 m0, s74, 0x2000
	s_nop 0
	global_load_lds_dwordx4 v212, s[50:51]
	s_add_u32 s62, s50, 0x4000
	s_addc_u32 s63, s51, 0
	s_mov_b32 m0, s75
	s_nop 0
	global_load_lds_dwordx4 v195, s[62:63]
	s_add_u32 m0, s75, 0x2000
	s_nop 0
	global_load_lds_dwordx4 v212, s[62:63]
	s_andn2_b64 vcc, exec, s[54:55]
	s_mov_b32 m0, s73
	s_nop 0
	global_load_lds_dwordx4 v195, s[52:53]
	s_add_u32 m0, s73, 0x2000
	s_nop 0
	global_load_lds_dwordx4 v212, s[52:53]
	s_cbranch_vccnz .LBB0_366
	v_mov_b32_e32 v2, 0
	v_mov_b32_e32 v3, v2
	v_mov_b32_e32 v4, v2
	v_mov_b32_e32 v5, v2
	v_mov_b32_e32 v6, v2
	v_mov_b32_e32 v7, v2
	v_mov_b32_e32 v8, v2
	v_mov_b32_e32 v9, v2
	v_mov_b32_e32 v10, v2
	v_mov_b32_e32 v11, v2
	v_mov_b32_e32 v12, v2
	v_mov_b32_e32 v13, v2
	v_mov_b32_e32 v14, v2
	v_mov_b32_e32 v15, v2
	v_mov_b32_e32 v16, v2
	v_mov_b32_e32 v17, v2
	v_mov_b32_e32 v18, v2
	v_mov_b32_e32 v19, v2
	v_mov_b32_e32 v20, v2
	v_mov_b32_e32 v21, v2
	v_mov_b32_e32 v22, v2
	v_mov_b32_e32 v23, v2
	v_mov_b32_e32 v24, v2
	v_mov_b32_e32 v25, v2
	v_mov_b32_e32 v26, v2
	v_mov_b32_e32 v27, v2
	v_mov_b32_e32 v28, v2
	v_mov_b32_e32 v29, v2
	v_mov_b32_e32 v30, v2
	v_mov_b32_e32 v31, v2
	v_mov_b32_e32 v32, v2
	v_mov_b32_e32 v33, v2
	v_mov_b32_e32 v34, v2
	v_mov_b32_e32 v35, v2
	v_mov_b32_e32 v36, v2
	v_mov_b32_e32 v37, v2
	v_mov_b32_e32 v38, v2
	v_mov_b32_e32 v39, v2
	v_mov_b32_e32 v40, v2
	v_mov_b32_e32 v41, v2
	v_mov_b32_e32 v42, v2
	v_mov_b32_e32 v43, v2
	v_mov_b32_e32 v44, v2
	v_mov_b32_e32 v45, v2
	v_mov_b32_e32 v46, v2
	v_mov_b32_e32 v47, v2
	v_mov_b32_e32 v48, v2
	v_mov_b32_e32 v49, v2
	v_mov_b32_e32 v50, v2
	v_mov_b32_e32 v51, v2
	v_mov_b32_e32 v52, v2
	v_mov_b32_e32 v53, v2
	v_mov_b32_e32 v54, v2
	v_mov_b32_e32 v55, v2
	v_mov_b32_e32 v56, v2
	v_mov_b32_e32 v57, v2
	v_mov_b32_e32 v58, v2
	v_mov_b32_e32 v59, v2
	v_mov_b32_e32 v60, v2
	v_mov_b32_e32 v61, v2
	v_mov_b32_e32 v62, v2
	v_mov_b32_e32 v63, v2
	v_mov_b32_e32 v64, v2
	v_mov_b32_e32 v65, v2
.LBB0_366:
	s_waitcnt vmcnt(8)
	s_add_u32 s54, s52, 0x8000
	s_waitcnt lgkmcnt(0)
	s_addc_u32 s55, s53, 0
	s_add_u32 s62, s50, 0x8000
	s_addc_u32 s63, s51, 0
	s_setprio 1
	s_barrier
	v_mfma_f32_16x16x32_bf16 v[62:65], v[146:149], v[186:189], v[62:65]
	v_mfma_f32_16x16x32_bf16 v[62:65], v[150:153], v[190:193], v[62:65]
	s_waitcnt lgkmcnt(5)
	s_setprio 0
	s_setprio 1
	v_mfma_f32_16x16x32_bf16 v[54:57], v[146:149], v[178:181], v[54:57]
	v_mfma_f32_16x16x32_bf16 v[54:57], v[150:153], v[182:185], v[54:57]
	s_waitcnt lgkmcnt(3)
	s_setprio 0
	s_setprio 1
	v_mfma_f32_16x16x32_bf16 v[46:49], v[146:149], v[170:173], v[46:49]
	v_mfma_f32_16x16x32_bf16 v[46:49], v[150:153], v[174:177], v[46:49]
	s_waitcnt lgkmcnt(1)
	s_setprio 0
	s_setprio 1
	v_mfma_f32_16x16x32_bf16 v[38:41], v[146:149], v[162:165], v[38:41]
	v_mfma_f32_16x16x32_bf16 v[38:41], v[150:153], v[166:169], v[38:41]
	s_setprio 0
	s_setprio 1
	v_mfma_f32_16x16x32_bf16 v[58:61], v[154:157], v[186:189], v[58:61]
	v_mfma_f32_16x16x32_bf16 v[58:61], v[158:161], v[190:193], v[58:61]
	s_setprio 0
	s_setprio 1
	v_mfma_f32_16x16x32_bf16 v[50:53], v[154:157], v[178:181], v[50:53]
	v_mfma_f32_16x16x32_bf16 v[50:53], v[158:161], v[182:185], v[50:53]
	s_setprio 0
	s_setprio 1
	v_mfma_f32_16x16x32_bf16 v[42:45], v[154:157], v[170:173], v[42:45]
	v_mfma_f32_16x16x32_bf16 v[42:45], v[158:161], v[174:177], v[42:45]
	s_waitcnt lgkmcnt(0)
	s_setprio 0
	s_setprio 1
	v_mfma_f32_16x16x32_bf16 v[34:37], v[154:157], v[162:165], v[34:37]
	v_mfma_f32_16x16x32_bf16 v[34:37], v[158:161], v[166:169], v[34:37]
	s_setprio 0
	s_setprio 1
	v_mfma_f32_16x16x32_bf16 v[30:33], v[130:133], v[186:189], v[30:33]
	v_mfma_f32_16x16x32_bf16 v[30:33], v[134:137], v[190:193], v[30:33]
	s_setprio 0
	s_setprio 1
	v_mfma_f32_16x16x32_bf16 v[22:25], v[130:133], v[178:181], v[22:25]
	v_mfma_f32_16x16x32_bf16 v[22:25], v[134:137], v[182:185], v[22:25]
	s_setprio 0
	s_setprio 1
	v_mfma_f32_16x16x32_bf16 v[14:17], v[130:133], v[170:173], v[14:17]
	v_mfma_f32_16x16x32_bf16 v[14:17], v[134:137], v[174:177], v[14:17]
	s_setprio 0
	s_setprio 1
	v_mfma_f32_16x16x32_bf16 v[6:9], v[130:133], v[162:165], v[6:9]
	v_mfma_f32_16x16x32_bf16 v[6:9], v[134:137], v[166:169], v[6:9]
	s_setprio 0
	s_setprio 1
	v_mfma_f32_16x16x32_bf16 v[26:29], v[138:141], v[186:189], v[26:29]
	v_mfma_f32_16x16x32_bf16 v[26:29], v[142:145], v[190:193], v[26:29]
	s_setprio 0
	s_setprio 1
	v_mfma_f32_16x16x32_bf16 v[18:21], v[138:141], v[178:181], v[18:21]
	v_mfma_f32_16x16x32_bf16 v[18:21], v[142:145], v[182:185], v[18:21]
	s_setprio 0
	s_setprio 1
	v_mfma_f32_16x16x32_bf16 v[10:13], v[138:141], v[170:173], v[10:13]
	v_mfma_f32_16x16x32_bf16 v[10:13], v[142:145], v[174:177], v[10:13]
	s_setprio 2
	s_barrier
	v_mfma_f32_16x16x32_bf16 v[2:5], v[138:141], v[162:165], v[2:5]
	v_mfma_f32_16x16x32_bf16 v[2:5], v[142:145], v[166:169], v[2:5]
	s_setprio 0
	s_nop 0
	v_add_u32_e32 v142, 0x18000, v218
	v_add_u32_e32 v158, 0x1c000, v218
	ds_read_b128 v[130:133], v142
	ds_read_b128 v[134:137], v142 offset:1024
	ds_read_b128 v[138:141], v142 offset:2048
	ds_read_b128 v[142:145], v142 offset:3072
	ds_read_b128 v[146:149], v158
	ds_read_b128 v[150:153], v158 offset:1024
	ds_read_b128 v[154:157], v158 offset:2048
	ds_read_b128 v[158:161], v158 offset:3072
	ds_read_b128 v[162:165], v219 offset:32768
	ds_read_b128 v[166:169], v219 offset:33792
	ds_read_b128 v[170:173], v219 offset:34816
	ds_read_b128 v[174:177], v219 offset:35840
	ds_read_b128 v[178:181], v219 offset:36864
	ds_read_b128 v[182:185], v219 offset:37888
	ds_read_b128 v[186:189], v219 offset:38912
	ds_read_b128 v[190:193], v219 offset:39936
	s_add_u32 s52, s52, 0x4000
	s_addc_u32 s53, s53, 0
	s_mov_b32 m0, s76
	s_nop 0
	global_load_lds_dwordx4 v195, s[52:53]
	s_add_u32 m0, s76, 0x2000
	s_nop 0
	global_load_lds_dwordx4 v212, s[52:53]
	s_waitcnt vmcnt(8)
	s_waitcnt lgkmcnt(0)
	s_setprio 1
	s_barrier
	v_mfma_f32_16x16x32_bf16 v[126:129], v[130:133], v[162:165], v[126:129]
	v_mfma_f32_16x16x32_bf16 v[126:129], v[134:137], v[166:169], v[126:129]
	s_waitcnt lgkmcnt(5)
	s_setprio 0
	s_setprio 1
	v_mfma_f32_16x16x32_bf16 v[118:121], v[130:133], v[170:173], v[118:121]
	v_mfma_f32_16x16x32_bf16 v[118:121], v[134:137], v[174:177], v[118:121]
	s_waitcnt lgkmcnt(3)
	s_setprio 0
	s_setprio 1
	v_mfma_f32_16x16x32_bf16 v[110:113], v[130:133], v[178:181], v[110:113]
	v_mfma_f32_16x16x32_bf16 v[110:113], v[134:137], v[182:185], v[110:113]
	s_waitcnt lgkmcnt(1)
	s_setprio 0
	s_setprio 1
	v_mfma_f32_16x16x32_bf16 v[102:105], v[130:133], v[186:189], v[102:105]
	v_mfma_f32_16x16x32_bf16 v[102:105], v[134:137], v[190:193], v[102:105]
	s_setprio 0
	s_setprio 1
	v_mfma_f32_16x16x32_bf16 v[122:125], v[138:141], v[162:165], v[122:125]
	v_mfma_f32_16x16x32_bf16 v[122:125], v[142:145], v[166:169], v[122:125]
	s_setprio 0
	s_setprio 1
	v_mfma_f32_16x16x32_bf16 v[114:117], v[138:141], v[170:173], v[114:117]
	v_mfma_f32_16x16x32_bf16 v[114:117], v[142:145], v[174:177], v[114:117]
	s_setprio 0
	s_setprio 1
	v_mfma_f32_16x16x32_bf16 v[106:109], v[138:141], v[178:181], v[106:109]
	v_mfma_f32_16x16x32_bf16 v[106:109], v[142:145], v[182:185], v[106:109]
	s_waitcnt lgkmcnt(0)
	s_setprio 0
	s_setprio 1
	v_mfma_f32_16x16x32_bf16 v[98:101], v[138:141], v[186:189], v[98:101]
	v_mfma_f32_16x16x32_bf16 v[98:101], v[142:145], v[190:193], v[98:101]
	s_setprio 0
	s_setprio 1
	v_mfma_f32_16x16x32_bf16 v[94:97], v[146:149], v[162:165], v[94:97]
	v_mfma_f32_16x16x32_bf16 v[94:97], v[150:153], v[166:169], v[94:97]
	s_setprio 0
	s_setprio 1
	v_mfma_f32_16x16x32_bf16 v[86:89], v[146:149], v[170:173], v[86:89]
	v_mfma_f32_16x16x32_bf16 v[86:89], v[150:153], v[174:177], v[86:89]
	s_setprio 0
	s_setprio 1
	v_mfma_f32_16x16x32_bf16 v[78:81], v[146:149], v[178:181], v[78:81]
	v_mfma_f32_16x16x32_bf16 v[78:81], v[150:153], v[182:185], v[78:81]
	s_setprio 0
	s_setprio 1
	v_mfma_f32_16x16x32_bf16 v[70:73], v[146:149], v[186:189], v[70:73]
	v_mfma_f32_16x16x32_bf16 v[70:73], v[150:153], v[190:193], v[70:73]
	s_setprio 0
	s_setprio 1
	v_mfma_f32_16x16x32_bf16 v[90:93], v[154:157], v[162:165], v[90:93]
	v_mfma_f32_16x16x32_bf16 v[90:93], v[158:161], v[166:169], v[90:93]
	s_setprio 0
	s_setprio 1
	v_mfma_f32_16x16x32_bf16 v[82:85], v[154:157], v[170:173], v[82:85]
	v_mfma_f32_16x16x32_bf16 v[82:85], v[158:161], v[174:177], v[82:85]
	s_setprio 0
	s_setprio 1
	v_mfma_f32_16x16x32_bf16 v[74:77], v[154:157], v[178:181], v[74:77]
	v_mfma_f32_16x16x32_bf16 v[74:77], v[158:161], v[182:185], v[74:77]
	s_setprio 2
	s_barrier
	v_mfma_f32_16x16x32_bf16 v[66:69], v[154:157], v[186:189], v[66:69]
	v_mfma_f32_16x16x32_bf16 v[66:69], v[158:161], v[190:193], v[66:69]
	s_setprio 0
	s_nop 0
	ds_read_b128 v[162:165], v219 offset:49152
	ds_read_b128 v[166:169], v219 offset:50176
	ds_read_b128 v[170:173], v219 offset:51200
	ds_read_b128 v[174:177], v219 offset:52224
	ds_read_b128 v[178:181], v219 offset:53248
	ds_read_b128 v[182:185], v219 offset:54272
	ds_read_b128 v[186:189], v219 offset:55296
	ds_read_b128 v[190:193], v219 offset:56320
	s_mov_b32 m0, s80
	s_nop 0
	global_load_lds_dwordx4 v195, s[62:63]
	s_add_u32 m0, s80, 0x2000
	s_nop 0
	global_load_lds_dwordx4 v212, s[62:63]
	s_add_u32 s50, s50, 0xc000
	s_addc_u32 s51, s51, 0
	s_mov_b32 m0, s82
	s_nop 0
	global_load_lds_dwordx4 v195, s[50:51]
	s_add_u32 m0, s82, 0x2000
	s_nop 0
	global_load_lds_dwordx4 v212, s[50:51]
	s_nop 0
	s_mov_b32 m0, s81
	s_nop 0
	global_load_lds_dwordx4 v195, s[54:55]
	s_add_u32 m0, s81, 0x2000
	s_nop 0
	global_load_lds_dwordx4 v212, s[54:55]
	s_waitcnt vmcnt(8)
	s_waitcnt lgkmcnt(0)
	s_setprio 1
	s_barrier
	v_mfma_f32_16x16x32_bf16 v[62:65], v[130:133], v[162:165], v[62:65]
	v_mfma_f32_16x16x32_bf16 v[62:65], v[134:137], v[166:169], v[62:65]
	s_waitcnt lgkmcnt(5)
	s_setprio 0
	s_setprio 1
	v_mfma_f32_16x16x32_bf16 v[54:57], v[130:133], v[170:173], v[54:57]
	v_mfma_f32_16x16x32_bf16 v[54:57], v[134:137], v[174:177], v[54:57]
	s_waitcnt lgkmcnt(3)
	s_setprio 0
	s_setprio 1
	v_mfma_f32_16x16x32_bf16 v[46:49], v[130:133], v[178:181], v[46:49]
	v_mfma_f32_16x16x32_bf16 v[46:49], v[134:137], v[182:185], v[46:49]
	s_waitcnt lgkmcnt(1)
	s_setprio 0
	s_setprio 1
	v_mfma_f32_16x16x32_bf16 v[38:41], v[130:133], v[186:189], v[38:41]
	v_mfma_f32_16x16x32_bf16 v[38:41], v[134:137], v[190:193], v[38:41]
	s_setprio 0
	s_setprio 1
	v_mfma_f32_16x16x32_bf16 v[58:61], v[138:141], v[162:165], v[58:61]
	v_mfma_f32_16x16x32_bf16 v[58:61], v[142:145], v[166:169], v[58:61]
	s_setprio 0
	s_setprio 1
	v_mfma_f32_16x16x32_bf16 v[50:53], v[138:141], v[170:173], v[50:53]
	v_mfma_f32_16x16x32_bf16 v[50:53], v[142:145], v[174:177], v[50:53]
	s_setprio 0
	s_setprio 1
	v_mfma_f32_16x16x32_bf16 v[42:45], v[138:141], v[178:181], v[42:45]
	v_mfma_f32_16x16x32_bf16 v[42:45], v[142:145], v[182:185], v[42:45]
	s_waitcnt lgkmcnt(0)
	s_setprio 0
	s_setprio 1
	v_mfma_f32_16x16x32_bf16 v[34:37], v[138:141], v[186:189], v[34:37]
	v_mfma_f32_16x16x32_bf16 v[34:37], v[142:145], v[190:193], v[34:37]
	s_setprio 0
	s_setprio 1
	v_mfma_f32_16x16x32_bf16 v[30:33], v[146:149], v[162:165], v[30:33]
	v_mfma_f32_16x16x32_bf16 v[30:33], v[150:153], v[166:169], v[30:33]
	s_setprio 0
	s_setprio 1
	v_mfma_f32_16x16x32_bf16 v[22:25], v[146:149], v[170:173], v[22:25]
	v_mfma_f32_16x16x32_bf16 v[22:25], v[150:153], v[174:177], v[22:25]
	s_setprio 0
	s_setprio 1
	v_mfma_f32_16x16x32_bf16 v[14:17], v[146:149], v[178:181], v[14:17]
	v_mfma_f32_16x16x32_bf16 v[14:17], v[150:153], v[182:185], v[14:17]
	s_setprio 0
	s_setprio 1
	v_mfma_f32_16x16x32_bf16 v[6:9], v[146:149], v[186:189], v[6:9]
	v_mfma_f32_16x16x32_bf16 v[6:9], v[150:153], v[190:193], v[6:9]
	s_setprio 0
	s_setprio 1
	v_mfma_f32_16x16x32_bf16 v[26:29], v[154:157], v[162:165], v[26:29]
	v_mfma_f32_16x16x32_bf16 v[26:29], v[158:161], v[166:169], v[26:29]
	s_setprio 0
	s_setprio 1
	v_mfma_f32_16x16x32_bf16 v[18:21], v[154:157], v[170:173], v[18:21]
	v_mfma_f32_16x16x32_bf16 v[18:21], v[158:161], v[174:177], v[18:21]
	s_setprio 0
	s_setprio 1
	v_mfma_f32_16x16x32_bf16 v[10:13], v[154:157], v[178:181], v[10:13]
	v_mfma_f32_16x16x32_bf16 v[10:13], v[158:161], v[182:185], v[10:13]
	s_setprio 2
	s_barrier
	v_mfma_f32_16x16x32_bf16 v[2:5], v[154:157], v[186:189], v[2:5]
	v_mfma_f32_16x16x32_bf16 v[2:5], v[158:161], v[190:193], v[2:5]
	s_setprio 0
	s_nop 0
	s_cmp_gt_u32 s93, 41
	s_cbranch_scc1 .LBB0_368
	v_mov_b32_e32 v130, v198
	s_mov_b32 s93, s26
	s_branch .LBB0_343

.LBB0_519:
	ds_read_b128 v[130:133], v141
	ds_read_b128 v[134:137], v141 offset:1024
	ds_read_b128 v[146:149], v141 offset:2048
	ds_read_b128 v[150:153], v141 offset:3072
	ds_read_b128 v[154:157], v142
	ds_read_b128 v[158:161], v142 offset:1024
	ds_read_b128 v[162:165], v142 offset:2048
	ds_read_b128 v[166:169], v142 offset:3072
	s_add_u32 s24, s26, 0x10000
	s_addc_u32 s25, s27, 0
	s_cmp_eq_u32 s77, 12
	s_cselect_b32 s48, s17, s24
	s_cselect_b32 s49, s1, s25
	s_cselect_b32 s30, s23, s75
	s_cselect_b32 s31, s15, s76
	s_add_u32 s28, s48, 0x8000
	s_addc_u32 s29, s49, 0
	ds_read_b128 v[170:173], v143
	ds_read_b128 v[174:177], v143 offset:1024
	ds_read_b128 v[178:181], v143 offset:2048
	ds_read_b128 v[182:185], v143 offset:3072
	ds_read_b128 v[186:189], v143 offset:4096
	ds_read_b128 v[190:193], v143 offset:5120
	ds_read_b128 v[198:201], v143 offset:6144
	ds_read_b128 v[202:205], v143 offset:7168
	s_add_u32 s38, s30, 0x8000
	s_addc_u32 s39, s31, 0
	s_add_u32 s26, s26, 0xc000
	s_addc_u32 s27, s27, 0
	s_mov_b32 m0, s72
	s_nop 0
	global_load_lds_dwordx4 v195, s[26:27]
	s_add_u32 m0, s72, 0x2000
	s_nop 0
	global_load_lds_dwordx4 v212, s[26:27]
	s_waitcnt vmcnt(8)
	s_waitcnt lgkmcnt(0)
	s_setprio 1
	s_barrier
	v_mfma_f32_16x16x32_bf16 v[122:125], v[130:133], v[170:173], v[122:125]
	v_mfma_f32_16x16x32_bf16 v[122:125], v[134:137], v[174:177], v[122:125]
	s_waitcnt lgkmcnt(5)
	s_setprio 0
	s_setprio 1
	v_mfma_f32_16x16x32_bf16 v[110:113], v[130:133], v[178:181], v[110:113]
	v_mfma_f32_16x16x32_bf16 v[110:113], v[134:137], v[182:185], v[110:113]
	s_waitcnt lgkmcnt(3)
	s_setprio 0
	s_setprio 1
	v_mfma_f32_16x16x32_bf16 v[94:97], v[130:133], v[186:189], v[94:97]
	v_mfma_f32_16x16x32_bf16 v[94:97], v[134:137], v[190:193], v[94:97]
	s_waitcnt lgkmcnt(1)
	s_setprio 0
	s_setprio 1
	v_mfma_f32_16x16x32_bf16 v[78:81], v[130:133], v[198:201], v[78:81]
	v_mfma_f32_16x16x32_bf16 v[78:81], v[134:137], v[202:205], v[78:81]
	s_setprio 0
	s_setprio 1
	v_mfma_f32_16x16x32_bf16 v[126:129], v[146:149], v[170:173], v[126:129]
	v_mfma_f32_16x16x32_bf16 v[126:129], v[150:153], v[174:177], v[126:129]
	s_setprio 0
	s_setprio 1
	v_mfma_f32_16x16x32_bf16 v[106:109], v[146:149], v[178:181], v[106:109]
	v_mfma_f32_16x16x32_bf16 v[106:109], v[150:153], v[182:185], v[106:109]
	s_setprio 0
	s_setprio 1
	v_mfma_f32_16x16x32_bf16 v[90:93], v[146:149], v[186:189], v[90:93]
	v_mfma_f32_16x16x32_bf16 v[90:93], v[150:153], v[190:193], v[90:93]
	s_waitcnt lgkmcnt(0)
	s_setprio 0
	s_setprio 1
	v_mfma_f32_16x16x32_bf16 v[74:77], v[146:149], v[198:201], v[74:77]
	v_mfma_f32_16x16x32_bf16 v[74:77], v[150:153], v[202:205], v[74:77]
	s_setprio 0
	s_setprio 1
	v_mfma_f32_16x16x32_bf16 v[114:117], v[154:157], v[170:173], v[114:117]
	v_mfma_f32_16x16x32_bf16 v[114:117], v[158:161], v[174:177], v[114:117]
	s_setprio 0
	s_setprio 1
	v_mfma_f32_16x16x32_bf16 v[98:101], v[154:157], v[178:181], v[98:101]
	v_mfma_f32_16x16x32_bf16 v[98:101], v[158:161], v[182:185], v[98:101]
	s_setprio 0
	s_setprio 1
	v_mfma_f32_16x16x32_bf16 v[82:85], v[154:157], v[186:189], v[82:85]
	v_mfma_f32_16x16x32_bf16 v[82:85], v[158:161], v[190:193], v[82:85]
	s_setprio 0
	s_setprio 1
	v_mfma_f32_16x16x32_bf16 v[66:69], v[154:157], v[198:201], v[66:69]
	v_mfma_f32_16x16x32_bf16 v[66:69], v[158:161], v[202:205], v[66:69]
	s_setprio 0
	s_setprio 1
	v_mfma_f32_16x16x32_bf16 v[118:121], v[162:165], v[170:173], v[118:121]
	v_mfma_f32_16x16x32_bf16 v[118:121], v[166:169], v[174:177], v[118:121]
	s_setprio 0
	s_setprio 1
	v_mfma_f32_16x16x32_bf16 v[102:105], v[162:165], v[178:181], v[102:105]
	v_mfma_f32_16x16x32_bf16 v[102:105], v[166:169], v[182:185], v[102:105]
	s_setprio 0
	s_setprio 1
	v_mfma_f32_16x16x32_bf16 v[86:89], v[162:165], v[186:189], v[86:89]
	v_mfma_f32_16x16x32_bf16 v[86:89], v[166:169], v[190:193], v[86:89]
	s_setprio 2
	s_barrier
	v_mfma_f32_16x16x32_bf16 v[70:73], v[162:165], v[198:201], v[70:73]
	v_mfma_f32_16x16x32_bf16 v[70:73], v[166:169], v[202:205], v[70:73]
	s_setprio 0
	s_nop 0
	ds_read_b128 v[170:173], v143 offset:16384
	ds_read_b128 v[174:177], v143 offset:17408
	ds_read_b128 v[178:181], v143 offset:18432
	ds_read_b128 v[182:185], v143 offset:19456
	ds_read_b128 v[186:189], v143 offset:20480
	ds_read_b128 v[190:193], v143 offset:21504
	ds_read_b128 v[198:201], v143 offset:22528
	ds_read_b128 v[202:205], v143 offset:23552
	s_mov_b32 m0, s55
	s_nop 0
	global_load_lds_dwordx4 v195, s[30:31]
	s_add_u32 m0, s55, 0x2000
	s_nop 0
	global_load_lds_dwordx4 v212, s[30:31]
	s_add_u32 s26, s30, 0x4000
	s_addc_u32 s27, s31, 0
	s_mov_b32 m0, s62
	s_nop 0
	global_load_lds_dwordx4 v195, s[26:27]
	s_add_u32 m0, s62, 0x2000
	s_nop 0
	global_load_lds_dwordx4 v212, s[26:27]
	s_nop 0
	s_mov_b32 m0, s54
	s_nop 0
	global_load_lds_dwordx4 v195, s[48:49]
	s_add_u32 m0, s54, 0x2000
	s_nop 0
	global_load_lds_dwordx4 v212, s[48:49]
	s_waitcnt vmcnt(8)
	s_waitcnt lgkmcnt(0)
	s_setprio 1
	s_barrier
	v_mfma_f32_16x16x32_bf16 v[62:65], v[130:133], v[170:173], v[62:65]
	v_mfma_f32_16x16x32_bf16 v[62:65], v[134:137], v[174:177], v[62:65]
	s_waitcnt lgkmcnt(5)
	s_setprio 0
	s_setprio 1
	v_mfma_f32_16x16x32_bf16 v[46:49], v[130:133], v[178:181], v[46:49]
	v_mfma_f32_16x16x32_bf16 v[46:49], v[134:137], v[182:185], v[46:49]
	s_waitcnt lgkmcnt(3)
	s_setprio 0
	s_setprio 1
	v_mfma_f32_16x16x32_bf16 v[30:33], v[130:133], v[186:189], v[30:33]
	v_mfma_f32_16x16x32_bf16 v[30:33], v[134:137], v[190:193], v[30:33]
	s_waitcnt lgkmcnt(1)
	s_setprio 0
	s_setprio 1
	v_mfma_f32_16x16x32_bf16 v[14:17], v[130:133], v[198:201], v[14:17]
	v_mfma_f32_16x16x32_bf16 v[14:17], v[134:137], v[202:205], v[14:17]
	s_setprio 0
	s_setprio 1
	v_mfma_f32_16x16x32_bf16 v[58:61], v[146:149], v[170:173], v[58:61]
	v_mfma_f32_16x16x32_bf16 v[58:61], v[150:153], v[174:177], v[58:61]
	s_setprio 0
	s_setprio 1
	v_mfma_f32_16x16x32_bf16 v[42:45], v[146:149], v[178:181], v[42:45]
	v_mfma_f32_16x16x32_bf16 v[42:45], v[150:153], v[182:185], v[42:45]
	s_setprio 0
	s_setprio 1
	v_mfma_f32_16x16x32_bf16 v[26:29], v[146:149], v[186:189], v[26:29]
	v_mfma_f32_16x16x32_bf16 v[26:29], v[150:153], v[190:193], v[26:29]
	s_waitcnt lgkmcnt(0)
	s_setprio 0
	s_setprio 1
	v_mfma_f32_16x16x32_bf16 v[10:13], v[146:149], v[198:201], v[10:13]
	v_mfma_f32_16x16x32_bf16 v[10:13], v[150:153], v[202:205], v[10:13]
	s_setprio 0
	s_setprio 1
	v_mfma_f32_16x16x32_bf16 v[50:53], v[154:157], v[170:173], v[50:53]
	v_mfma_f32_16x16x32_bf16 v[50:53], v[158:161], v[174:177], v[50:53]
	s_setprio 0
	s_setprio 1
	v_mfma_f32_16x16x32_bf16 v[34:37], v[154:157], v[178:181], v[34:37]
	v_mfma_f32_16x16x32_bf16 v[34:37], v[158:161], v[182:185], v[34:37]
	s_setprio 0
	s_setprio 1
	v_mfma_f32_16x16x32_bf16 v[18:21], v[154:157], v[186:189], v[18:21]
	v_mfma_f32_16x16x32_bf16 v[18:21], v[158:161], v[190:193], v[18:21]
	s_setprio 0
	s_setprio 1
	v_mfma_f32_16x16x32_bf16 v[2:5], v[154:157], v[198:201], v[2:5]
	v_mfma_f32_16x16x32_bf16 v[2:5], v[158:161], v[202:205], v[2:5]
	s_setprio 0
	s_setprio 1
	v_mfma_f32_16x16x32_bf16 v[54:57], v[162:165], v[170:173], v[54:57]
	v_mfma_f32_16x16x32_bf16 v[54:57], v[166:169], v[174:177], v[54:57]
	s_setprio 0
	s_setprio 1
	v_mfma_f32_16x16x32_bf16 v[38:41], v[162:165], v[178:181], v[38:41]
	v_mfma_f32_16x16x32_bf16 v[38:41], v[166:169], v[182:185], v[38:41]
	s_setprio 0
	s_setprio 1
	v_mfma_f32_16x16x32_bf16 v[22:25], v[162:165], v[186:189], v[22:25]
	v_mfma_f32_16x16x32_bf16 v[22:25], v[166:169], v[190:193], v[22:25]
	s_setprio 2
	s_barrier
	v_mfma_f32_16x16x32_bf16 v[6:9], v[162:165], v[198:201], v[6:9]
	v_mfma_f32_16x16x32_bf16 v[6:9], v[166:169], v[202:205], v[6:9]
	s_setprio 0
	s_nop 0
	ds_read_b128 v[130:133], v144
	ds_read_b128 v[134:137], v144 offset:1024
	ds_read_b128 v[146:149], v144 offset:2048
	ds_read_b128 v[150:153], v144 offset:3072
	ds_read_b128 v[154:157], v145
	ds_read_b128 v[158:161], v145 offset:1024
	ds_read_b128 v[162:165], v145 offset:2048
	ds_read_b128 v[166:169], v145 offset:3072
	ds_read_b128 v[170:173], v143 offset:32768
	ds_read_b128 v[174:177], v143 offset:33792
	ds_read_b128 v[178:181], v143 offset:34816
	ds_read_b128 v[182:185], v143 offset:35840
	ds_read_b128 v[186:189], v143 offset:36864
	ds_read_b128 v[190:193], v143 offset:37888
	ds_read_b128 v[198:201], v143 offset:38912
	ds_read_b128 v[202:205], v143 offset:39936
	s_add_u32 s26, s48, 0x4000
	s_addc_u32 s27, s49, 0
	s_mov_b32 m0, s63
	s_nop 0
	global_load_lds_dwordx4 v195, s[26:27]
	s_add_u32 m0, s63, 0x2000
	s_nop 0
	global_load_lds_dwordx4 v212, s[26:27]
	s_waitcnt vmcnt(8)
	s_waitcnt lgkmcnt(0)
	s_setprio 1
	s_barrier
	v_mfma_f32_16x16x32_bf16 v[122:125], v[130:133], v[170:173], v[122:125]
	v_mfma_f32_16x16x32_bf16 v[122:125], v[134:137], v[174:177], v[122:125]
	s_waitcnt lgkmcnt(5)
	s_setprio 0
	s_setprio 1
	v_mfma_f32_16x16x32_bf16 v[110:113], v[130:133], v[178:181], v[110:113]
	v_mfma_f32_16x16x32_bf16 v[110:113], v[134:137], v[182:185], v[110:113]
	s_waitcnt lgkmcnt(3)
	s_setprio 0
	s_setprio 1
	v_mfma_f32_16x16x32_bf16 v[94:97], v[130:133], v[186:189], v[94:97]
	v_mfma_f32_16x16x32_bf16 v[94:97], v[134:137], v[190:193], v[94:97]
	s_waitcnt lgkmcnt(1)
	s_setprio 0
	s_setprio 1
	v_mfma_f32_16x16x32_bf16 v[78:81], v[130:133], v[198:201], v[78:81]
	v_mfma_f32_16x16x32_bf16 v[78:81], v[134:137], v[202:205], v[78:81]
	s_setprio 0
	s_setprio 1
	v_mfma_f32_16x16x32_bf16 v[126:129], v[146:149], v[170:173], v[126:129]
	v_mfma_f32_16x16x32_bf16 v[126:129], v[150:153], v[174:177], v[126:129]
	s_setprio 0
	s_setprio 1
	v_mfma_f32_16x16x32_bf16 v[106:109], v[146:149], v[178:181], v[106:109]
	v_mfma_f32_16x16x32_bf16 v[106:109], v[150:153], v[182:185], v[106:109]
	s_setprio 0
	s_setprio 1
	v_mfma_f32_16x16x32_bf16 v[90:93], v[146:149], v[186:189], v[90:93]
	v_mfma_f32_16x16x32_bf16 v[90:93], v[150:153], v[190:193], v[90:93]
	s_waitcnt lgkmcnt(0)
	s_setprio 0
	s_setprio 1
	v_mfma_f32_16x16x32_bf16 v[74:77], v[146:149], v[198:201], v[74:77]
	v_mfma_f32_16x16x32_bf16 v[74:77], v[150:153], v[202:205], v[74:77]
	s_setprio 0
	s_setprio 1
	v_mfma_f32_16x16x32_bf16 v[114:117], v[154:157], v[170:173], v[114:117]
	v_mfma_f32_16x16x32_bf16 v[114:117], v[158:161], v[174:177], v[114:117]
	s_setprio 0
	s_setprio 1
	v_mfma_f32_16x16x32_bf16 v[98:101], v[154:157], v[178:181], v[98:101]
	v_mfma_f32_16x16x32_bf16 v[98:101], v[158:161], v[182:185], v[98:101]
	s_setprio 0
	s_setprio 1
	v_mfma_f32_16x16x32_bf16 v[82:85], v[154:157], v[186:189], v[82:85]
	v_mfma_f32_16x16x32_bf16 v[82:85], v[158:161], v[190:193], v[82:85]
	s_setprio 0
	s_setprio 1
	v_mfma_f32_16x16x32_bf16 v[66:69], v[154:157], v[198:201], v[66:69]
	v_mfma_f32_16x16x32_bf16 v[66:69], v[158:161], v[202:205], v[66:69]
	s_setprio 0
	s_setprio 1
	v_mfma_f32_16x16x32_bf16 v[118:121], v[162:165], v[170:173], v[118:121]
	v_mfma_f32_16x16x32_bf16 v[118:121], v[166:169], v[174:177], v[118:121]
	s_setprio 0
	s_setprio 1
	v_mfma_f32_16x16x32_bf16 v[102:105], v[162:165], v[178:181], v[102:105]
	v_mfma_f32_16x16x32_bf16 v[102:105], v[166:169], v[182:185], v[102:105]
	s_setprio 0
	s_setprio 1
	v_mfma_f32_16x16x32_bf16 v[86:89], v[162:165], v[186:189], v[86:89]
	v_mfma_f32_16x16x32_bf16 v[86:89], v[166:169], v[190:193], v[86:89]
	s_setprio 2
	s_barrier
	v_mfma_f32_16x16x32_bf16 v[70:73], v[162:165], v[198:201], v[70:73]
	v_mfma_f32_16x16x32_bf16 v[70:73], v[166:169], v[202:205], v[70:73]
	s_setprio 0
	s_nop 0
	ds_read_b128 v[170:173], v143 offset:49152
	ds_read_b128 v[174:177], v143 offset:50176
	ds_read_b128 v[178:181], v143 offset:51200
	ds_read_b128 v[182:185], v143 offset:52224
	ds_read_b128 v[186:189], v143 offset:53248
	ds_read_b128 v[190:193], v143 offset:54272
	ds_read_b128 v[198:201], v143 offset:55296
	ds_read_b128 v[202:205], v143 offset:56320
	s_mov_b32 m0, s69
	s_nop 0
	global_load_lds_dwordx4 v195, s[38:39]
	s_add_u32 m0, s69, 0x2000
	s_nop 0
	global_load_lds_dwordx4 v212, s[38:39]
	s_add_u32 s26, s30, 0xc000
	s_addc_u32 s27, s31, 0
	s_mov_b32 m0, s71
	s_nop 0
	global_load_lds_dwordx4 v195, s[26:27]
	s_add_u32 m0, s71, 0x2000
	s_nop 0
	global_load_lds_dwordx4 v212, s[26:27]
	s_nop 0
	s_mov_b32 m0, s70
	s_nop 0
	global_load_lds_dwordx4 v195, s[28:29]
	s_add_u32 m0, s70, 0x2000
	s_nop 0
	global_load_lds_dwordx4 v212, s[28:29]
	s_waitcnt vmcnt(8)
	s_waitcnt lgkmcnt(0)
	s_setprio 1
	s_barrier
	v_mfma_f32_16x16x32_bf16 v[62:65], v[130:133], v[170:173], v[62:65]
	v_mfma_f32_16x16x32_bf16 v[62:65], v[134:137], v[174:177], v[62:65]
	s_waitcnt lgkmcnt(5)
	s_setprio 0
	s_setprio 1
	v_mfma_f32_16x16x32_bf16 v[46:49], v[130:133], v[178:181], v[46:49]
	v_mfma_f32_16x16x32_bf16 v[46:49], v[134:137], v[182:185], v[46:49]
	s_waitcnt lgkmcnt(3)
	s_setprio 0
	s_setprio 1
	v_mfma_f32_16x16x32_bf16 v[30:33], v[130:133], v[186:189], v[30:33]
	v_mfma_f32_16x16x32_bf16 v[30:33], v[134:137], v[190:193], v[30:33]
	s_waitcnt lgkmcnt(1)
	s_setprio 0
	s_setprio 1
	v_mfma_f32_16x16x32_bf16 v[14:17], v[130:133], v[198:201], v[14:17]
	v_mfma_f32_16x16x32_bf16 v[14:17], v[134:137], v[202:205], v[14:17]
	s_setprio 0
	s_setprio 1
	v_mfma_f32_16x16x32_bf16 v[58:61], v[146:149], v[170:173], v[58:61]
	v_mfma_f32_16x16x32_bf16 v[58:61], v[150:153], v[174:177], v[58:61]
	s_setprio 0
	s_setprio 1
	v_mfma_f32_16x16x32_bf16 v[42:45], v[146:149], v[178:181], v[42:45]
	v_mfma_f32_16x16x32_bf16 v[42:45], v[150:153], v[182:185], v[42:45]
	s_setprio 0
	s_setprio 1
	v_mfma_f32_16x16x32_bf16 v[26:29], v[146:149], v[186:189], v[26:29]
	v_mfma_f32_16x16x32_bf16 v[26:29], v[150:153], v[190:193], v[26:29]
	s_waitcnt lgkmcnt(0)
	s_setprio 0
	s_setprio 1
	v_mfma_f32_16x16x32_bf16 v[10:13], v[146:149], v[198:201], v[10:13]
	v_mfma_f32_16x16x32_bf16 v[10:13], v[150:153], v[202:205], v[10:13]
	s_setprio 0
	s_setprio 1
	v_mfma_f32_16x16x32_bf16 v[50:53], v[154:157], v[170:173], v[50:53]
	v_mfma_f32_16x16x32_bf16 v[50:53], v[158:161], v[174:177], v[50:53]
	s_setprio 0
	s_setprio 1
	v_mfma_f32_16x16x32_bf16 v[34:37], v[154:157], v[178:181], v[34:37]
	v_mfma_f32_16x16x32_bf16 v[34:37], v[158:161], v[182:185], v[34:37]
	s_setprio 0
	s_setprio 1
	v_mfma_f32_16x16x32_bf16 v[18:21], v[154:157], v[186:189], v[18:21]
	v_mfma_f32_16x16x32_bf16 v[18:21], v[158:161], v[190:193], v[18:21]
	s_setprio 0
	s_setprio 1
	v_mfma_f32_16x16x32_bf16 v[2:5], v[154:157], v[198:201], v[2:5]
	v_mfma_f32_16x16x32_bf16 v[2:5], v[158:161], v[202:205], v[2:5]
	s_setprio 0
	s_setprio 1
	v_mfma_f32_16x16x32_bf16 v[54:57], v[162:165], v[170:173], v[54:57]
	v_mfma_f32_16x16x32_bf16 v[54:57], v[166:169], v[174:177], v[54:57]
	s_setprio 0
	s_setprio 1
	v_mfma_f32_16x16x32_bf16 v[38:41], v[162:165], v[178:181], v[38:41]
	v_mfma_f32_16x16x32_bf16 v[38:41], v[166:169], v[182:185], v[38:41]
	s_setprio 0
	s_setprio 1
	v_mfma_f32_16x16x32_bf16 v[22:25], v[162:165], v[186:189], v[22:25]
	v_mfma_f32_16x16x32_bf16 v[22:25], v[166:169], v[190:193], v[22:25]
	s_setprio 2
	s_barrier
	v_mfma_f32_16x16x32_bf16 v[6:9], v[162:165], v[198:201], v[6:9]
	v_mfma_f32_16x16x32_bf16 v[6:9], v[166:169], v[202:205], v[6:9]
	s_setprio 0
	s_nop 0
	s_add_i32 s77, s77, 2
	s_add_u32 s75, s75, 0x10000
	s_addc_u32 s76, s76, 0
	s_cmp_gt_u32 s77, 13
	s_mov_b64 s[26:27], s[24:25]
	s_cbranch_scc0 .LBB0_519
	s_and_b64 vcc, exec, s[10:11]
	s_cbranch_vccz .LBB0_522
	s_barrier
	s_setprio 1

.LBB0_635:
	s_add_u32 s28, s24, 0x10000
	s_addc_u32 s29, s25, 0
	s_and_b64 s[24:25], s[22:23], exec
	s_cselect_b32 s25, s29, s15
	s_cselect_b32 s24, s28, s33
	s_add_u32 s3, s52, s3
	s_addc_u32 s28, s53, 0
	s_add_u32 s3, s3, 0x10000
	s_waitcnt vmcnt(8)
	s_addc_u32 s28, s28, 0
	s_waitcnt lgkmcnt(0)
	s_and_b64 s[22:23], s[22:23], exec
	s_cselect_b32 s23, s28, s13
	s_cselect_b32 s22, s3, s70
	s_setprio 1
	s_barrier
	v_mfma_f32_16x16x32_bf16 v[126:129], v[146:149], v[186:189], v[126:129]
	v_mfma_f32_16x16x32_bf16 v[126:129], v[150:153], v[190:193], v[126:129]
	s_waitcnt lgkmcnt(5)
	s_setprio 0
	s_setprio 1
	v_mfma_f32_16x16x32_bf16 v[118:121], v[146:149], v[178:181], v[118:121]
	v_mfma_f32_16x16x32_bf16 v[118:121], v[150:153], v[182:185], v[118:121]
	s_waitcnt lgkmcnt(3)
	s_setprio 0
	s_setprio 1
	v_mfma_f32_16x16x32_bf16 v[110:113], v[146:149], v[170:173], v[110:113]
	v_mfma_f32_16x16x32_bf16 v[110:113], v[150:153], v[174:177], v[110:113]
	s_waitcnt lgkmcnt(1)
	s_setprio 0
	s_setprio 1
	v_mfma_f32_16x16x32_bf16 v[102:105], v[146:149], v[162:165], v[102:105]
	v_mfma_f32_16x16x32_bf16 v[102:105], v[150:153], v[166:169], v[102:105]
	s_setprio 0
	s_setprio 1
	v_mfma_f32_16x16x32_bf16 v[122:125], v[154:157], v[186:189], v[122:125]
	v_mfma_f32_16x16x32_bf16 v[122:125], v[158:161], v[190:193], v[122:125]
	s_setprio 0
	s_setprio 1
	v_mfma_f32_16x16x32_bf16 v[114:117], v[154:157], v[178:181], v[114:117]
	v_mfma_f32_16x16x32_bf16 v[114:117], v[158:161], v[182:185], v[114:117]
	s_setprio 0
	s_setprio 1
	v_mfma_f32_16x16x32_bf16 v[106:109], v[154:157], v[170:173], v[106:109]
	v_mfma_f32_16x16x32_bf16 v[106:109], v[158:161], v[174:177], v[106:109]
	s_waitcnt lgkmcnt(0)
	s_setprio 0
	s_setprio 1
	v_mfma_f32_16x16x32_bf16 v[98:101], v[154:157], v[162:165], v[98:101]
	v_mfma_f32_16x16x32_bf16 v[98:101], v[158:161], v[166:169], v[98:101]
	s_setprio 0
	s_setprio 1
	v_mfma_f32_16x16x32_bf16 v[94:97], v[130:133], v[186:189], v[94:97]
	v_mfma_f32_16x16x32_bf16 v[94:97], v[134:137], v[190:193], v[94:97]
	s_setprio 0
	s_setprio 1
	v_mfma_f32_16x16x32_bf16 v[86:89], v[130:133], v[178:181], v[86:89]
	v_mfma_f32_16x16x32_bf16 v[86:89], v[134:137], v[182:185], v[86:89]
	s_setprio 0
	s_setprio 1
	v_mfma_f32_16x16x32_bf16 v[78:81], v[130:133], v[170:173], v[78:81]
	v_mfma_f32_16x16x32_bf16 v[78:81], v[134:137], v[174:177], v[78:81]
	s_setprio 0
	s_setprio 1
	v_mfma_f32_16x16x32_bf16 v[70:73], v[130:133], v[162:165], v[70:73]
	v_mfma_f32_16x16x32_bf16 v[70:73], v[134:137], v[166:169], v[70:73]
	s_setprio 0
	s_setprio 1
	v_mfma_f32_16x16x32_bf16 v[90:93], v[138:141], v[186:189], v[90:93]
	v_mfma_f32_16x16x32_bf16 v[90:93], v[142:145], v[190:193], v[90:93]
	s_setprio 0
	s_setprio 1
	v_mfma_f32_16x16x32_bf16 v[82:85], v[138:141], v[178:181], v[82:85]
	v_mfma_f32_16x16x32_bf16 v[82:85], v[142:145], v[182:185], v[82:85]
	s_setprio 0
	s_setprio 1
	v_mfma_f32_16x16x32_bf16 v[74:77], v[138:141], v[170:173], v[74:77]
	v_mfma_f32_16x16x32_bf16 v[74:77], v[142:145], v[174:177], v[74:77]
	s_setprio 2
	s_barrier
	v_mfma_f32_16x16x32_bf16 v[66:69], v[138:141], v[162:165], v[66:69]
	v_mfma_f32_16x16x32_bf16 v[66:69], v[142:145], v[166:169], v[66:69]
	s_setprio 0
	s_nop 0
	ds_read_b128 v[186:189], v219 offset:16384
	ds_read_b128 v[190:193], v219 offset:17408
	ds_read_b128 v[178:181], v219 offset:18432
	ds_read_b128 v[182:185], v219 offset:19456
	ds_read_b128 v[170:173], v219 offset:20480
	ds_read_b128 v[174:177], v219 offset:21504
	ds_read_b128 v[162:165], v219 offset:22528
	ds_read_b128 v[166:169], v219 offset:23552
	s_mov_b32 m0, s89
	s_nop 0
	global_load_lds_dwordx4 v195, s[22:23]
	s_add_u32 m0, s89, 0x2000
	s_nop 0
	global_load_lds_dwordx4 v213, s[22:23]
	s_add_u32 s28, s22, 0x4000
	s_addc_u32 s29, s23, 0
	s_mov_b32 m0, s54
	s_nop 0
	global_load_lds_dwordx4 v195, s[28:29]
	s_add_u32 m0, s54, 0x2000
	s_nop 0
	global_load_lds_dwordx4 v213, s[28:29]
	s_andn2_b64 vcc, exec, s[26:27]
	s_mov_b32 m0, s39
	s_nop 0
	global_load_lds_dwordx4 v195, s[24:25]
	s_add_u32 m0, s39, 0x2000
	s_nop 0
	global_load_lds_dwordx4 v213, s[24:25]
	s_cbranch_vccnz .LBB0_637
	v_mov_b32_e32 v2, 0
	v_mov_b32_e32 v3, v2
	v_mov_b32_e32 v4, v2
	v_mov_b32_e32 v5, v2
	v_mov_b32_e32 v6, v2
	v_mov_b32_e32 v7, v2
	v_mov_b32_e32 v8, v2
	v_mov_b32_e32 v9, v2
	v_mov_b32_e32 v10, v2
	v_mov_b32_e32 v11, v2
	v_mov_b32_e32 v12, v2
	v_mov_b32_e32 v13, v2
	v_mov_b32_e32 v14, v2
	v_mov_b32_e32 v15, v2
	v_mov_b32_e32 v16, v2
	v_mov_b32_e32 v17, v2
	v_mov_b32_e32 v18, v2
	v_mov_b32_e32 v19, v2
	v_mov_b32_e32 v20, v2
	v_mov_b32_e32 v21, v2
	v_mov_b32_e32 v22, v2
	v_mov_b32_e32 v23, v2
	v_mov_b32_e32 v24, v2
	v_mov_b32_e32 v25, v2
	v_mov_b32_e32 v26, v2
	v_mov_b32_e32 v27, v2
	v_mov_b32_e32 v28, v2
	v_mov_b32_e32 v29, v2
	v_mov_b32_e32 v30, v2
	v_mov_b32_e32 v31, v2
	v_mov_b32_e32 v32, v2
	v_mov_b32_e32 v33, v2
	v_mov_b32_e32 v34, v2
	v_mov_b32_e32 v35, v2
	v_mov_b32_e32 v36, v2
	v_mov_b32_e32 v37, v2
	v_mov_b32_e32 v38, v2
	v_mov_b32_e32 v39, v2
	v_mov_b32_e32 v40, v2
	v_mov_b32_e32 v41, v2
	v_mov_b32_e32 v42, v2
	v_mov_b32_e32 v43, v2
	v_mov_b32_e32 v44, v2
	v_mov_b32_e32 v45, v2
	v_mov_b32_e32 v46, v2
	v_mov_b32_e32 v47, v2
	v_mov_b32_e32 v48, v2
	v_mov_b32_e32 v49, v2
	v_mov_b32_e32 v50, v2
	v_mov_b32_e32 v51, v2
	v_mov_b32_e32 v52, v2
	v_mov_b32_e32 v53, v2
	v_mov_b32_e32 v54, v2
	v_mov_b32_e32 v55, v2
	v_mov_b32_e32 v56, v2
	v_mov_b32_e32 v57, v2
	v_mov_b32_e32 v58, v2
	v_mov_b32_e32 v59, v2
	v_mov_b32_e32 v60, v2
	v_mov_b32_e32 v61, v2
	v_mov_b32_e32 v62, v2
	v_mov_b32_e32 v63, v2
	v_mov_b32_e32 v64, v2
	v_mov_b32_e32 v65, v2
.LBB0_637:
	s_waitcnt vmcnt(8)
	s_add_u32 s26, s24, 0x8000
	s_waitcnt lgkmcnt(0)
	s_addc_u32 s27, s25, 0
	s_add_u32 s28, s22, 0x8000
	s_addc_u32 s29, s23, 0
	s_setprio 1
	s_barrier
	v_mfma_f32_16x16x32_bf16 v[62:65], v[146:149], v[186:189], v[62:65]
	v_mfma_f32_16x16x32_bf16 v[62:65], v[150:153], v[190:193], v[62:65]
	s_waitcnt lgkmcnt(5)
	s_setprio 0
	s_setprio 1
	v_mfma_f32_16x16x32_bf16 v[54:57], v[146:149], v[178:181], v[54:57]
	v_mfma_f32_16x16x32_bf16 v[54:57], v[150:153], v[182:185], v[54:57]
	s_waitcnt lgkmcnt(3)
	s_setprio 0
	s_setprio 1
	v_mfma_f32_16x16x32_bf16 v[46:49], v[146:149], v[170:173], v[46:49]
	v_mfma_f32_16x16x32_bf16 v[46:49], v[150:153], v[174:177], v[46:49]
	s_waitcnt lgkmcnt(1)
	s_setprio 0
	s_setprio 1
	v_mfma_f32_16x16x32_bf16 v[38:41], v[146:149], v[162:165], v[38:41]
	v_mfma_f32_16x16x32_bf16 v[38:41], v[150:153], v[166:169], v[38:41]
	s_setprio 0
	s_setprio 1
	v_mfma_f32_16x16x32_bf16 v[58:61], v[154:157], v[186:189], v[58:61]
	v_mfma_f32_16x16x32_bf16 v[58:61], v[158:161], v[190:193], v[58:61]
	s_setprio 0
	s_setprio 1
	v_mfma_f32_16x16x32_bf16 v[50:53], v[154:157], v[178:181], v[50:53]
	v_mfma_f32_16x16x32_bf16 v[50:53], v[158:161], v[182:185], v[50:53]
	s_setprio 0
	s_setprio 1
	v_mfma_f32_16x16x32_bf16 v[42:45], v[154:157], v[170:173], v[42:45]
	v_mfma_f32_16x16x32_bf16 v[42:45], v[158:161], v[174:177], v[42:45]
	s_waitcnt lgkmcnt(0)
	s_setprio 0
	s_setprio 1
	v_mfma_f32_16x16x32_bf16 v[34:37], v[154:157], v[162:165], v[34:37]
	v_mfma_f32_16x16x32_bf16 v[34:37], v[158:161], v[166:169], v[34:37]
	s_setprio 0
	s_setprio 1
	v_mfma_f32_16x16x32_bf16 v[30:33], v[130:133], v[186:189], v[30:33]
	v_mfma_f32_16x16x32_bf16 v[30:33], v[134:137], v[190:193], v[30:33]
	s_setprio 0
	s_setprio 1
	v_mfma_f32_16x16x32_bf16 v[22:25], v[130:133], v[178:181], v[22:25]
	v_mfma_f32_16x16x32_bf16 v[22:25], v[134:137], v[182:185], v[22:25]
	s_setprio 0
	s_setprio 1
	v_mfma_f32_16x16x32_bf16 v[14:17], v[130:133], v[170:173], v[14:17]
	v_mfma_f32_16x16x32_bf16 v[14:17], v[134:137], v[174:177], v[14:17]
	s_setprio 0
	s_setprio 1
	v_mfma_f32_16x16x32_bf16 v[6:9], v[130:133], v[162:165], v[6:9]
	v_mfma_f32_16x16x32_bf16 v[6:9], v[134:137], v[166:169], v[6:9]
	s_setprio 0
	s_setprio 1
	v_mfma_f32_16x16x32_bf16 v[26:29], v[138:141], v[186:189], v[26:29]
	v_mfma_f32_16x16x32_bf16 v[26:29], v[142:145], v[190:193], v[26:29]
	s_setprio 0
	s_setprio 1
	v_mfma_f32_16x16x32_bf16 v[18:21], v[138:141], v[178:181], v[18:21]
	v_mfma_f32_16x16x32_bf16 v[18:21], v[142:145], v[182:185], v[18:21]
	s_setprio 0
	s_setprio 1
	v_mfma_f32_16x16x32_bf16 v[10:13], v[138:141], v[170:173], v[10:13]
	v_mfma_f32_16x16x32_bf16 v[10:13], v[142:145], v[174:177], v[10:13]
	s_setprio 2
	s_barrier
	v_mfma_f32_16x16x32_bf16 v[2:5], v[138:141], v[162:165], v[2:5]
	v_mfma_f32_16x16x32_bf16 v[2:5], v[142:145], v[166:169], v[2:5]
	s_setprio 0
	s_nop 0
	v_add_u32_e32 v142, 0x18000, v218
	v_add_u32_e32 v158, 0x1c000, v218
	ds_read_b128 v[130:133], v142
	ds_read_b128 v[134:137], v142 offset:1024
	ds_read_b128 v[138:141], v142 offset:2048
	ds_read_b128 v[142:145], v142 offset:3072
	ds_read_b128 v[146:149], v158
	ds_read_b128 v[150:153], v158 offset:1024
	ds_read_b128 v[154:157], v158 offset:2048
	ds_read_b128 v[158:161], v158 offset:3072
	ds_read_b128 v[162:165], v219 offset:32768
	ds_read_b128 v[166:169], v219 offset:33792
	ds_read_b128 v[170:173], v219 offset:34816
	ds_read_b128 v[174:177], v219 offset:35840
	ds_read_b128 v[178:181], v219 offset:36864
	ds_read_b128 v[182:185], v219 offset:37888
	ds_read_b128 v[186:189], v219 offset:38912
	ds_read_b128 v[190:193], v219 offset:39936
	s_add_u32 s24, s24, 0x4000
	s_addc_u32 s25, s25, 0
	s_mov_b32 m0, s55
	s_nop 0
	global_load_lds_dwordx4 v195, s[24:25]
	s_add_u32 m0, s55, 0x2000
	s_nop 0
	global_load_lds_dwordx4 v213, s[24:25]
	s_waitcnt vmcnt(8)
	s_waitcnt lgkmcnt(0)
	s_setprio 1
	s_barrier
	v_mfma_f32_16x16x32_bf16 v[126:129], v[130:133], v[162:165], v[126:129]
	v_mfma_f32_16x16x32_bf16 v[126:129], v[134:137], v[166:169], v[126:129]
	s_waitcnt lgkmcnt(5)
	s_setprio 0
	s_setprio 1
	v_mfma_f32_16x16x32_bf16 v[118:121], v[130:133], v[170:173], v[118:121]
	v_mfma_f32_16x16x32_bf16 v[118:121], v[134:137], v[174:177], v[118:121]
	s_waitcnt lgkmcnt(3)
	s_setprio 0
	s_setprio 1
	v_mfma_f32_16x16x32_bf16 v[110:113], v[130:133], v[178:181], v[110:113]
	v_mfma_f32_16x16x32_bf16 v[110:113], v[134:137], v[182:185], v[110:113]
	s_waitcnt lgkmcnt(1)
	s_setprio 0
	s_setprio 1
	v_mfma_f32_16x16x32_bf16 v[102:105], v[130:133], v[186:189], v[102:105]
	v_mfma_f32_16x16x32_bf16 v[102:105], v[134:137], v[190:193], v[102:105]
	s_setprio 0
	s_setprio 1
	v_mfma_f32_16x16x32_bf16 v[122:125], v[138:141], v[162:165], v[122:125]
	v_mfma_f32_16x16x32_bf16 v[122:125], v[142:145], v[166:169], v[122:125]
	s_setprio 0
	s_setprio 1
	v_mfma_f32_16x16x32_bf16 v[114:117], v[138:141], v[170:173], v[114:117]
	v_mfma_f32_16x16x32_bf16 v[114:117], v[142:145], v[174:177], v[114:117]
	s_setprio 0
	s_setprio 1
	v_mfma_f32_16x16x32_bf16 v[106:109], v[138:141], v[178:181], v[106:109]
	v_mfma_f32_16x16x32_bf16 v[106:109], v[142:145], v[182:185], v[106:109]
	s_waitcnt lgkmcnt(0)
	s_setprio 0
	s_setprio 1
	v_mfma_f32_16x16x32_bf16 v[98:101], v[138:141], v[186:189], v[98:101]
	v_mfma_f32_16x16x32_bf16 v[98:101], v[142:145], v[190:193], v[98:101]
	s_setprio 0
	s_setprio 1
	v_mfma_f32_16x16x32_bf16 v[94:97], v[146:149], v[162:165], v[94:97]
	v_mfma_f32_16x16x32_bf16 v[94:97], v[150:153], v[166:169], v[94:97]
	s_setprio 0
	s_setprio 1
	v_mfma_f32_16x16x32_bf16 v[86:89], v[146:149], v[170:173], v[86:89]
	v_mfma_f32_16x16x32_bf16 v[86:89], v[150:153], v[174:177], v[86:89]
	s_setprio 0
	s_setprio 1
	v_mfma_f32_16x16x32_bf16 v[78:81], v[146:149], v[178:181], v[78:81]
	v_mfma_f32_16x16x32_bf16 v[78:81], v[150:153], v[182:185], v[78:81]
	s_setprio 0
	s_setprio 1
	v_mfma_f32_16x16x32_bf16 v[70:73], v[146:149], v[186:189], v[70:73]
	v_mfma_f32_16x16x32_bf16 v[70:73], v[150:153], v[190:193], v[70:73]
	s_setprio 0
	s_setprio 1
	v_mfma_f32_16x16x32_bf16 v[90:93], v[154:157], v[162:165], v[90:93]
	v_mfma_f32_16x16x32_bf16 v[90:93], v[158:161], v[166:169], v[90:93]
	s_setprio 0
	s_setprio 1
	v_mfma_f32_16x16x32_bf16 v[82:85], v[154:157], v[170:173], v[82:85]
	v_mfma_f32_16x16x32_bf16 v[82:85], v[158:161], v[174:177], v[82:85]
	s_setprio 0
	s_setprio 1
	v_mfma_f32_16x16x32_bf16 v[74:77], v[154:157], v[178:181], v[74:77]
	v_mfma_f32_16x16x32_bf16 v[74:77], v[158:161], v[182:185], v[74:77]
	s_setprio 2
	s_barrier
	v_mfma_f32_16x16x32_bf16 v[66:69], v[154:157], v[186:189], v[66:69]
	v_mfma_f32_16x16x32_bf16 v[66:69], v[158:161], v[190:193], v[66:69]
	s_setprio 0
	s_nop 0
	ds_read_b128 v[162:165], v219 offset:49152
	ds_read_b128 v[166:169], v219 offset:50176
	ds_read_b128 v[170:173], v219 offset:51200
	ds_read_b128 v[174:177], v219 offset:52224
	ds_read_b128 v[178:181], v219 offset:53248
	ds_read_b128 v[182:185], v219 offset:54272
	ds_read_b128 v[186:189], v219 offset:55296
	ds_read_b128 v[190:193], v219 offset:56320
	s_mov_b32 m0, s83
	s_nop 0
	global_load_lds_dwordx4 v195, s[28:29]
	s_add_u32 m0, s83, 0x2000
	s_nop 0
	global_load_lds_dwordx4 v213, s[28:29]
	s_add_u32 s22, s22, 0xc000
	s_addc_u32 s23, s23, 0
	s_mov_b32 m0, s91
	s_nop 0
	global_load_lds_dwordx4 v195, s[22:23]
	s_add_u32 m0, s91, 0x2000
	s_nop 0
	global_load_lds_dwordx4 v213, s[22:23]
	s_nop 0
	s_mov_b32 m0, s90
	s_nop 0
	global_load_lds_dwordx4 v195, s[26:27]
	s_add_u32 m0, s90, 0x2000
	s_nop 0
	global_load_lds_dwordx4 v213, s[26:27]
	s_waitcnt vmcnt(8)
	s_waitcnt lgkmcnt(0)
	s_setprio 1
	s_barrier
	v_mfma_f32_16x16x32_bf16 v[62:65], v[130:133], v[162:165], v[62:65]
	v_mfma_f32_16x16x32_bf16 v[62:65], v[134:137], v[166:169], v[62:65]
	s_waitcnt lgkmcnt(5)
	s_setprio 0
	s_setprio 1
	v_mfma_f32_16x16x32_bf16 v[54:57], v[130:133], v[170:173], v[54:57]
	v_mfma_f32_16x16x32_bf16 v[54:57], v[134:137], v[174:177], v[54:57]
	s_waitcnt lgkmcnt(3)
	s_setprio 0
	s_setprio 1
	v_mfma_f32_16x16x32_bf16 v[46:49], v[130:133], v[178:181], v[46:49]
	v_mfma_f32_16x16x32_bf16 v[46:49], v[134:137], v[182:185], v[46:49]
	s_waitcnt lgkmcnt(1)
	s_setprio 0
	s_setprio 1
	v_mfma_f32_16x16x32_bf16 v[38:41], v[130:133], v[186:189], v[38:41]
	v_mfma_f32_16x16x32_bf16 v[38:41], v[134:137], v[190:193], v[38:41]
	s_setprio 0
	s_setprio 1
	v_mfma_f32_16x16x32_bf16 v[58:61], v[138:141], v[162:165], v[58:61]
	v_mfma_f32_16x16x32_bf16 v[58:61], v[142:145], v[166:169], v[58:61]
	s_setprio 0
	s_setprio 1
	v_mfma_f32_16x16x32_bf16 v[50:53], v[138:141], v[170:173], v[50:53]
	v_mfma_f32_16x16x32_bf16 v[50:53], v[142:145], v[174:177], v[50:53]
	s_setprio 0
	s_setprio 1
	v_mfma_f32_16x16x32_bf16 v[42:45], v[138:141], v[178:181], v[42:45]
	v_mfma_f32_16x16x32_bf16 v[42:45], v[142:145], v[182:185], v[42:45]
	s_waitcnt lgkmcnt(0)
	s_setprio 0
	s_setprio 1
	v_mfma_f32_16x16x32_bf16 v[34:37], v[138:141], v[186:189], v[34:37]
	v_mfma_f32_16x16x32_bf16 v[34:37], v[142:145], v[190:193], v[34:37]
	s_setprio 0
	s_setprio 1
	v_mfma_f32_16x16x32_bf16 v[30:33], v[146:149], v[162:165], v[30:33]
	v_mfma_f32_16x16x32_bf16 v[30:33], v[150:153], v[166:169], v[30:33]
	s_setprio 0
	s_setprio 1
	v_mfma_f32_16x16x32_bf16 v[22:25], v[146:149], v[170:173], v[22:25]
	v_mfma_f32_16x16x32_bf16 v[22:25], v[150:153], v[174:177], v[22:25]
	s_setprio 0
	s_setprio 1
	v_mfma_f32_16x16x32_bf16 v[14:17], v[146:149], v[178:181], v[14:17]
	v_mfma_f32_16x16x32_bf16 v[14:17], v[150:153], v[182:185], v[14:17]
	s_setprio 0
	s_setprio 1
	v_mfma_f32_16x16x32_bf16 v[6:9], v[146:149], v[186:189], v[6:9]
	v_mfma_f32_16x16x32_bf16 v[6:9], v[150:153], v[190:193], v[6:9]
	s_setprio 0
	s_setprio 1
	v_mfma_f32_16x16x32_bf16 v[26:29], v[154:157], v[162:165], v[26:29]
	v_mfma_f32_16x16x32_bf16 v[26:29], v[158:161], v[166:169], v[26:29]
	s_setprio 0
	s_setprio 1
	v_mfma_f32_16x16x32_bf16 v[18:21], v[154:157], v[170:173], v[18:21]
	v_mfma_f32_16x16x32_bf16 v[18:21], v[158:161], v[174:177], v[18:21]
	s_setprio 0
	s_setprio 1
	v_mfma_f32_16x16x32_bf16 v[10:13], v[154:157], v[178:181], v[10:13]
	v_mfma_f32_16x16x32_bf16 v[10:13], v[158:161], v[182:185], v[10:13]
	s_setprio 2
	s_barrier
	v_mfma_f32_16x16x32_bf16 v[2:5], v[154:157], v[186:189], v[2:5]
	v_mfma_f32_16x16x32_bf16 v[2:5], v[158:161], v[190:193], v[2:5]
	s_setprio 0
	s_nop 0
	s_add_i32 s3, s71, 2
	s_cmp_gt_u32 s71, 13
	s_cbranch_scc1 .LBB0_639
	s_mov_b32 s71, s3
	s_branch .LBB0_616

.LBB0_1068:
	s_or_b64 exec, exec, s[62:63]
	s_add_u32 s88, s12, s0
	ds_read_b128 v[132:135], v214
	ds_read_b128 v[136:139], v214 offset:1024
	ds_read_b128 v[140:143], v214 offset:2048
	ds_read_b128 v[144:147], v214 offset:3072
	ds_read_b128 v[154:157], v215
	ds_read_b128 v[158:161], v215 offset:1024
	ds_read_b128 v[162:165], v215 offset:2048
	ds_read_b128 v[166:169], v215 offset:3072
	s_addc_u32 s89, s13, s1
	s_add_u32 s62, s88, 0x20000
	s_addc_u32 s63, s89, 0
	s_add_u32 s64, s94, s0
	s_addc_u32 s65, s96, s1
	s_cmp_eq_u32 s0, 0x60000
	s_cselect_b32 s68, s53, s62
	s_cselect_b32 s69, s33, s63
	s_cselect_b32 s63, s51, s65
	s_cselect_b32 s62, s95, s64
	s_add_u32 s64, s68, 0x8000
	s_addc_u32 s65, s69, 0
	s_add_u32 s66, s62, 0x8000
	s_addc_u32 s67, s63, 0
	ds_read_b128 v[170:173], v216
	ds_read_b128 v[174:177], v216 offset:1024
	ds_read_b128 v[178:181], v216 offset:2048
	ds_read_b128 v[182:185], v216 offset:3072
	ds_read_b128 v[186:189], v216 offset:4096
	ds_read_b128 v[190:193], v216 offset:5120
	ds_read_b128 v[198:201], v216 offset:6144
	ds_read_b128 v[202:205], v216 offset:7168
	s_add_u32 s88, s88, 0x1c000
	s_addc_u32 s89, s89, 0
	s_mov_b32 m0, s79
	s_nop 0
	global_load_lds_dwordx4 v195, s[88:89]
	s_add_u32 m0, s79, 0x2000
	s_nop 0
	global_load_lds_dwordx4 v212, s[88:89]
	s_waitcnt vmcnt(8)
	s_waitcnt lgkmcnt(0)
	s_setprio 1
	s_barrier
	v_mfma_f32_16x16x32_bf16 v[126:129], v[132:135], v[170:173], v[126:129]
	v_mfma_f32_16x16x32_bf16 v[126:129], v[136:139], v[174:177], v[126:129]
	s_waitcnt lgkmcnt(5)
	s_setprio 0
	s_setprio 1
	v_mfma_f32_16x16x32_bf16 v[110:113], v[132:135], v[178:181], v[110:113]
	v_mfma_f32_16x16x32_bf16 v[110:113], v[136:139], v[182:185], v[110:113]
	s_waitcnt lgkmcnt(3)
	s_setprio 0
	s_setprio 1
	v_mfma_f32_16x16x32_bf16 v[94:97], v[132:135], v[186:189], v[94:97]
	v_mfma_f32_16x16x32_bf16 v[94:97], v[136:139], v[190:193], v[94:97]
	s_waitcnt lgkmcnt(1)
	s_setprio 0
	s_setprio 1
	v_mfma_f32_16x16x32_bf16 v[78:81], v[132:135], v[198:201], v[78:81]
	v_mfma_f32_16x16x32_bf16 v[78:81], v[136:139], v[202:205], v[78:81]
	s_setprio 0
	s_setprio 1
	v_mfma_f32_16x16x32_bf16 v[122:125], v[140:143], v[170:173], v[122:125]
	v_mfma_f32_16x16x32_bf16 v[122:125], v[144:147], v[174:177], v[122:125]
	s_setprio 0
	s_setprio 1
	v_mfma_f32_16x16x32_bf16 v[106:109], v[140:143], v[178:181], v[106:109]
	v_mfma_f32_16x16x32_bf16 v[106:109], v[144:147], v[182:185], v[106:109]
	s_setprio 0
	s_setprio 1
	v_mfma_f32_16x16x32_bf16 v[90:93], v[140:143], v[186:189], v[90:93]
	v_mfma_f32_16x16x32_bf16 v[90:93], v[144:147], v[190:193], v[90:93]
	s_waitcnt lgkmcnt(0)
	s_setprio 0
	s_setprio 1
	v_mfma_f32_16x16x32_bf16 v[74:77], v[140:143], v[198:201], v[74:77]
	v_mfma_f32_16x16x32_bf16 v[74:77], v[144:147], v[202:205], v[74:77]
	s_setprio 0
	s_setprio 1
	v_mfma_f32_16x16x32_bf16 v[118:121], v[154:157], v[170:173], v[118:121]
	v_mfma_f32_16x16x32_bf16 v[118:121], v[158:161], v[174:177], v[118:121]
	s_setprio 0
	s_setprio 1
	v_mfma_f32_16x16x32_bf16 v[102:105], v[154:157], v[178:181], v[102:105]
	v_mfma_f32_16x16x32_bf16 v[102:105], v[158:161], v[182:185], v[102:105]
	s_setprio 0
	s_setprio 1
	v_mfma_f32_16x16x32_bf16 v[86:89], v[154:157], v[186:189], v[86:89]
	v_mfma_f32_16x16x32_bf16 v[86:89], v[158:161], v[190:193], v[86:89]
	s_setprio 0
	s_setprio 1
	v_mfma_f32_16x16x32_bf16 v[70:73], v[154:157], v[198:201], v[70:73]
	v_mfma_f32_16x16x32_bf16 v[70:73], v[158:161], v[202:205], v[70:73]
	s_setprio 0
	s_setprio 1
	v_mfma_f32_16x16x32_bf16 v[114:117], v[162:165], v[170:173], v[114:117]
	v_mfma_f32_16x16x32_bf16 v[114:117], v[166:169], v[174:177], v[114:117]
	s_setprio 0
	s_setprio 1
	v_mfma_f32_16x16x32_bf16 v[98:101], v[162:165], v[178:181], v[98:101]
	v_mfma_f32_16x16x32_bf16 v[98:101], v[166:169], v[182:185], v[98:101]
	s_setprio 0
	s_setprio 1
	v_mfma_f32_16x16x32_bf16 v[82:85], v[162:165], v[186:189], v[82:85]
	v_mfma_f32_16x16x32_bf16 v[82:85], v[166:169], v[190:193], v[82:85]
	s_setprio 2
	s_barrier
	v_mfma_f32_16x16x32_bf16 v[66:69], v[162:165], v[198:201], v[66:69]
	v_mfma_f32_16x16x32_bf16 v[66:69], v[166:169], v[202:205], v[66:69]
	s_setprio 0
	s_nop 0
	ds_read_b128 v[170:173], v216 offset:16384
	ds_read_b128 v[174:177], v216 offset:17408
	ds_read_b128 v[178:181], v216 offset:18432
	ds_read_b128 v[182:185], v216 offset:19456
	ds_read_b128 v[186:189], v216 offset:20480
	ds_read_b128 v[190:193], v216 offset:21504
	ds_read_b128 v[198:201], v216 offset:22528
	ds_read_b128 v[202:205], v216 offset:23552
	s_mov_b32 m0, s3
	s_nop 0
	global_load_lds_dwordx4 v195, s[62:63]
	s_add_u32 m0, s3, 0x2000
	s_nop 0
	global_load_lds_dwordx4 v212, s[62:63]
	s_add_u32 s88, s62, 0x4000
	s_addc_u32 s89, s63, 0
	s_mov_b32 m0, s71
	s_nop 0
	global_load_lds_dwordx4 v195, s[88:89]
	s_add_u32 m0, s71, 0x2000
	s_nop 0
	global_load_lds_dwordx4 v212, s[88:89]
	s_nop 0
	s_mov_b32 m0, s70
	s_nop 0
	global_load_lds_dwordx4 v195, s[68:69]
	s_add_u32 m0, s70, 0x2000
	s_nop 0
	global_load_lds_dwordx4 v212, s[68:69]
	s_waitcnt vmcnt(8)
	s_waitcnt lgkmcnt(0)
	s_setprio 1
	s_barrier
	v_mfma_f32_16x16x32_bf16 v[62:65], v[132:135], v[170:173], v[62:65]
	v_mfma_f32_16x16x32_bf16 v[62:65], v[136:139], v[174:177], v[62:65]
	s_waitcnt lgkmcnt(5)
	s_setprio 0
	s_setprio 1
	v_mfma_f32_16x16x32_bf16 v[46:49], v[132:135], v[178:181], v[46:49]
	v_mfma_f32_16x16x32_bf16 v[46:49], v[136:139], v[182:185], v[46:49]
	s_waitcnt lgkmcnt(3)
	s_setprio 0
	s_setprio 1
	v_mfma_f32_16x16x32_bf16 v[30:33], v[132:135], v[186:189], v[30:33]
	v_mfma_f32_16x16x32_bf16 v[30:33], v[136:139], v[190:193], v[30:33]
	s_waitcnt lgkmcnt(1)
	s_setprio 0
	s_setprio 1
	v_mfma_f32_16x16x32_bf16 v[14:17], v[132:135], v[198:201], v[14:17]
	v_mfma_f32_16x16x32_bf16 v[14:17], v[136:139], v[202:205], v[14:17]
	s_setprio 0
	s_setprio 1
	v_mfma_f32_16x16x32_bf16 v[58:61], v[140:143], v[170:173], v[58:61]
	v_mfma_f32_16x16x32_bf16 v[58:61], v[144:147], v[174:177], v[58:61]
	s_setprio 0
	s_setprio 1
	v_mfma_f32_16x16x32_bf16 v[42:45], v[140:143], v[178:181], v[42:45]
	v_mfma_f32_16x16x32_bf16 v[42:45], v[144:147], v[182:185], v[42:45]
	s_setprio 0
	s_setprio 1
	v_mfma_f32_16x16x32_bf16 v[26:29], v[140:143], v[186:189], v[26:29]
	v_mfma_f32_16x16x32_bf16 v[26:29], v[144:147], v[190:193], v[26:29]
	s_waitcnt lgkmcnt(0)
	s_setprio 0
	s_setprio 1
	v_mfma_f32_16x16x32_bf16 v[10:13], v[140:143], v[198:201], v[10:13]
	v_mfma_f32_16x16x32_bf16 v[10:13], v[144:147], v[202:205], v[10:13]
	s_setprio 0
	s_setprio 1
	v_mfma_f32_16x16x32_bf16 v[54:57], v[154:157], v[170:173], v[54:57]
	v_mfma_f32_16x16x32_bf16 v[54:57], v[158:161], v[174:177], v[54:57]
	s_setprio 0
	s_setprio 1
	v_mfma_f32_16x16x32_bf16 v[38:41], v[154:157], v[178:181], v[38:41]
	v_mfma_f32_16x16x32_bf16 v[38:41], v[158:161], v[182:185], v[38:41]
	s_setprio 0
	s_setprio 1
	v_mfma_f32_16x16x32_bf16 v[22:25], v[154:157], v[186:189], v[22:25]
	v_mfma_f32_16x16x32_bf16 v[22:25], v[158:161], v[190:193], v[22:25]
	s_setprio 0
	s_setprio 1
	v_mfma_f32_16x16x32_bf16 v[6:9], v[154:157], v[198:201], v[6:9]
	v_mfma_f32_16x16x32_bf16 v[6:9], v[158:161], v[202:205], v[6:9]
	s_setprio 0
	s_setprio 1
	v_mfma_f32_16x16x32_bf16 v[50:53], v[162:165], v[170:173], v[50:53]
	v_mfma_f32_16x16x32_bf16 v[50:53], v[166:169], v[174:177], v[50:53]
	s_setprio 0
	s_setprio 1
	v_mfma_f32_16x16x32_bf16 v[34:37], v[162:165], v[178:181], v[34:37]
	v_mfma_f32_16x16x32_bf16 v[34:37], v[166:169], v[182:185], v[34:37]
	s_setprio 0
	s_setprio 1
	v_mfma_f32_16x16x32_bf16 v[18:21], v[162:165], v[186:189], v[18:21]
	v_mfma_f32_16x16x32_bf16 v[18:21], v[166:169], v[190:193], v[18:21]
	s_setprio 2
	s_barrier
	v_mfma_f32_16x16x32_bf16 v[2:5], v[162:165], v[198:201], v[2:5]
	v_mfma_f32_16x16x32_bf16 v[2:5], v[166:169], v[202:205], v[2:5]
	s_setprio 0
	s_nop 0
	ds_read_b128 v[132:135], v217
	ds_read_b128 v[136:139], v217 offset:1024
	ds_read_b128 v[140:143], v217 offset:2048
	ds_read_b128 v[144:147], v217 offset:3072
	ds_read_b128 v[154:157], v218
	ds_read_b128 v[158:161], v218 offset:1024
	ds_read_b128 v[162:165], v218 offset:2048
	ds_read_b128 v[166:169], v218 offset:3072
	ds_read_b128 v[170:173], v216 offset:32768
	ds_read_b128 v[174:177], v216 offset:33792
	ds_read_b128 v[178:181], v216 offset:34816
	ds_read_b128 v[182:185], v216 offset:35840
	ds_read_b128 v[186:189], v216 offset:36864
	ds_read_b128 v[190:193], v216 offset:37888
	ds_read_b128 v[198:201], v216 offset:38912
	ds_read_b128 v[202:205], v216 offset:39936
	s_add_u32 s68, s68, 0x4000
	s_addc_u32 s69, s69, 0
	s_mov_b32 m0, s72
	s_nop 0
	global_load_lds_dwordx4 v195, s[68:69]
	s_add_u32 m0, s72, 0x2000
	s_nop 0
	global_load_lds_dwordx4 v212, s[68:69]
	s_waitcnt vmcnt(8)
	s_waitcnt lgkmcnt(0)
	s_setprio 1
	s_barrier
	v_mfma_f32_16x16x32_bf16 v[126:129], v[132:135], v[170:173], v[126:129]
	v_mfma_f32_16x16x32_bf16 v[126:129], v[136:139], v[174:177], v[126:129]
	s_waitcnt lgkmcnt(5)
	s_setprio 0
	s_setprio 1
	v_mfma_f32_16x16x32_bf16 v[110:113], v[132:135], v[178:181], v[110:113]
	v_mfma_f32_16x16x32_bf16 v[110:113], v[136:139], v[182:185], v[110:113]
	s_waitcnt lgkmcnt(3)
	s_setprio 0
	s_setprio 1
	v_mfma_f32_16x16x32_bf16 v[94:97], v[132:135], v[186:189], v[94:97]
	v_mfma_f32_16x16x32_bf16 v[94:97], v[136:139], v[190:193], v[94:97]
	s_waitcnt lgkmcnt(1)
	s_setprio 0
	s_setprio 1
	v_mfma_f32_16x16x32_bf16 v[78:81], v[132:135], v[198:201], v[78:81]
	v_mfma_f32_16x16x32_bf16 v[78:81], v[136:139], v[202:205], v[78:81]
	s_setprio 0
	s_setprio 1
	v_mfma_f32_16x16x32_bf16 v[122:125], v[140:143], v[170:173], v[122:125]
	v_mfma_f32_16x16x32_bf16 v[122:125], v[144:147], v[174:177], v[122:125]
	s_setprio 0
	s_setprio 1
	v_mfma_f32_16x16x32_bf16 v[106:109], v[140:143], v[178:181], v[106:109]
	v_mfma_f32_16x16x32_bf16 v[106:109], v[144:147], v[182:185], v[106:109]
	s_setprio 0
	s_setprio 1
	v_mfma_f32_16x16x32_bf16 v[90:93], v[140:143], v[186:189], v[90:93]
	v_mfma_f32_16x16x32_bf16 v[90:93], v[144:147], v[190:193], v[90:93]
	s_waitcnt lgkmcnt(0)
	s_setprio 0
	s_setprio 1
	v_mfma_f32_16x16x32_bf16 v[74:77], v[140:143], v[198:201], v[74:77]
	v_mfma_f32_16x16x32_bf16 v[74:77], v[144:147], v[202:205], v[74:77]
	s_setprio 0
	s_setprio 1
	v_mfma_f32_16x16x32_bf16 v[118:121], v[154:157], v[170:173], v[118:121]
	v_mfma_f32_16x16x32_bf16 v[118:121], v[158:161], v[174:177], v[118:121]
	s_setprio 0
	s_setprio 1
	v_mfma_f32_16x16x32_bf16 v[102:105], v[154:157], v[178:181], v[102:105]
	v_mfma_f32_16x16x32_bf16 v[102:105], v[158:161], v[182:185], v[102:105]
	s_setprio 0
	s_setprio 1
	v_mfma_f32_16x16x32_bf16 v[86:89], v[154:157], v[186:189], v[86:89]
	v_mfma_f32_16x16x32_bf16 v[86:89], v[158:161], v[190:193], v[86:89]
	s_setprio 0
	s_setprio 1
	v_mfma_f32_16x16x32_bf16 v[70:73], v[154:157], v[198:201], v[70:73]
	v_mfma_f32_16x16x32_bf16 v[70:73], v[158:161], v[202:205], v[70:73]
	s_setprio 0
	s_setprio 1
	v_mfma_f32_16x16x32_bf16 v[114:117], v[162:165], v[170:173], v[114:117]
	v_mfma_f32_16x16x32_bf16 v[114:117], v[166:169], v[174:177], v[114:117]
	s_setprio 0
	s_setprio 1
	v_mfma_f32_16x16x32_bf16 v[98:101], v[162:165], v[178:181], v[98:101]
	v_mfma_f32_16x16x32_bf16 v[98:101], v[166:169], v[182:185], v[98:101]
	s_setprio 0
	s_setprio 1
	v_mfma_f32_16x16x32_bf16 v[82:85], v[162:165], v[186:189], v[82:85]
	v_mfma_f32_16x16x32_bf16 v[82:85], v[166:169], v[190:193], v[82:85]
	s_setprio 2
	s_barrier
	v_mfma_f32_16x16x32_bf16 v[66:69], v[162:165], v[198:201], v[66:69]
	v_mfma_f32_16x16x32_bf16 v[66:69], v[166:169], v[202:205], v[66:69]
	s_setprio 0
	s_nop 0
	ds_read_b128 v[170:173], v216 offset:49152
	ds_read_b128 v[174:177], v216 offset:50176
	ds_read_b128 v[178:181], v216 offset:51200
	ds_read_b128 v[182:185], v216 offset:52224
	ds_read_b128 v[186:189], v216 offset:53248
	ds_read_b128 v[190:193], v216 offset:54272
	ds_read_b128 v[198:201], v216 offset:55296
	ds_read_b128 v[202:205], v216 offset:56320
	s_mov_b32 m0, s76
	s_nop 0
	global_load_lds_dwordx4 v195, s[66:67]
	s_add_u32 m0, s76, 0x2000
	s_nop 0
	global_load_lds_dwordx4 v212, s[66:67]
	s_add_u32 s62, s62, 0xc000
	s_addc_u32 s63, s63, 0
	s_mov_b32 m0, s78
	s_nop 0
	global_load_lds_dwordx4 v195, s[62:63]
	s_add_u32 m0, s78, 0x2000
	s_nop 0
	global_load_lds_dwordx4 v212, s[62:63]
	s_nop 0
	s_mov_b32 m0, s77
	s_nop 0
	global_load_lds_dwordx4 v195, s[64:65]
	s_add_u32 m0, s77, 0x2000
	s_nop 0
	global_load_lds_dwordx4 v212, s[64:65]
	s_waitcnt vmcnt(8)
	s_waitcnt lgkmcnt(0)
	s_setprio 1
	s_barrier
	v_mfma_f32_16x16x32_bf16 v[62:65], v[132:135], v[170:173], v[62:65]
	v_mfma_f32_16x16x32_bf16 v[62:65], v[136:139], v[174:177], v[62:65]
	s_waitcnt lgkmcnt(5)
	s_setprio 0
	s_setprio 1
	v_mfma_f32_16x16x32_bf16 v[46:49], v[132:135], v[178:181], v[46:49]
	v_mfma_f32_16x16x32_bf16 v[46:49], v[136:139], v[182:185], v[46:49]
	s_waitcnt lgkmcnt(3)
	s_setprio 0
	s_setprio 1
	v_mfma_f32_16x16x32_bf16 v[30:33], v[132:135], v[186:189], v[30:33]
	v_mfma_f32_16x16x32_bf16 v[30:33], v[136:139], v[190:193], v[30:33]
	s_waitcnt lgkmcnt(1)
	s_setprio 0
	s_setprio 1
	v_mfma_f32_16x16x32_bf16 v[14:17], v[132:135], v[198:201], v[14:17]
	v_mfma_f32_16x16x32_bf16 v[14:17], v[136:139], v[202:205], v[14:17]
	s_setprio 0
	s_setprio 1
	v_mfma_f32_16x16x32_bf16 v[58:61], v[140:143], v[170:173], v[58:61]
	v_mfma_f32_16x16x32_bf16 v[58:61], v[144:147], v[174:177], v[58:61]
	s_setprio 0
	s_setprio 1
	v_mfma_f32_16x16x32_bf16 v[42:45], v[140:143], v[178:181], v[42:45]
	v_mfma_f32_16x16x32_bf16 v[42:45], v[144:147], v[182:185], v[42:45]
	s_setprio 0
	s_setprio 1
	v_mfma_f32_16x16x32_bf16 v[26:29], v[140:143], v[186:189], v[26:29]
	v_mfma_f32_16x16x32_bf16 v[26:29], v[144:147], v[190:193], v[26:29]
	s_waitcnt lgkmcnt(0)
	s_setprio 0
	s_setprio 1
	v_mfma_f32_16x16x32_bf16 v[10:13], v[140:143], v[198:201], v[10:13]
	v_mfma_f32_16x16x32_bf16 v[10:13], v[144:147], v[202:205], v[10:13]
	s_setprio 0
	s_setprio 1
	v_mfma_f32_16x16x32_bf16 v[54:57], v[154:157], v[170:173], v[54:57]
	v_mfma_f32_16x16x32_bf16 v[54:57], v[158:161], v[174:177], v[54:57]
	s_setprio 0
	s_setprio 1
	v_mfma_f32_16x16x32_bf16 v[38:41], v[154:157], v[178:181], v[38:41]
	v_mfma_f32_16x16x32_bf16 v[38:41], v[158:161], v[182:185], v[38:41]
	s_setprio 0
	s_setprio 1
	v_mfma_f32_16x16x32_bf16 v[22:25], v[154:157], v[186:189], v[22:25]
	v_mfma_f32_16x16x32_bf16 v[22:25], v[158:161], v[190:193], v[22:25]
	s_setprio 0
	s_setprio 1
	v_mfma_f32_16x16x32_bf16 v[6:9], v[154:157], v[198:201], v[6:9]
	v_mfma_f32_16x16x32_bf16 v[6:9], v[158:161], v[202:205], v[6:9]
	s_setprio 0
	s_setprio 1
	v_mfma_f32_16x16x32_bf16 v[50:53], v[162:165], v[170:173], v[50:53]
	v_mfma_f32_16x16x32_bf16 v[50:53], v[166:169], v[174:177], v[50:53]
	s_setprio 0
	s_setprio 1
	v_mfma_f32_16x16x32_bf16 v[34:37], v[162:165], v[178:181], v[34:37]
	v_mfma_f32_16x16x32_bf16 v[34:37], v[166:169], v[182:185], v[34:37]
	s_setprio 0
	s_setprio 1
	v_mfma_f32_16x16x32_bf16 v[18:21], v[162:165], v[186:189], v[18:21]
	v_mfma_f32_16x16x32_bf16 v[18:21], v[166:169], v[190:193], v[18:21]
	s_setprio 2
	s_barrier
	v_mfma_f32_16x16x32_bf16 v[2:5], v[162:165], v[198:201], v[2:5]
	v_mfma_f32_16x16x32_bf16 v[2:5], v[166:169], v[202:205], v[2:5]
	s_setprio 0
	s_nop 0
	s_add_i32 s97, s97, 2
	s_add_u32 s0, s0, 0x10000
	s_addc_u32 s1, s1, 0
	s_cmp_gt_u32 s97, 13
	s_cbranch_scc1 .LBB0_1070
	v_mov_b32_e32 v131, v130
	s_branch .LBB0_1066

.LBB0_1336:
	s_add_u32 s50, s46, 0x10000
	s_addc_u32 s51, s47, 0
	s_and_b64 s[46:47], s[42:43], exec
	s_cselect_b32 s47, s51, s23
	s_cselect_b32 s46, s50, s75
	s_add_u32 s13, s16, s13
	s_addc_u32 s50, s17, 0
	s_add_u32 s13, s13, 0x10000
	s_waitcnt vmcnt(8)
	s_addc_u32 s50, s50, 0
	s_waitcnt lgkmcnt(0)
	s_and_b64 s[42:43], s[42:43], exec
	s_cselect_b32 s43, s50, s25
	s_cselect_b32 s42, s13, s76
	s_setprio 1
	s_barrier
	v_mfma_f32_16x16x32_bf16 v[126:129], v[146:149], v[186:189], v[126:129]
	v_mfma_f32_16x16x32_bf16 v[126:129], v[150:153], v[190:193], v[126:129]
	s_waitcnt lgkmcnt(5)
	s_setprio 0
	s_setprio 1
	v_mfma_f32_16x16x32_bf16 v[118:121], v[146:149], v[178:181], v[118:121]
	v_mfma_f32_16x16x32_bf16 v[118:121], v[150:153], v[182:185], v[118:121]
	s_waitcnt lgkmcnt(3)
	s_setprio 0
	s_setprio 1
	v_mfma_f32_16x16x32_bf16 v[110:113], v[146:149], v[170:173], v[110:113]
	v_mfma_f32_16x16x32_bf16 v[110:113], v[150:153], v[174:177], v[110:113]
	s_waitcnt lgkmcnt(1)
	s_setprio 0
	s_setprio 1
	v_mfma_f32_16x16x32_bf16 v[102:105], v[146:149], v[162:165], v[102:105]
	v_mfma_f32_16x16x32_bf16 v[102:105], v[150:153], v[166:169], v[102:105]
	s_setprio 0
	s_setprio 1
	v_mfma_f32_16x16x32_bf16 v[122:125], v[154:157], v[186:189], v[122:125]
	v_mfma_f32_16x16x32_bf16 v[122:125], v[158:161], v[190:193], v[122:125]
	s_setprio 0
	s_setprio 1
	v_mfma_f32_16x16x32_bf16 v[114:117], v[154:157], v[178:181], v[114:117]
	v_mfma_f32_16x16x32_bf16 v[114:117], v[158:161], v[182:185], v[114:117]
	s_setprio 0
	s_setprio 1
	v_mfma_f32_16x16x32_bf16 v[106:109], v[154:157], v[170:173], v[106:109]
	v_mfma_f32_16x16x32_bf16 v[106:109], v[158:161], v[174:177], v[106:109]
	s_waitcnt lgkmcnt(0)
	s_setprio 0
	s_setprio 1
	v_mfma_f32_16x16x32_bf16 v[98:101], v[154:157], v[162:165], v[98:101]
	v_mfma_f32_16x16x32_bf16 v[98:101], v[158:161], v[166:169], v[98:101]
	s_setprio 0
	s_setprio 1
	v_mfma_f32_16x16x32_bf16 v[94:97], v[130:133], v[186:189], v[94:97]
	v_mfma_f32_16x16x32_bf16 v[94:97], v[134:137], v[190:193], v[94:97]
	s_setprio 0
	s_setprio 1
	v_mfma_f32_16x16x32_bf16 v[86:89], v[130:133], v[178:181], v[86:89]
	v_mfma_f32_16x16x32_bf16 v[86:89], v[134:137], v[182:185], v[86:89]
	s_setprio 0
	s_setprio 1
	v_mfma_f32_16x16x32_bf16 v[78:81], v[130:133], v[170:173], v[78:81]
	v_mfma_f32_16x16x32_bf16 v[78:81], v[134:137], v[174:177], v[78:81]
	s_setprio 0
	s_setprio 1
	v_mfma_f32_16x16x32_bf16 v[70:73], v[130:133], v[162:165], v[70:73]
	v_mfma_f32_16x16x32_bf16 v[70:73], v[134:137], v[166:169], v[70:73]
	s_setprio 0
	s_setprio 1
	v_mfma_f32_16x16x32_bf16 v[90:93], v[138:141], v[186:189], v[90:93]
	v_mfma_f32_16x16x32_bf16 v[90:93], v[142:145], v[190:193], v[90:93]
	s_setprio 0
	s_setprio 1
	v_mfma_f32_16x16x32_bf16 v[82:85], v[138:141], v[178:181], v[82:85]
	v_mfma_f32_16x16x32_bf16 v[82:85], v[142:145], v[182:185], v[82:85]
	s_setprio 0
	s_setprio 1
	v_mfma_f32_16x16x32_bf16 v[74:77], v[138:141], v[170:173], v[74:77]
	v_mfma_f32_16x16x32_bf16 v[74:77], v[142:145], v[174:177], v[74:77]
	s_setprio 2
	s_barrier
	v_mfma_f32_16x16x32_bf16 v[66:69], v[138:141], v[162:165], v[66:69]
	v_mfma_f32_16x16x32_bf16 v[66:69], v[142:145], v[166:169], v[66:69]
	s_setprio 0
	s_nop 0
	ds_read_b128 v[186:189], v208 offset:16384
	ds_read_b128 v[190:193], v208 offset:17408
	ds_read_b128 v[178:181], v208 offset:18432
	ds_read_b128 v[182:185], v208 offset:19456
	ds_read_b128 v[170:173], v208 offset:20480
	ds_read_b128 v[174:177], v208 offset:21504
	ds_read_b128 v[162:165], v208 offset:22528
	ds_read_b128 v[166:169], v208 offset:23552
	s_mov_b32 m0, s58
	s_nop 0
	global_load_lds_dwordx4 v202, s[42:43]
	s_add_u32 m0, s58, 0x2000
	s_nop 0
	global_load_lds_dwordx4 v203, s[42:43]
	s_add_u32 s50, s42, 0x4000
	s_addc_u32 s51, s43, 0
	s_mov_b32 m0, s59
	s_nop 0
	global_load_lds_dwordx4 v202, s[50:51]
	s_add_u32 m0, s59, 0x2000
	s_nop 0
	global_load_lds_dwordx4 v203, s[50:51]
	s_andn2_b64 vcc, exec, s[48:49]
	s_mov_b32 m0, s7
	s_nop 0
	global_load_lds_dwordx4 v202, s[46:47]
	s_add_u32 m0, s7, 0x2000
	s_nop 0
	global_load_lds_dwordx4 v203, s[46:47]
	s_cbranch_vccnz .LBB0_1338
	v_mov_b32_e32 v2, 0
	v_mov_b32_e32 v3, v2
	v_mov_b32_e32 v4, v2
	v_mov_b32_e32 v5, v2
	v_mov_b32_e32 v6, v2
	v_mov_b32_e32 v7, v2
	v_mov_b32_e32 v8, v2
	v_mov_b32_e32 v9, v2
	v_mov_b32_e32 v10, v2
	v_mov_b32_e32 v11, v2
	v_mov_b32_e32 v12, v2
	v_mov_b32_e32 v13, v2
	v_mov_b32_e32 v14, v2
	v_mov_b32_e32 v15, v2
	v_mov_b32_e32 v16, v2
	v_mov_b32_e32 v17, v2
	v_mov_b32_e32 v18, v2
	v_mov_b32_e32 v19, v2
	v_mov_b32_e32 v20, v2
	v_mov_b32_e32 v21, v2
	v_mov_b32_e32 v22, v2
	v_mov_b32_e32 v23, v2
	v_mov_b32_e32 v24, v2
	v_mov_b32_e32 v25, v2
	v_mov_b32_e32 v26, v2
	v_mov_b32_e32 v27, v2
	v_mov_b32_e32 v28, v2
	v_mov_b32_e32 v29, v2
	v_mov_b32_e32 v30, v2
	v_mov_b32_e32 v31, v2
	v_mov_b32_e32 v32, v2
	v_mov_b32_e32 v33, v2
	v_mov_b32_e32 v34, v2
	v_mov_b32_e32 v35, v2
	v_mov_b32_e32 v36, v2
	v_mov_b32_e32 v37, v2
	v_mov_b32_e32 v38, v2
	v_mov_b32_e32 v39, v2
	v_mov_b32_e32 v40, v2
	v_mov_b32_e32 v41, v2
	v_mov_b32_e32 v42, v2
	v_mov_b32_e32 v43, v2
	v_mov_b32_e32 v44, v2
	v_mov_b32_e32 v45, v2
	v_mov_b32_e32 v46, v2
	v_mov_b32_e32 v47, v2
	v_mov_b32_e32 v48, v2
	v_mov_b32_e32 v49, v2
	v_mov_b32_e32 v50, v2
	v_mov_b32_e32 v51, v2
	v_mov_b32_e32 v52, v2
	v_mov_b32_e32 v53, v2
	v_mov_b32_e32 v54, v2
	v_mov_b32_e32 v55, v2
	v_mov_b32_e32 v56, v2
	v_mov_b32_e32 v57, v2
	v_mov_b32_e32 v58, v2
	v_mov_b32_e32 v59, v2
	v_mov_b32_e32 v60, v2
	v_mov_b32_e32 v61, v2
	v_mov_b32_e32 v62, v2
	v_mov_b32_e32 v63, v2
	v_mov_b32_e32 v64, v2
	v_mov_b32_e32 v65, v2
.LBB0_1338:
	s_waitcnt vmcnt(8)
	s_add_u32 s48, s46, 0x8000
	s_waitcnt lgkmcnt(0)
	s_addc_u32 s49, s47, 0
	s_add_u32 s50, s42, 0x8000
	s_addc_u32 s51, s43, 0
	s_setprio 1
	s_barrier
	v_mfma_f32_16x16x32_bf16 v[62:65], v[146:149], v[186:189], v[62:65]
	v_mfma_f32_16x16x32_bf16 v[62:65], v[150:153], v[190:193], v[62:65]
	s_waitcnt lgkmcnt(5)
	s_setprio 0
	s_setprio 1
	v_mfma_f32_16x16x32_bf16 v[54:57], v[146:149], v[178:181], v[54:57]
	v_mfma_f32_16x16x32_bf16 v[54:57], v[150:153], v[182:185], v[54:57]
	s_waitcnt lgkmcnt(3)
	s_setprio 0
	s_setprio 1
	v_mfma_f32_16x16x32_bf16 v[46:49], v[146:149], v[170:173], v[46:49]
	v_mfma_f32_16x16x32_bf16 v[46:49], v[150:153], v[174:177], v[46:49]
	s_waitcnt lgkmcnt(1)
	s_setprio 0
	s_setprio 1
	v_mfma_f32_16x16x32_bf16 v[38:41], v[146:149], v[162:165], v[38:41]
	v_mfma_f32_16x16x32_bf16 v[38:41], v[150:153], v[166:169], v[38:41]
	s_setprio 0
	s_setprio 1
	v_mfma_f32_16x16x32_bf16 v[58:61], v[154:157], v[186:189], v[58:61]
	v_mfma_f32_16x16x32_bf16 v[58:61], v[158:161], v[190:193], v[58:61]
	s_setprio 0
	s_setprio 1
	v_mfma_f32_16x16x32_bf16 v[50:53], v[154:157], v[178:181], v[50:53]
	v_mfma_f32_16x16x32_bf16 v[50:53], v[158:161], v[182:185], v[50:53]
	s_setprio 0
	s_setprio 1
	v_mfma_f32_16x16x32_bf16 v[42:45], v[154:157], v[170:173], v[42:45]
	v_mfma_f32_16x16x32_bf16 v[42:45], v[158:161], v[174:177], v[42:45]
	s_waitcnt lgkmcnt(0)
	s_setprio 0
	s_setprio 1
	v_mfma_f32_16x16x32_bf16 v[34:37], v[154:157], v[162:165], v[34:37]
	v_mfma_f32_16x16x32_bf16 v[34:37], v[158:161], v[166:169], v[34:37]
	s_setprio 0
	s_setprio 1
	v_mfma_f32_16x16x32_bf16 v[30:33], v[130:133], v[186:189], v[30:33]
	v_mfma_f32_16x16x32_bf16 v[30:33], v[134:137], v[190:193], v[30:33]
	s_setprio 0
	s_setprio 1
	v_mfma_f32_16x16x32_bf16 v[22:25], v[130:133], v[178:181], v[22:25]
	v_mfma_f32_16x16x32_bf16 v[22:25], v[134:137], v[182:185], v[22:25]
	s_setprio 0
	s_setprio 1
	v_mfma_f32_16x16x32_bf16 v[14:17], v[130:133], v[170:173], v[14:17]
	v_mfma_f32_16x16x32_bf16 v[14:17], v[134:137], v[174:177], v[14:17]
	s_setprio 0
	s_setprio 1
	v_mfma_f32_16x16x32_bf16 v[6:9], v[130:133], v[162:165], v[6:9]
	v_mfma_f32_16x16x32_bf16 v[6:9], v[134:137], v[166:169], v[6:9]
	s_setprio 0
	s_setprio 1
	v_mfma_f32_16x16x32_bf16 v[26:29], v[138:141], v[186:189], v[26:29]
	v_mfma_f32_16x16x32_bf16 v[26:29], v[142:145], v[190:193], v[26:29]
	s_setprio 0
	s_setprio 1
	v_mfma_f32_16x16x32_bf16 v[18:21], v[138:141], v[178:181], v[18:21]
	v_mfma_f32_16x16x32_bf16 v[18:21], v[142:145], v[182:185], v[18:21]
	s_setprio 0
	s_setprio 1
	v_mfma_f32_16x16x32_bf16 v[10:13], v[138:141], v[170:173], v[10:13]
	v_mfma_f32_16x16x32_bf16 v[10:13], v[142:145], v[174:177], v[10:13]
	s_setprio 2
	s_barrier
	v_mfma_f32_16x16x32_bf16 v[2:5], v[138:141], v[162:165], v[2:5]
	v_mfma_f32_16x16x32_bf16 v[2:5], v[142:145], v[166:169], v[2:5]
	s_setprio 0
	s_nop 0
	v_add_u32_e32 v142, 0x18000, v207
	v_add_u32_e32 v158, 0x1c000, v207
	ds_read_b128 v[130:133], v142
	ds_read_b128 v[134:137], v142 offset:1024
	ds_read_b128 v[138:141], v142 offset:2048
	ds_read_b128 v[142:145], v142 offset:3072
	ds_read_b128 v[146:149], v158
	ds_read_b128 v[150:153], v158 offset:1024
	ds_read_b128 v[154:157], v158 offset:2048
	ds_read_b128 v[158:161], v158 offset:3072
	ds_read_b128 v[162:165], v208 offset:32768
	ds_read_b128 v[166:169], v208 offset:33792
	ds_read_b128 v[170:173], v208 offset:34816
	ds_read_b128 v[174:177], v208 offset:35840
	ds_read_b128 v[178:181], v208 offset:36864
	ds_read_b128 v[182:185], v208 offset:37888
	ds_read_b128 v[186:189], v208 offset:38912
	ds_read_b128 v[190:193], v208 offset:39936
	s_add_u32 s46, s46, 0x4000
	s_addc_u32 s47, s47, 0
	s_mov_b32 m0, s60
	s_nop 0
	global_load_lds_dwordx4 v202, s[46:47]
	s_add_u32 m0, s60, 0x2000
	s_nop 0
	global_load_lds_dwordx4 v203, s[46:47]
	s_waitcnt vmcnt(8)
	s_waitcnt lgkmcnt(0)
	s_setprio 1
	s_barrier
	v_mfma_f32_16x16x32_bf16 v[126:129], v[130:133], v[162:165], v[126:129]
	v_mfma_f32_16x16x32_bf16 v[126:129], v[134:137], v[166:169], v[126:129]
	s_waitcnt lgkmcnt(5)
	s_setprio 0
	s_setprio 1
	v_mfma_f32_16x16x32_bf16 v[118:121], v[130:133], v[170:173], v[118:121]
	v_mfma_f32_16x16x32_bf16 v[118:121], v[134:137], v[174:177], v[118:121]
	s_waitcnt lgkmcnt(3)
	s_setprio 0
	s_setprio 1
	v_mfma_f32_16x16x32_bf16 v[110:113], v[130:133], v[178:181], v[110:113]
	v_mfma_f32_16x16x32_bf16 v[110:113], v[134:137], v[182:185], v[110:113]
	s_waitcnt lgkmcnt(1)
	s_setprio 0
	s_setprio 1
	v_mfma_f32_16x16x32_bf16 v[102:105], v[130:133], v[186:189], v[102:105]
	v_mfma_f32_16x16x32_bf16 v[102:105], v[134:137], v[190:193], v[102:105]
	s_setprio 0
	s_setprio 1
	v_mfma_f32_16x16x32_bf16 v[122:125], v[138:141], v[162:165], v[122:125]
	v_mfma_f32_16x16x32_bf16 v[122:125], v[142:145], v[166:169], v[122:125]
	s_setprio 0
	s_setprio 1
	v_mfma_f32_16x16x32_bf16 v[114:117], v[138:141], v[170:173], v[114:117]
	v_mfma_f32_16x16x32_bf16 v[114:117], v[142:145], v[174:177], v[114:117]
	s_setprio 0
	s_setprio 1
	v_mfma_f32_16x16x32_bf16 v[106:109], v[138:141], v[178:181], v[106:109]
	v_mfma_f32_16x16x32_bf16 v[106:109], v[142:145], v[182:185], v[106:109]
	s_waitcnt lgkmcnt(0)
	s_setprio 0
	s_setprio 1
	v_mfma_f32_16x16x32_bf16 v[98:101], v[138:141], v[186:189], v[98:101]
	v_mfma_f32_16x16x32_bf16 v[98:101], v[142:145], v[190:193], v[98:101]
	s_setprio 0
	s_setprio 1
	v_mfma_f32_16x16x32_bf16 v[94:97], v[146:149], v[162:165], v[94:97]
	v_mfma_f32_16x16x32_bf16 v[94:97], v[150:153], v[166:169], v[94:97]
	s_setprio 0
	s_setprio 1
	v_mfma_f32_16x16x32_bf16 v[86:89], v[146:149], v[170:173], v[86:89]
	v_mfma_f32_16x16x32_bf16 v[86:89], v[150:153], v[174:177], v[86:89]
	s_setprio 0
	s_setprio 1
	v_mfma_f32_16x16x32_bf16 v[78:81], v[146:149], v[178:181], v[78:81]
	v_mfma_f32_16x16x32_bf16 v[78:81], v[150:153], v[182:185], v[78:81]
	s_setprio 0
	s_setprio 1
	v_mfma_f32_16x16x32_bf16 v[70:73], v[146:149], v[186:189], v[70:73]
	v_mfma_f32_16x16x32_bf16 v[70:73], v[150:153], v[190:193], v[70:73]
	s_setprio 0
	s_setprio 1
	v_mfma_f32_16x16x32_bf16 v[90:93], v[154:157], v[162:165], v[90:93]
	v_mfma_f32_16x16x32_bf16 v[90:93], v[158:161], v[166:169], v[90:93]
	s_setprio 0
	s_setprio 1
	v_mfma_f32_16x16x32_bf16 v[82:85], v[154:157], v[170:173], v[82:85]
	v_mfma_f32_16x16x32_bf16 v[82:85], v[158:161], v[174:177], v[82:85]
	s_setprio 0
	s_setprio 1
	v_mfma_f32_16x16x32_bf16 v[74:77], v[154:157], v[178:181], v[74:77]
	v_mfma_f32_16x16x32_bf16 v[74:77], v[158:161], v[182:185], v[74:77]
	s_setprio 2
	s_barrier
	v_mfma_f32_16x16x32_bf16 v[66:69], v[154:157], v[186:189], v[66:69]
	v_mfma_f32_16x16x32_bf16 v[66:69], v[158:161], v[190:193], v[66:69]
	s_setprio 0
	s_nop 0
	ds_read_b128 v[162:165], v208 offset:49152
	ds_read_b128 v[166:169], v208 offset:50176
	ds_read_b128 v[170:173], v208 offset:51200
	ds_read_b128 v[174:177], v208 offset:52224
	ds_read_b128 v[178:181], v208 offset:53248
	ds_read_b128 v[182:185], v208 offset:54272
	ds_read_b128 v[186:189], v208 offset:55296
	ds_read_b128 v[190:193], v208 offset:56320
	s_mov_b32 m0, s64
	s_nop 0
	global_load_lds_dwordx4 v202, s[50:51]
	s_add_u32 m0, s64, 0x2000
	s_nop 0
	global_load_lds_dwordx4 v203, s[50:51]
	s_add_u32 s42, s42, 0xc000
	s_addc_u32 s43, s43, 0
	s_mov_b32 m0, s66
	s_nop 0
	global_load_lds_dwordx4 v202, s[42:43]
	s_add_u32 m0, s66, 0x2000
	s_nop 0
	global_load_lds_dwordx4 v203, s[42:43]
	s_nop 0
	s_mov_b32 m0, s65
	s_nop 0
	global_load_lds_dwordx4 v202, s[48:49]
	s_add_u32 m0, s65, 0x2000
	s_nop 0
	global_load_lds_dwordx4 v203, s[48:49]
	s_waitcnt vmcnt(8)
	s_waitcnt lgkmcnt(0)
	s_setprio 1
	s_barrier
	v_mfma_f32_16x16x32_bf16 v[62:65], v[130:133], v[162:165], v[62:65]
	v_mfma_f32_16x16x32_bf16 v[62:65], v[134:137], v[166:169], v[62:65]
	s_waitcnt lgkmcnt(5)
	s_setprio 0
	s_setprio 1
	v_mfma_f32_16x16x32_bf16 v[54:57], v[130:133], v[170:173], v[54:57]
	v_mfma_f32_16x16x32_bf16 v[54:57], v[134:137], v[174:177], v[54:57]
	s_waitcnt lgkmcnt(3)
	s_setprio 0
	s_setprio 1
	v_mfma_f32_16x16x32_bf16 v[46:49], v[130:133], v[178:181], v[46:49]
	v_mfma_f32_16x16x32_bf16 v[46:49], v[134:137], v[182:185], v[46:49]
	s_waitcnt lgkmcnt(1)
	s_setprio 0
	s_setprio 1
	v_mfma_f32_16x16x32_bf16 v[38:41], v[130:133], v[186:189], v[38:41]
	v_mfma_f32_16x16x32_bf16 v[38:41], v[134:137], v[190:193], v[38:41]
	s_setprio 0
	s_setprio 1
	v_mfma_f32_16x16x32_bf16 v[58:61], v[138:141], v[162:165], v[58:61]
	v_mfma_f32_16x16x32_bf16 v[58:61], v[142:145], v[166:169], v[58:61]
	s_setprio 0
	s_setprio 1
	v_mfma_f32_16x16x32_bf16 v[50:53], v[138:141], v[170:173], v[50:53]
	v_mfma_f32_16x16x32_bf16 v[50:53], v[142:145], v[174:177], v[50:53]
	s_setprio 0
	s_setprio 1
	v_mfma_f32_16x16x32_bf16 v[42:45], v[138:141], v[178:181], v[42:45]
	v_mfma_f32_16x16x32_bf16 v[42:45], v[142:145], v[182:185], v[42:45]
	s_waitcnt lgkmcnt(0)
	s_setprio 0
	s_setprio 1
	v_mfma_f32_16x16x32_bf16 v[34:37], v[138:141], v[186:189], v[34:37]
	v_mfma_f32_16x16x32_bf16 v[34:37], v[142:145], v[190:193], v[34:37]
	s_setprio 0
	s_setprio 1
	v_mfma_f32_16x16x32_bf16 v[30:33], v[146:149], v[162:165], v[30:33]
	v_mfma_f32_16x16x32_bf16 v[30:33], v[150:153], v[166:169], v[30:33]
	s_setprio 0
	s_setprio 1
	v_mfma_f32_16x16x32_bf16 v[22:25], v[146:149], v[170:173], v[22:25]
	v_mfma_f32_16x16x32_bf16 v[22:25], v[150:153], v[174:177], v[22:25]
	s_setprio 0
	s_setprio 1
	v_mfma_f32_16x16x32_bf16 v[14:17], v[146:149], v[178:181], v[14:17]
	v_mfma_f32_16x16x32_bf16 v[14:17], v[150:153], v[182:185], v[14:17]
	s_setprio 0
	s_setprio 1
	v_mfma_f32_16x16x32_bf16 v[6:9], v[146:149], v[186:189], v[6:9]
	v_mfma_f32_16x16x32_bf16 v[6:9], v[150:153], v[190:193], v[6:9]
	s_setprio 0
	s_setprio 1
	v_mfma_f32_16x16x32_bf16 v[26:29], v[154:157], v[162:165], v[26:29]
	v_mfma_f32_16x16x32_bf16 v[26:29], v[158:161], v[166:169], v[26:29]
	s_setprio 0
	s_setprio 1
	v_mfma_f32_16x16x32_bf16 v[18:21], v[154:157], v[170:173], v[18:21]
	v_mfma_f32_16x16x32_bf16 v[18:21], v[158:161], v[174:177], v[18:21]
	s_setprio 0
	s_setprio 1
	v_mfma_f32_16x16x32_bf16 v[10:13], v[154:157], v[178:181], v[10:13]
	v_mfma_f32_16x16x32_bf16 v[10:13], v[158:161], v[182:185], v[10:13]
	s_setprio 2
	s_barrier
	v_mfma_f32_16x16x32_bf16 v[2:5], v[154:157], v[186:189], v[2:5]
	v_mfma_f32_16x16x32_bf16 v[2:5], v[158:161], v[190:193], v[2:5]
	s_setprio 0
	s_nop 0
	s_add_i32 s13, s77, 2
	s_cmp_gt_u32 s77, 5
	s_cbranch_scc1 .LBB0_1340
	s_mov_b32 s77, s13
	s_branch .LBB0_1317

.LBB0_1374:
	s_or_b64 exec, exec, s[40:41]
	s_add_u32 s76, s16, s6
	ds_read_b128 v[132:135], v168
	ds_read_b128 v[136:139], v168 offset:1024
	ds_read_b128 v[140:143], v168 offset:2048
	ds_read_b128 v[144:147], v168 offset:3072
	ds_read_b128 v[148:151], v169
	ds_read_b128 v[158:161], v169 offset:1024
	ds_read_b128 v[162:165], v169 offset:2048
	ds_read_b128 v[174:177], v169 offset:3072
	s_addc_u32 s77, s17, s7
	s_add_u32 s40, s76, 0x20000
	s_addc_u32 s41, s77, 0
	s_add_u32 s42, s71, s6
	s_addc_u32 s43, s72, s7
	s_cmp_eq_u32 s6, 0x20000
	s_cselect_b32 s48, s73, s40
	s_cselect_b32 s49, s27, s41
	s_cselect_b32 s41, s25, s43
	s_cselect_b32 s40, s74, s42
	s_add_u32 s42, s48, 0x8000
	s_addc_u32 s43, s49, 0
	s_add_u32 s46, s40, 0x8000
	s_addc_u32 s47, s41, 0
	ds_read_b128 v[178:181], v170
	ds_read_b128 v[182:185], v170 offset:1024
	ds_read_b128 v[186:189], v170 offset:2048
	ds_read_b128 v[190:193], v170 offset:3072
	ds_read_b128 v[198:201], v170 offset:4096
	ds_read_b128 v[204:207], v170 offset:5120
	ds_read_b128 v[212:215], v170 offset:6144
	ds_read_b128 v[216:219], v170 offset:7168
	s_add_u32 s76, s76, 0x1c000
	s_addc_u32 s77, s77, 0
	s_mov_b32 m0, s63
	s_nop 0
	global_load_lds_dwordx4 v202, s[76:77]
	s_add_u32 m0, s63, 0x2000
	s_nop 0
	global_load_lds_dwordx4 v203, s[76:77]
	s_waitcnt vmcnt(8)
	s_waitcnt lgkmcnt(0)
	s_setprio 1
	s_barrier
	v_mfma_f32_16x16x32_bf16 v[126:129], v[132:135], v[178:181], v[126:129]
	v_mfma_f32_16x16x32_bf16 v[126:129], v[136:139], v[182:185], v[126:129]
	s_waitcnt lgkmcnt(5)
	s_setprio 0
	s_setprio 1
	v_mfma_f32_16x16x32_bf16 v[110:113], v[132:135], v[186:189], v[110:113]
	v_mfma_f32_16x16x32_bf16 v[110:113], v[136:139], v[190:193], v[110:113]
	s_waitcnt lgkmcnt(3)
	s_setprio 0
	s_setprio 1
	v_mfma_f32_16x16x32_bf16 v[94:97], v[132:135], v[198:201], v[94:97]
	v_mfma_f32_16x16x32_bf16 v[94:97], v[136:139], v[204:207], v[94:97]
	s_waitcnt lgkmcnt(1)
	s_setprio 0
	s_setprio 1
	v_mfma_f32_16x16x32_bf16 v[78:81], v[132:135], v[212:215], v[78:81]
	v_mfma_f32_16x16x32_bf16 v[78:81], v[136:139], v[216:219], v[78:81]
	s_setprio 0
	s_setprio 1
	v_mfma_f32_16x16x32_bf16 v[122:125], v[140:143], v[178:181], v[122:125]
	v_mfma_f32_16x16x32_bf16 v[122:125], v[144:147], v[182:185], v[122:125]
	s_setprio 0
	s_setprio 1
	v_mfma_f32_16x16x32_bf16 v[106:109], v[140:143], v[186:189], v[106:109]
	v_mfma_f32_16x16x32_bf16 v[106:109], v[144:147], v[190:193], v[106:109]
	s_setprio 0
	s_setprio 1
	v_mfma_f32_16x16x32_bf16 v[90:93], v[140:143], v[198:201], v[90:93]
	v_mfma_f32_16x16x32_bf16 v[90:93], v[144:147], v[204:207], v[90:93]
	s_waitcnt lgkmcnt(0)
	s_setprio 0
	s_setprio 1
	v_mfma_f32_16x16x32_bf16 v[74:77], v[140:143], v[212:215], v[74:77]
	v_mfma_f32_16x16x32_bf16 v[74:77], v[144:147], v[216:219], v[74:77]
	s_setprio 0
	s_setprio 1
	v_mfma_f32_16x16x32_bf16 v[118:121], v[148:151], v[178:181], v[118:121]
	v_mfma_f32_16x16x32_bf16 v[118:121], v[158:161], v[182:185], v[118:121]
	s_setprio 0
	s_setprio 1
	v_mfma_f32_16x16x32_bf16 v[102:105], v[148:151], v[186:189], v[102:105]
	v_mfma_f32_16x16x32_bf16 v[102:105], v[158:161], v[190:193], v[102:105]
	s_setprio 0
	s_setprio 1
	v_mfma_f32_16x16x32_bf16 v[86:89], v[148:151], v[198:201], v[86:89]
	v_mfma_f32_16x16x32_bf16 v[86:89], v[158:161], v[204:207], v[86:89]
	s_setprio 0
	s_setprio 1
	v_mfma_f32_16x16x32_bf16 v[70:73], v[148:151], v[212:215], v[70:73]
	v_mfma_f32_16x16x32_bf16 v[70:73], v[158:161], v[216:219], v[70:73]
	s_setprio 0
	s_setprio 1
	v_mfma_f32_16x16x32_bf16 v[114:117], v[162:165], v[178:181], v[114:117]
	v_mfma_f32_16x16x32_bf16 v[114:117], v[174:177], v[182:185], v[114:117]
	s_setprio 0
	s_setprio 1
	v_mfma_f32_16x16x32_bf16 v[98:101], v[162:165], v[186:189], v[98:101]
	v_mfma_f32_16x16x32_bf16 v[98:101], v[174:177], v[190:193], v[98:101]
	s_setprio 0
	s_setprio 1
	v_mfma_f32_16x16x32_bf16 v[82:85], v[162:165], v[198:201], v[82:85]
	v_mfma_f32_16x16x32_bf16 v[82:85], v[174:177], v[204:207], v[82:85]
	s_setprio 2
	s_barrier
	v_mfma_f32_16x16x32_bf16 v[66:69], v[162:165], v[212:215], v[66:69]
	v_mfma_f32_16x16x32_bf16 v[66:69], v[174:177], v[216:219], v[66:69]
	s_setprio 0
	s_nop 0
	ds_read_b128 v[178:181], v170 offset:16384
	ds_read_b128 v[182:185], v170 offset:17408
	ds_read_b128 v[186:189], v170 offset:18432
	ds_read_b128 v[190:193], v170 offset:19456
	ds_read_b128 v[198:201], v170 offset:20480
	ds_read_b128 v[204:207], v170 offset:21504
	ds_read_b128 v[212:215], v170 offset:22528
	ds_read_b128 v[216:219], v170 offset:23552
	s_mov_b32 m0, s13
	s_nop 0
	global_load_lds_dwordx4 v202, s[40:41]
	s_add_u32 m0, s13, 0x2000
	s_nop 0
	global_load_lds_dwordx4 v203, s[40:41]
	s_add_u32 s76, s40, 0x4000
	s_addc_u32 s77, s41, 0
	s_mov_b32 m0, s55
	s_nop 0
	global_load_lds_dwordx4 v202, s[76:77]
	s_add_u32 m0, s55, 0x2000
	s_nop 0
	global_load_lds_dwordx4 v203, s[76:77]
	s_nop 0
	s_mov_b32 m0, s54
	s_nop 0
	global_load_lds_dwordx4 v202, s[48:49]
	s_add_u32 m0, s54, 0x2000
	s_nop 0
	global_load_lds_dwordx4 v203, s[48:49]
	s_waitcnt vmcnt(8)
	s_waitcnt lgkmcnt(0)
	s_setprio 1
	s_barrier
	v_mfma_f32_16x16x32_bf16 v[62:65], v[132:135], v[178:181], v[62:65]
	v_mfma_f32_16x16x32_bf16 v[62:65], v[136:139], v[182:185], v[62:65]
	s_waitcnt lgkmcnt(5)
	s_setprio 0
	s_setprio 1
	v_mfma_f32_16x16x32_bf16 v[46:49], v[132:135], v[186:189], v[46:49]
	v_mfma_f32_16x16x32_bf16 v[46:49], v[136:139], v[190:193], v[46:49]
	s_waitcnt lgkmcnt(3)
	s_setprio 0
	s_setprio 1
	v_mfma_f32_16x16x32_bf16 v[30:33], v[132:135], v[198:201], v[30:33]
	v_mfma_f32_16x16x32_bf16 v[30:33], v[136:139], v[204:207], v[30:33]
	s_waitcnt lgkmcnt(1)
	s_setprio 0
	s_setprio 1
	v_mfma_f32_16x16x32_bf16 v[14:17], v[132:135], v[212:215], v[14:17]
	v_mfma_f32_16x16x32_bf16 v[14:17], v[136:139], v[216:219], v[14:17]
	s_setprio 0
	s_setprio 1
	v_mfma_f32_16x16x32_bf16 v[58:61], v[140:143], v[178:181], v[58:61]
	v_mfma_f32_16x16x32_bf16 v[58:61], v[144:147], v[182:185], v[58:61]
	s_setprio 0
	s_setprio 1
	v_mfma_f32_16x16x32_bf16 v[42:45], v[140:143], v[186:189], v[42:45]
	v_mfma_f32_16x16x32_bf16 v[42:45], v[144:147], v[190:193], v[42:45]
	s_setprio 0
	s_setprio 1
	v_mfma_f32_16x16x32_bf16 v[26:29], v[140:143], v[198:201], v[26:29]
	v_mfma_f32_16x16x32_bf16 v[26:29], v[144:147], v[204:207], v[26:29]
	s_waitcnt lgkmcnt(0)
	s_setprio 0
	s_setprio 1
	v_mfma_f32_16x16x32_bf16 v[10:13], v[140:143], v[212:215], v[10:13]
	v_mfma_f32_16x16x32_bf16 v[10:13], v[144:147], v[216:219], v[10:13]
	s_setprio 0
	s_setprio 1
	v_mfma_f32_16x16x32_bf16 v[54:57], v[148:151], v[178:181], v[54:57]
	v_mfma_f32_16x16x32_bf16 v[54:57], v[158:161], v[182:185], v[54:57]
	s_setprio 0
	s_setprio 1
	v_mfma_f32_16x16x32_bf16 v[38:41], v[148:151], v[186:189], v[38:41]
	v_mfma_f32_16x16x32_bf16 v[38:41], v[158:161], v[190:193], v[38:41]
	s_setprio 0
	s_setprio 1
	v_mfma_f32_16x16x32_bf16 v[22:25], v[148:151], v[198:201], v[22:25]
	v_mfma_f32_16x16x32_bf16 v[22:25], v[158:161], v[204:207], v[22:25]
	s_setprio 0
	s_setprio 1
	v_mfma_f32_16x16x32_bf16 v[6:9], v[148:151], v[212:215], v[6:9]
	v_mfma_f32_16x16x32_bf16 v[6:9], v[158:161], v[216:219], v[6:9]
	s_setprio 0
	s_setprio 1
	v_mfma_f32_16x16x32_bf16 v[50:53], v[162:165], v[178:181], v[50:53]
	v_mfma_f32_16x16x32_bf16 v[50:53], v[174:177], v[182:185], v[50:53]
	s_setprio 0
	s_setprio 1
	v_mfma_f32_16x16x32_bf16 v[34:37], v[162:165], v[186:189], v[34:37]
	v_mfma_f32_16x16x32_bf16 v[34:37], v[174:177], v[190:193], v[34:37]
	s_setprio 0
	s_setprio 1
	v_mfma_f32_16x16x32_bf16 v[18:21], v[162:165], v[198:201], v[18:21]
	v_mfma_f32_16x16x32_bf16 v[18:21], v[174:177], v[204:207], v[18:21]
	s_setprio 2
	s_barrier
	v_mfma_f32_16x16x32_bf16 v[2:5], v[162:165], v[212:215], v[2:5]
	v_mfma_f32_16x16x32_bf16 v[2:5], v[174:177], v[216:219], v[2:5]
	s_setprio 0
	s_nop 0
	ds_read_b128 v[132:135], v171
	ds_read_b128 v[136:139], v171 offset:1024
	ds_read_b128 v[140:143], v171 offset:2048
	ds_read_b128 v[144:147], v171 offset:3072
	ds_read_b128 v[148:151], v172
	ds_read_b128 v[158:161], v172 offset:1024
	ds_read_b128 v[162:165], v172 offset:2048
	ds_read_b128 v[174:177], v172 offset:3072
	ds_read_b128 v[178:181], v170 offset:32768
	ds_read_b128 v[182:185], v170 offset:33792
	ds_read_b128 v[186:189], v170 offset:34816
	ds_read_b128 v[190:193], v170 offset:35840
	ds_read_b128 v[198:201], v170 offset:36864
	ds_read_b128 v[204:207], v170 offset:37888
	ds_read_b128 v[212:215], v170 offset:38912
	ds_read_b128 v[216:219], v170 offset:39936
	s_add_u32 s48, s48, 0x4000
	s_addc_u32 s49, s49, 0
	s_mov_b32 m0, s56
	s_nop 0
	global_load_lds_dwordx4 v202, s[48:49]
	s_add_u32 m0, s56, 0x2000
	s_nop 0
	global_load_lds_dwordx4 v203, s[48:49]
	s_waitcnt vmcnt(8)
	s_waitcnt lgkmcnt(0)
	s_setprio 1
	s_barrier
	v_mfma_f32_16x16x32_bf16 v[126:129], v[132:135], v[178:181], v[126:129]
	v_mfma_f32_16x16x32_bf16 v[126:129], v[136:139], v[182:185], v[126:129]
	s_waitcnt lgkmcnt(5)
	s_setprio 0
	s_setprio 1
	v_mfma_f32_16x16x32_bf16 v[110:113], v[132:135], v[186:189], v[110:113]
	v_mfma_f32_16x16x32_bf16 v[110:113], v[136:139], v[190:193], v[110:113]
	s_waitcnt lgkmcnt(3)
	s_setprio 0
	s_setprio 1
	v_mfma_f32_16x16x32_bf16 v[94:97], v[132:135], v[198:201], v[94:97]
	v_mfma_f32_16x16x32_bf16 v[94:97], v[136:139], v[204:207], v[94:97]
	s_waitcnt lgkmcnt(1)
	s_setprio 0
	s_setprio 1
	v_mfma_f32_16x16x32_bf16 v[78:81], v[132:135], v[212:215], v[78:81]
	v_mfma_f32_16x16x32_bf16 v[78:81], v[136:139], v[216:219], v[78:81]
	s_setprio 0
	s_setprio 1
	v_mfma_f32_16x16x32_bf16 v[122:125], v[140:143], v[178:181], v[122:125]
	v_mfma_f32_16x16x32_bf16 v[122:125], v[144:147], v[182:185], v[122:125]
	s_setprio 0
	s_setprio 1
	v_mfma_f32_16x16x32_bf16 v[106:109], v[140:143], v[186:189], v[106:109]
	v_mfma_f32_16x16x32_bf16 v[106:109], v[144:147], v[190:193], v[106:109]
	s_setprio 0
	s_setprio 1
	v_mfma_f32_16x16x32_bf16 v[90:93], v[140:143], v[198:201], v[90:93]
	v_mfma_f32_16x16x32_bf16 v[90:93], v[144:147], v[204:207], v[90:93]
	s_waitcnt lgkmcnt(0)
	s_setprio 0
	s_setprio 1
	v_mfma_f32_16x16x32_bf16 v[74:77], v[140:143], v[212:215], v[74:77]
	v_mfma_f32_16x16x32_bf16 v[74:77], v[144:147], v[216:219], v[74:77]
	s_setprio 0
	s_setprio 1
	v_mfma_f32_16x16x32_bf16 v[118:121], v[148:151], v[178:181], v[118:121]
	v_mfma_f32_16x16x32_bf16 v[118:121], v[158:161], v[182:185], v[118:121]
	s_setprio 0
	s_setprio 1
	v_mfma_f32_16x16x32_bf16 v[102:105], v[148:151], v[186:189], v[102:105]
	v_mfma_f32_16x16x32_bf16 v[102:105], v[158:161], v[190:193], v[102:105]
	s_setprio 0
	s_setprio 1
	v_mfma_f32_16x16x32_bf16 v[86:89], v[148:151], v[198:201], v[86:89]
	v_mfma_f32_16x16x32_bf16 v[86:89], v[158:161], v[204:207], v[86:89]
	s_setprio 0
	s_setprio 1
	v_mfma_f32_16x16x32_bf16 v[70:73], v[148:151], v[212:215], v[70:73]
	v_mfma_f32_16x16x32_bf16 v[70:73], v[158:161], v[216:219], v[70:73]
	s_setprio 0
	s_setprio 1
	v_mfma_f32_16x16x32_bf16 v[114:117], v[162:165], v[178:181], v[114:117]
	v_mfma_f32_16x16x32_bf16 v[114:117], v[174:177], v[182:185], v[114:117]
	s_setprio 0
	s_setprio 1
	v_mfma_f32_16x16x32_bf16 v[98:101], v[162:165], v[186:189], v[98:101]
	v_mfma_f32_16x16x32_bf16 v[98:101], v[174:177], v[190:193], v[98:101]
	s_setprio 0
	s_setprio 1
	v_mfma_f32_16x16x32_bf16 v[82:85], v[162:165], v[198:201], v[82:85]
	v_mfma_f32_16x16x32_bf16 v[82:85], v[174:177], v[204:207], v[82:85]
	s_setprio 2
	s_barrier
	v_mfma_f32_16x16x32_bf16 v[66:69], v[162:165], v[212:215], v[66:69]
	v_mfma_f32_16x16x32_bf16 v[66:69], v[174:177], v[216:219], v[66:69]
	s_setprio 0
	s_nop 0
	ds_read_b128 v[178:181], v170 offset:49152
	ds_read_b128 v[182:185], v170 offset:50176
	ds_read_b128 v[186:189], v170 offset:51200
	ds_read_b128 v[190:193], v170 offset:52224
	ds_read_b128 v[198:201], v170 offset:53248
	ds_read_b128 v[204:207], v170 offset:54272
	ds_read_b128 v[212:215], v170 offset:55296
	ds_read_b128 v[216:219], v170 offset:56320
	s_mov_b32 m0, s59
	s_nop 0
	global_load_lds_dwordx4 v202, s[46:47]
	s_add_u32 m0, s59, 0x2000
	s_nop 0
	global_load_lds_dwordx4 v203, s[46:47]
	s_add_u32 s40, s40, 0xc000
	s_addc_u32 s41, s41, 0
	s_mov_b32 m0, s62
	s_nop 0
	global_load_lds_dwordx4 v202, s[40:41]
	s_add_u32 m0, s62, 0x2000
	s_nop 0
	global_load_lds_dwordx4 v203, s[40:41]
	s_nop 0
	s_mov_b32 m0, s61
	s_nop 0
	global_load_lds_dwordx4 v202, s[42:43]
	s_add_u32 m0, s61, 0x2000
	s_nop 0
	global_load_lds_dwordx4 v203, s[42:43]
	s_waitcnt vmcnt(8)
	s_waitcnt lgkmcnt(0)
	s_setprio 1
	s_barrier
	v_mfma_f32_16x16x32_bf16 v[62:65], v[132:135], v[178:181], v[62:65]
	v_mfma_f32_16x16x32_bf16 v[62:65], v[136:139], v[182:185], v[62:65]
	s_waitcnt lgkmcnt(5)
	s_setprio 0
	s_setprio 1
	v_mfma_f32_16x16x32_bf16 v[46:49], v[132:135], v[186:189], v[46:49]
	v_mfma_f32_16x16x32_bf16 v[46:49], v[136:139], v[190:193], v[46:49]
	s_waitcnt lgkmcnt(3)
	s_setprio 0
	s_setprio 1
	v_mfma_f32_16x16x32_bf16 v[30:33], v[132:135], v[198:201], v[30:33]
	v_mfma_f32_16x16x32_bf16 v[30:33], v[136:139], v[204:207], v[30:33]
	s_waitcnt lgkmcnt(1)
	s_setprio 0
	s_setprio 1
	v_mfma_f32_16x16x32_bf16 v[14:17], v[132:135], v[212:215], v[14:17]
	v_mfma_f32_16x16x32_bf16 v[14:17], v[136:139], v[216:219], v[14:17]
	s_setprio 0
	s_setprio 1
	v_mfma_f32_16x16x32_bf16 v[58:61], v[140:143], v[178:181], v[58:61]
	v_mfma_f32_16x16x32_bf16 v[58:61], v[144:147], v[182:185], v[58:61]
	s_setprio 0
	s_setprio 1
	v_mfma_f32_16x16x32_bf16 v[42:45], v[140:143], v[186:189], v[42:45]
	v_mfma_f32_16x16x32_bf16 v[42:45], v[144:147], v[190:193], v[42:45]
	s_setprio 0
	s_setprio 1
	v_mfma_f32_16x16x32_bf16 v[26:29], v[140:143], v[198:201], v[26:29]
	v_mfma_f32_16x16x32_bf16 v[26:29], v[144:147], v[204:207], v[26:29]
	s_waitcnt lgkmcnt(0)
	s_setprio 0
	s_setprio 1
	v_mfma_f32_16x16x32_bf16 v[10:13], v[140:143], v[212:215], v[10:13]
	v_mfma_f32_16x16x32_bf16 v[10:13], v[144:147], v[216:219], v[10:13]
	s_setprio 0
	s_setprio 1
	v_mfma_f32_16x16x32_bf16 v[54:57], v[148:151], v[178:181], v[54:57]
	v_mfma_f32_16x16x32_bf16 v[54:57], v[158:161], v[182:185], v[54:57]
	s_setprio 0
	s_setprio 1
	v_mfma_f32_16x16x32_bf16 v[38:41], v[148:151], v[186:189], v[38:41]
	v_mfma_f32_16x16x32_bf16 v[38:41], v[158:161], v[190:193], v[38:41]
	s_setprio 0
	s_setprio 1
	v_mfma_f32_16x16x32_bf16 v[22:25], v[148:151], v[198:201], v[22:25]
	v_mfma_f32_16x16x32_bf16 v[22:25], v[158:161], v[204:207], v[22:25]
	s_setprio 0
	s_setprio 1
	v_mfma_f32_16x16x32_bf16 v[6:9], v[148:151], v[212:215], v[6:9]
	v_mfma_f32_16x16x32_bf16 v[6:9], v[158:161], v[216:219], v[6:9]
	s_setprio 0
	s_setprio 1
	v_mfma_f32_16x16x32_bf16 v[50:53], v[162:165], v[178:181], v[50:53]
	v_mfma_f32_16x16x32_bf16 v[50:53], v[174:177], v[182:185], v[50:53]
	s_setprio 0
	s_setprio 1
	v_mfma_f32_16x16x32_bf16 v[34:37], v[162:165], v[186:189], v[34:37]
	v_mfma_f32_16x16x32_bf16 v[34:37], v[174:177], v[190:193], v[34:37]
	s_setprio 0
	s_setprio 1
	v_mfma_f32_16x16x32_bf16 v[18:21], v[162:165], v[198:201], v[18:21]
	v_mfma_f32_16x16x32_bf16 v[18:21], v[174:177], v[204:207], v[18:21]
	s_setprio 2
	s_barrier
	v_mfma_f32_16x16x32_bf16 v[2:5], v[162:165], v[212:215], v[2:5]
	v_mfma_f32_16x16x32_bf16 v[2:5], v[174:177], v[216:219], v[2:5]
	s_setprio 0
	s_nop 0
	s_add_i32 s75, s75, 2
	s_add_u32 s6, s6, 0x10000
	s_addc_u32 s7, s7, 0
	s_cmp_gt_u32 s75, 5
	s_cbranch_scc1 .LBB0_1376
	v_mov_b32_e32 v131, v130
	s_branch .LBB0_1372

.LBB0_1519:
	s_add_i32 s26, s58, 2
	s_lshl_b64 s[54:55], s[26:27], 15
	s_add_u32 s17, s18, s54
	s_addc_u32 s59, s19, s55
	s_and_b64 s[50:51], s[12:13], exec
	s_cselect_b32 s51, s59, s41
	s_cselect_b32 s50, s17, s56
	s_add_u32 s17, s20, s54
	s_waitcnt vmcnt(8)
	s_addc_u32 s54, s21, s55
	s_waitcnt lgkmcnt(0)
	s_and_b64 s[12:13], s[12:13], exec
	s_cselect_b32 s13, s54, s39
	s_cselect_b32 s12, s17, s57
	s_setprio 1
	s_barrier
	v_mfma_f32_16x16x32_bf16 v[126:129], v[146:149], v[186:189], v[126:129]
	v_mfma_f32_16x16x32_bf16 v[126:129], v[150:153], v[190:193], v[126:129]
	s_waitcnt lgkmcnt(5)
	s_setprio 0
	s_setprio 1
	v_mfma_f32_16x16x32_bf16 v[118:121], v[146:149], v[178:181], v[118:121]
	v_mfma_f32_16x16x32_bf16 v[118:121], v[150:153], v[182:185], v[118:121]
	s_waitcnt lgkmcnt(3)
	s_setprio 0
	s_setprio 1
	v_mfma_f32_16x16x32_bf16 v[110:113], v[146:149], v[170:173], v[110:113]
	v_mfma_f32_16x16x32_bf16 v[110:113], v[150:153], v[174:177], v[110:113]
	s_waitcnt lgkmcnt(1)
	s_setprio 0
	s_setprio 1
	v_mfma_f32_16x16x32_bf16 v[102:105], v[146:149], v[162:165], v[102:105]
	v_mfma_f32_16x16x32_bf16 v[102:105], v[150:153], v[166:169], v[102:105]
	s_setprio 0
	s_setprio 1
	v_mfma_f32_16x16x32_bf16 v[122:125], v[154:157], v[186:189], v[122:125]
	v_mfma_f32_16x16x32_bf16 v[122:125], v[158:161], v[190:193], v[122:125]
	s_setprio 0
	s_setprio 1
	v_mfma_f32_16x16x32_bf16 v[114:117], v[154:157], v[178:181], v[114:117]
	v_mfma_f32_16x16x32_bf16 v[114:117], v[158:161], v[182:185], v[114:117]
	s_setprio 0
	s_setprio 1
	v_mfma_f32_16x16x32_bf16 v[106:109], v[154:157], v[170:173], v[106:109]
	v_mfma_f32_16x16x32_bf16 v[106:109], v[158:161], v[174:177], v[106:109]
	s_waitcnt lgkmcnt(0)
	s_setprio 0
	s_setprio 1
	v_mfma_f32_16x16x32_bf16 v[98:101], v[154:157], v[162:165], v[98:101]
	v_mfma_f32_16x16x32_bf16 v[98:101], v[158:161], v[166:169], v[98:101]
	s_setprio 0
	s_setprio 1
	v_mfma_f32_16x16x32_bf16 v[94:97], v[130:133], v[186:189], v[94:97]
	v_mfma_f32_16x16x32_bf16 v[94:97], v[134:137], v[190:193], v[94:97]
	s_setprio 0
	s_setprio 1
	v_mfma_f32_16x16x32_bf16 v[86:89], v[130:133], v[178:181], v[86:89]
	v_mfma_f32_16x16x32_bf16 v[86:89], v[134:137], v[182:185], v[86:89]
	s_setprio 0
	s_setprio 1
	v_mfma_f32_16x16x32_bf16 v[78:81], v[130:133], v[170:173], v[78:81]
	v_mfma_f32_16x16x32_bf16 v[78:81], v[134:137], v[174:177], v[78:81]
	s_setprio 0
	s_setprio 1
	v_mfma_f32_16x16x32_bf16 v[70:73], v[130:133], v[162:165], v[70:73]
	v_mfma_f32_16x16x32_bf16 v[70:73], v[134:137], v[166:169], v[70:73]
	s_setprio 0
	s_setprio 1
	v_mfma_f32_16x16x32_bf16 v[90:93], v[138:141], v[186:189], v[90:93]
	v_mfma_f32_16x16x32_bf16 v[90:93], v[142:145], v[190:193], v[90:93]
	s_setprio 0
	s_setprio 1
	v_mfma_f32_16x16x32_bf16 v[82:85], v[138:141], v[178:181], v[82:85]
	v_mfma_f32_16x16x32_bf16 v[82:85], v[142:145], v[182:185], v[82:85]
	s_setprio 0
	s_setprio 1
	v_mfma_f32_16x16x32_bf16 v[74:77], v[138:141], v[170:173], v[74:77]
	v_mfma_f32_16x16x32_bf16 v[74:77], v[142:145], v[174:177], v[74:77]
	s_setprio 2
	s_barrier
	v_mfma_f32_16x16x32_bf16 v[66:69], v[138:141], v[162:165], v[66:69]
	v_mfma_f32_16x16x32_bf16 v[66:69], v[142:145], v[166:169], v[66:69]
	s_setprio 0
	s_nop 0
	ds_read_b128 v[186:189], v217 offset:16384
	ds_read_b128 v[190:193], v217 offset:17408
	ds_read_b128 v[178:181], v217 offset:18432
	ds_read_b128 v[182:185], v217 offset:19456
	ds_read_b128 v[170:173], v217 offset:20480
	ds_read_b128 v[174:177], v217 offset:21504
	ds_read_b128 v[162:165], v217 offset:22528
	ds_read_b128 v[166:169], v217 offset:23552
	s_mov_b32 m0, s66
	s_nop 0
	global_load_lds_dwordx4 v195, s[12:13]
	s_add_u32 m0, s66, 0x2000
	s_nop 0
	global_load_lds_dwordx4 v212, s[12:13]
	s_add_u32 s54, s12, 0x4000
	s_addc_u32 s55, s13, 0
	s_mov_b32 m0, s67
	s_nop 0
	global_load_lds_dwordx4 v195, s[54:55]
	s_add_u32 m0, s67, 0x2000
	s_nop 0
	global_load_lds_dwordx4 v212, s[54:55]
	s_andn2_b64 vcc, exec, s[52:53]
	s_mov_b32 m0, s15
	s_nop 0
	global_load_lds_dwordx4 v195, s[50:51]
	s_add_u32 m0, s15, 0x2000
	s_nop 0
	global_load_lds_dwordx4 v212, s[50:51]
	s_cbranch_vccnz .LBB0_1521
	v_mov_b32_e32 v2, 0
	v_mov_b32_e32 v3, v2
	v_mov_b32_e32 v4, v2
	v_mov_b32_e32 v5, v2
	v_mov_b32_e32 v6, v2
	v_mov_b32_e32 v7, v2
	v_mov_b32_e32 v8, v2
	v_mov_b32_e32 v9, v2
	v_mov_b32_e32 v10, v2
	v_mov_b32_e32 v11, v2
	v_mov_b32_e32 v12, v2
	v_mov_b32_e32 v13, v2
	v_mov_b32_e32 v14, v2
	v_mov_b32_e32 v15, v2
	v_mov_b32_e32 v16, v2
	v_mov_b32_e32 v17, v2
	v_mov_b32_e32 v18, v2
	v_mov_b32_e32 v19, v2
	v_mov_b32_e32 v20, v2
	v_mov_b32_e32 v21, v2
	v_mov_b32_e32 v22, v2
	v_mov_b32_e32 v23, v2
	v_mov_b32_e32 v24, v2
	v_mov_b32_e32 v25, v2
	v_mov_b32_e32 v26, v2
	v_mov_b32_e32 v27, v2
	v_mov_b32_e32 v28, v2
	v_mov_b32_e32 v29, v2
	v_mov_b32_e32 v30, v2
	v_mov_b32_e32 v31, v2
	v_mov_b32_e32 v32, v2
	v_mov_b32_e32 v33, v2
	v_mov_b32_e32 v34, v2
	v_mov_b32_e32 v35, v2
	v_mov_b32_e32 v36, v2
	v_mov_b32_e32 v37, v2
	v_mov_b32_e32 v38, v2
	v_mov_b32_e32 v39, v2
	v_mov_b32_e32 v40, v2
	v_mov_b32_e32 v41, v2
	v_mov_b32_e32 v42, v2
	v_mov_b32_e32 v43, v2
	v_mov_b32_e32 v44, v2
	v_mov_b32_e32 v45, v2
	v_mov_b32_e32 v46, v2
	v_mov_b32_e32 v47, v2
	v_mov_b32_e32 v48, v2
	v_mov_b32_e32 v49, v2
	v_mov_b32_e32 v50, v2
	v_mov_b32_e32 v51, v2
	v_mov_b32_e32 v52, v2
	v_mov_b32_e32 v53, v2
	v_mov_b32_e32 v54, v2
	v_mov_b32_e32 v55, v2
	v_mov_b32_e32 v56, v2
	v_mov_b32_e32 v57, v2
	v_mov_b32_e32 v58, v2
	v_mov_b32_e32 v59, v2
	v_mov_b32_e32 v60, v2
	v_mov_b32_e32 v61, v2
	v_mov_b32_e32 v62, v2
	v_mov_b32_e32 v63, v2
	v_mov_b32_e32 v64, v2
	v_mov_b32_e32 v65, v2
.LBB0_1521:
	s_waitcnt vmcnt(8)
	s_add_u32 s52, s50, 0x8000
	s_waitcnt lgkmcnt(0)
	s_addc_u32 s53, s51, 0
	s_add_u32 s54, s12, 0x8000
	s_addc_u32 s55, s13, 0
	s_setprio 1
	s_barrier
	v_mfma_f32_16x16x32_bf16 v[62:65], v[146:149], v[186:189], v[62:65]
	v_mfma_f32_16x16x32_bf16 v[62:65], v[150:153], v[190:193], v[62:65]
	s_waitcnt lgkmcnt(5)
	s_setprio 0
	s_setprio 1
	v_mfma_f32_16x16x32_bf16 v[54:57], v[146:149], v[178:181], v[54:57]
	v_mfma_f32_16x16x32_bf16 v[54:57], v[150:153], v[182:185], v[54:57]
	s_waitcnt lgkmcnt(3)
	s_setprio 0
	s_setprio 1
	v_mfma_f32_16x16x32_bf16 v[46:49], v[146:149], v[170:173], v[46:49]
	v_mfma_f32_16x16x32_bf16 v[46:49], v[150:153], v[174:177], v[46:49]
	s_waitcnt lgkmcnt(1)
	s_setprio 0
	s_setprio 1
	v_mfma_f32_16x16x32_bf16 v[38:41], v[146:149], v[162:165], v[38:41]
	v_mfma_f32_16x16x32_bf16 v[38:41], v[150:153], v[166:169], v[38:41]
	s_setprio 0
	s_setprio 1
	v_mfma_f32_16x16x32_bf16 v[58:61], v[154:157], v[186:189], v[58:61]
	v_mfma_f32_16x16x32_bf16 v[58:61], v[158:161], v[190:193], v[58:61]
	s_setprio 0
	s_setprio 1
	v_mfma_f32_16x16x32_bf16 v[50:53], v[154:157], v[178:181], v[50:53]
	v_mfma_f32_16x16x32_bf16 v[50:53], v[158:161], v[182:185], v[50:53]
	s_setprio 0
	s_setprio 1
	v_mfma_f32_16x16x32_bf16 v[42:45], v[154:157], v[170:173], v[42:45]
	v_mfma_f32_16x16x32_bf16 v[42:45], v[158:161], v[174:177], v[42:45]
	s_waitcnt lgkmcnt(0)
	s_setprio 0
	s_setprio 1
	v_mfma_f32_16x16x32_bf16 v[34:37], v[154:157], v[162:165], v[34:37]
	v_mfma_f32_16x16x32_bf16 v[34:37], v[158:161], v[166:169], v[34:37]
	s_setprio 0
	s_setprio 1
	v_mfma_f32_16x16x32_bf16 v[30:33], v[130:133], v[186:189], v[30:33]
	v_mfma_f32_16x16x32_bf16 v[30:33], v[134:137], v[190:193], v[30:33]
	s_setprio 0
	s_setprio 1
	v_mfma_f32_16x16x32_bf16 v[22:25], v[130:133], v[178:181], v[22:25]
	v_mfma_f32_16x16x32_bf16 v[22:25], v[134:137], v[182:185], v[22:25]
	s_setprio 0
	s_setprio 1
	v_mfma_f32_16x16x32_bf16 v[14:17], v[130:133], v[170:173], v[14:17]
	v_mfma_f32_16x16x32_bf16 v[14:17], v[134:137], v[174:177], v[14:17]
	s_setprio 0
	s_setprio 1
	v_mfma_f32_16x16x32_bf16 v[6:9], v[130:133], v[162:165], v[6:9]
	v_mfma_f32_16x16x32_bf16 v[6:9], v[134:137], v[166:169], v[6:9]
	s_setprio 0
	s_setprio 1
	v_mfma_f32_16x16x32_bf16 v[26:29], v[138:141], v[186:189], v[26:29]
	v_mfma_f32_16x16x32_bf16 v[26:29], v[142:145], v[190:193], v[26:29]
	s_setprio 0
	s_setprio 1
	v_mfma_f32_16x16x32_bf16 v[18:21], v[138:141], v[178:181], v[18:21]
	v_mfma_f32_16x16x32_bf16 v[18:21], v[142:145], v[182:185], v[18:21]
	s_setprio 0
	s_setprio 1
	v_mfma_f32_16x16x32_bf16 v[10:13], v[138:141], v[170:173], v[10:13]
	v_mfma_f32_16x16x32_bf16 v[10:13], v[142:145], v[174:177], v[10:13]
	s_setprio 2
	s_barrier
	v_mfma_f32_16x16x32_bf16 v[2:5], v[138:141], v[162:165], v[2:5]
	v_mfma_f32_16x16x32_bf16 v[2:5], v[142:145], v[166:169], v[2:5]
	s_setprio 0
	s_nop 0
	v_add_u32_e32 v142, 0x18000, v216
	v_add_u32_e32 v158, 0x1c000, v216
	ds_read_b128 v[130:133], v142
	ds_read_b128 v[134:137], v142 offset:1024
	ds_read_b128 v[138:141], v142 offset:2048
	ds_read_b128 v[142:145], v142 offset:3072
	ds_read_b128 v[146:149], v158
	ds_read_b128 v[150:153], v158 offset:1024
	ds_read_b128 v[154:157], v158 offset:2048
	ds_read_b128 v[158:161], v158 offset:3072
	ds_read_b128 v[162:165], v217 offset:32768
	ds_read_b128 v[166:169], v217 offset:33792
	ds_read_b128 v[170:173], v217 offset:34816
	ds_read_b128 v[174:177], v217 offset:35840
	ds_read_b128 v[178:181], v217 offset:36864
	ds_read_b128 v[182:185], v217 offset:37888
	ds_read_b128 v[186:189], v217 offset:38912
	ds_read_b128 v[190:193], v217 offset:39936
	s_add_u32 s50, s50, 0x4000
	s_addc_u32 s51, s51, 0
	s_mov_b32 m0, s68
	s_nop 0
	global_load_lds_dwordx4 v195, s[50:51]
	s_add_u32 m0, s68, 0x2000
	s_nop 0
	global_load_lds_dwordx4 v212, s[50:51]
	s_waitcnt vmcnt(8)
	s_waitcnt lgkmcnt(0)
	s_setprio 1
	s_barrier
	v_mfma_f32_16x16x32_bf16 v[126:129], v[130:133], v[162:165], v[126:129]
	v_mfma_f32_16x16x32_bf16 v[126:129], v[134:137], v[166:169], v[126:129]
	s_waitcnt lgkmcnt(5)
	s_setprio 0
	s_setprio 1
	v_mfma_f32_16x16x32_bf16 v[118:121], v[130:133], v[170:173], v[118:121]
	v_mfma_f32_16x16x32_bf16 v[118:121], v[134:137], v[174:177], v[118:121]
	s_waitcnt lgkmcnt(3)
	s_setprio 0
	s_setprio 1
	v_mfma_f32_16x16x32_bf16 v[110:113], v[130:133], v[178:181], v[110:113]
	v_mfma_f32_16x16x32_bf16 v[110:113], v[134:137], v[182:185], v[110:113]
	s_waitcnt lgkmcnt(1)
	s_setprio 0
	s_setprio 1
	v_mfma_f32_16x16x32_bf16 v[102:105], v[130:133], v[186:189], v[102:105]
	v_mfma_f32_16x16x32_bf16 v[102:105], v[134:137], v[190:193], v[102:105]
	s_setprio 0
	s_setprio 1
	v_mfma_f32_16x16x32_bf16 v[122:125], v[138:141], v[162:165], v[122:125]
	v_mfma_f32_16x16x32_bf16 v[122:125], v[142:145], v[166:169], v[122:125]
	s_setprio 0
	s_setprio 1
	v_mfma_f32_16x16x32_bf16 v[114:117], v[138:141], v[170:173], v[114:117]
	v_mfma_f32_16x16x32_bf16 v[114:117], v[142:145], v[174:177], v[114:117]
	s_setprio 0
	s_setprio 1
	v_mfma_f32_16x16x32_bf16 v[106:109], v[138:141], v[178:181], v[106:109]
	v_mfma_f32_16x16x32_bf16 v[106:109], v[142:145], v[182:185], v[106:109]
	s_waitcnt lgkmcnt(0)
	s_setprio 0
	s_setprio 1
	v_mfma_f32_16x16x32_bf16 v[98:101], v[138:141], v[186:189], v[98:101]
	v_mfma_f32_16x16x32_bf16 v[98:101], v[142:145], v[190:193], v[98:101]
	s_setprio 0
	s_setprio 1
	v_mfma_f32_16x16x32_bf16 v[94:97], v[146:149], v[162:165], v[94:97]
	v_mfma_f32_16x16x32_bf16 v[94:97], v[150:153], v[166:169], v[94:97]
	s_setprio 0
	s_setprio 1
	v_mfma_f32_16x16x32_bf16 v[86:89], v[146:149], v[170:173], v[86:89]
	v_mfma_f32_16x16x32_bf16 v[86:89], v[150:153], v[174:177], v[86:89]
	s_setprio 0
	s_setprio 1
	v_mfma_f32_16x16x32_bf16 v[78:81], v[146:149], v[178:181], v[78:81]
	v_mfma_f32_16x16x32_bf16 v[78:81], v[150:153], v[182:185], v[78:81]
	s_setprio 0
	s_setprio 1
	v_mfma_f32_16x16x32_bf16 v[70:73], v[146:149], v[186:189], v[70:73]
	v_mfma_f32_16x16x32_bf16 v[70:73], v[150:153], v[190:193], v[70:73]
	s_setprio 0
	s_setprio 1
	v_mfma_f32_16x16x32_bf16 v[90:93], v[154:157], v[162:165], v[90:93]
	v_mfma_f32_16x16x32_bf16 v[90:93], v[158:161], v[166:169], v[90:93]
	s_setprio 0
	s_setprio 1
	v_mfma_f32_16x16x32_bf16 v[82:85], v[154:157], v[170:173], v[82:85]
	v_mfma_f32_16x16x32_bf16 v[82:85], v[158:161], v[174:177], v[82:85]
	s_setprio 0
	s_setprio 1
	v_mfma_f32_16x16x32_bf16 v[74:77], v[154:157], v[178:181], v[74:77]
	v_mfma_f32_16x16x32_bf16 v[74:77], v[158:161], v[182:185], v[74:77]
	s_setprio 2
	s_barrier
	v_mfma_f32_16x16x32_bf16 v[66:69], v[154:157], v[186:189], v[66:69]
	v_mfma_f32_16x16x32_bf16 v[66:69], v[158:161], v[190:193], v[66:69]
	s_setprio 0
	s_nop 0
	ds_read_b128 v[162:165], v217 offset:49152
	ds_read_b128 v[166:169], v217 offset:50176
	ds_read_b128 v[170:173], v217 offset:51200
	ds_read_b128 v[174:177], v217 offset:52224
	ds_read_b128 v[178:181], v217 offset:53248
	ds_read_b128 v[182:185], v217 offset:54272
	ds_read_b128 v[186:189], v217 offset:55296
	ds_read_b128 v[190:193], v217 offset:56320
	s_mov_b32 m0, s72
	s_nop 0
	global_load_lds_dwordx4 v195, s[54:55]
	s_add_u32 m0, s72, 0x2000
	s_nop 0
	global_load_lds_dwordx4 v212, s[54:55]
	s_add_u32 s12, s12, 0xc000
	s_addc_u32 s13, s13, 0
	s_mov_b32 m0, s74
	s_nop 0
	global_load_lds_dwordx4 v195, s[12:13]
	s_add_u32 m0, s74, 0x2000
	s_nop 0
	global_load_lds_dwordx4 v212, s[12:13]
	s_nop 0
	s_mov_b32 m0, s73
	s_nop 0
	global_load_lds_dwordx4 v195, s[52:53]
	s_add_u32 m0, s73, 0x2000
	s_nop 0
	global_load_lds_dwordx4 v212, s[52:53]
	s_waitcnt vmcnt(8)
	s_waitcnt lgkmcnt(0)
	s_setprio 1
	s_barrier
	v_mfma_f32_16x16x32_bf16 v[62:65], v[130:133], v[162:165], v[62:65]
	v_mfma_f32_16x16x32_bf16 v[62:65], v[134:137], v[166:169], v[62:65]
	s_waitcnt lgkmcnt(5)
	s_setprio 0
	s_setprio 1
	v_mfma_f32_16x16x32_bf16 v[54:57], v[130:133], v[170:173], v[54:57]
	v_mfma_f32_16x16x32_bf16 v[54:57], v[134:137], v[174:177], v[54:57]
	s_waitcnt lgkmcnt(3)
	s_setprio 0
	s_setprio 1
	v_mfma_f32_16x16x32_bf16 v[46:49], v[130:133], v[178:181], v[46:49]
	v_mfma_f32_16x16x32_bf16 v[46:49], v[134:137], v[182:185], v[46:49]
	s_waitcnt lgkmcnt(1)
	s_setprio 0
	s_setprio 1
	v_mfma_f32_16x16x32_bf16 v[38:41], v[130:133], v[186:189], v[38:41]
	v_mfma_f32_16x16x32_bf16 v[38:41], v[134:137], v[190:193], v[38:41]
	s_setprio 0
	s_setprio 1
	v_mfma_f32_16x16x32_bf16 v[58:61], v[138:141], v[162:165], v[58:61]
	v_mfma_f32_16x16x32_bf16 v[58:61], v[142:145], v[166:169], v[58:61]
	s_setprio 0
	s_setprio 1
	v_mfma_f32_16x16x32_bf16 v[50:53], v[138:141], v[170:173], v[50:53]
	v_mfma_f32_16x16x32_bf16 v[50:53], v[142:145], v[174:177], v[50:53]
	s_setprio 0
	s_setprio 1
	v_mfma_f32_16x16x32_bf16 v[42:45], v[138:141], v[178:181], v[42:45]
	v_mfma_f32_16x16x32_bf16 v[42:45], v[142:145], v[182:185], v[42:45]
	s_waitcnt lgkmcnt(0)
	s_setprio 0
	s_setprio 1
	v_mfma_f32_16x16x32_bf16 v[34:37], v[138:141], v[186:189], v[34:37]
	v_mfma_f32_16x16x32_bf16 v[34:37], v[142:145], v[190:193], v[34:37]
	s_setprio 0
	s_setprio 1
	v_mfma_f32_16x16x32_bf16 v[30:33], v[146:149], v[162:165], v[30:33]
	v_mfma_f32_16x16x32_bf16 v[30:33], v[150:153], v[166:169], v[30:33]
	s_setprio 0
	s_setprio 1
	v_mfma_f32_16x16x32_bf16 v[22:25], v[146:149], v[170:173], v[22:25]
	v_mfma_f32_16x16x32_bf16 v[22:25], v[150:153], v[174:177], v[22:25]
	s_setprio 0
	s_setprio 1
	v_mfma_f32_16x16x32_bf16 v[14:17], v[146:149], v[178:181], v[14:17]
	v_mfma_f32_16x16x32_bf16 v[14:17], v[150:153], v[182:185], v[14:17]
	s_setprio 0
	s_setprio 1
	v_mfma_f32_16x16x32_bf16 v[6:9], v[146:149], v[186:189], v[6:9]
	v_mfma_f32_16x16x32_bf16 v[6:9], v[150:153], v[190:193], v[6:9]
	s_setprio 0
	s_setprio 1
	v_mfma_f32_16x16x32_bf16 v[26:29], v[154:157], v[162:165], v[26:29]
	v_mfma_f32_16x16x32_bf16 v[26:29], v[158:161], v[166:169], v[26:29]
	s_setprio 0
	s_setprio 1
	v_mfma_f32_16x16x32_bf16 v[18:21], v[154:157], v[170:173], v[18:21]
	v_mfma_f32_16x16x32_bf16 v[18:21], v[158:161], v[174:177], v[18:21]
	s_setprio 0
	s_setprio 1
	v_mfma_f32_16x16x32_bf16 v[10:13], v[154:157], v[178:181], v[10:13]
	v_mfma_f32_16x16x32_bf16 v[10:13], v[158:161], v[182:185], v[10:13]
	s_setprio 2
	s_barrier
	v_mfma_f32_16x16x32_bf16 v[2:5], v[154:157], v[186:189], v[2:5]
	v_mfma_f32_16x16x32_bf16 v[2:5], v[158:161], v[190:193], v[2:5]
	s_setprio 0
	s_nop 0
	s_cmp_gt_u32 s58, 13
	s_cbranch_scc1 .LBB0_1523
	v_mov_b32_e32 v130, v198
	s_mov_b32 s58, s26
	s_branch .LBB0_1498

.LBB0_1712:
	s_add_u32 s52, s48, 0x10000
	s_addc_u32 s53, s49, 0
	s_and_b64 s[48:49], s[46:47], exec
	s_cselect_b32 s49, s53, s25
	s_cselect_b32 s48, s52, s75
	s_add_u32 s13, s16, s13
	s_addc_u32 s52, s17, 0
	s_add_u32 s13, s13, 0x10000
	s_waitcnt vmcnt(8)
	s_addc_u32 s52, s52, 0
	s_waitcnt lgkmcnt(0)
	s_and_b64 s[46:47], s[46:47], exec
	s_cselect_b32 s47, s52, s27
	s_cselect_b32 s46, s13, s76
	s_setprio 1
	s_barrier
	v_mfma_f32_16x16x32_bf16 v[126:129], v[146:149], v[186:189], v[126:129]
	v_mfma_f32_16x16x32_bf16 v[126:129], v[150:153], v[190:193], v[126:129]
	s_waitcnt lgkmcnt(5)
	s_setprio 0
	s_setprio 1
	v_mfma_f32_16x16x32_bf16 v[118:121], v[146:149], v[178:181], v[118:121]
	v_mfma_f32_16x16x32_bf16 v[118:121], v[150:153], v[182:185], v[118:121]
	s_waitcnt lgkmcnt(3)
	s_setprio 0
	s_setprio 1
	v_mfma_f32_16x16x32_bf16 v[110:113], v[146:149], v[170:173], v[110:113]
	v_mfma_f32_16x16x32_bf16 v[110:113], v[150:153], v[174:177], v[110:113]
	s_waitcnt lgkmcnt(1)
	s_setprio 0
	s_setprio 1
	v_mfma_f32_16x16x32_bf16 v[102:105], v[146:149], v[162:165], v[102:105]
	v_mfma_f32_16x16x32_bf16 v[102:105], v[150:153], v[166:169], v[102:105]
	s_setprio 0
	s_setprio 1
	v_mfma_f32_16x16x32_bf16 v[122:125], v[154:157], v[186:189], v[122:125]
	v_mfma_f32_16x16x32_bf16 v[122:125], v[158:161], v[190:193], v[122:125]
	s_setprio 0
	s_setprio 1
	v_mfma_f32_16x16x32_bf16 v[114:117], v[154:157], v[178:181], v[114:117]
	v_mfma_f32_16x16x32_bf16 v[114:117], v[158:161], v[182:185], v[114:117]
	s_setprio 0
	s_setprio 1
	v_mfma_f32_16x16x32_bf16 v[106:109], v[154:157], v[170:173], v[106:109]
	v_mfma_f32_16x16x32_bf16 v[106:109], v[158:161], v[174:177], v[106:109]
	s_waitcnt lgkmcnt(0)
	s_setprio 0
	s_setprio 1
	v_mfma_f32_16x16x32_bf16 v[98:101], v[154:157], v[162:165], v[98:101]
	v_mfma_f32_16x16x32_bf16 v[98:101], v[158:161], v[166:169], v[98:101]
	s_setprio 0
	s_setprio 1
	v_mfma_f32_16x16x32_bf16 v[94:97], v[130:133], v[186:189], v[94:97]
	v_mfma_f32_16x16x32_bf16 v[94:97], v[134:137], v[190:193], v[94:97]
	s_setprio 0
	s_setprio 1
	v_mfma_f32_16x16x32_bf16 v[86:89], v[130:133], v[178:181], v[86:89]
	v_mfma_f32_16x16x32_bf16 v[86:89], v[134:137], v[182:185], v[86:89]
	s_setprio 0
	s_setprio 1
	v_mfma_f32_16x16x32_bf16 v[78:81], v[130:133], v[170:173], v[78:81]
	v_mfma_f32_16x16x32_bf16 v[78:81], v[134:137], v[174:177], v[78:81]
	s_setprio 0
	s_setprio 1
	v_mfma_f32_16x16x32_bf16 v[70:73], v[130:133], v[162:165], v[70:73]
	v_mfma_f32_16x16x32_bf16 v[70:73], v[134:137], v[166:169], v[70:73]
	s_setprio 0
	s_setprio 1
	v_mfma_f32_16x16x32_bf16 v[90:93], v[138:141], v[186:189], v[90:93]
	v_mfma_f32_16x16x32_bf16 v[90:93], v[142:145], v[190:193], v[90:93]
	s_setprio 0
	s_setprio 1
	v_mfma_f32_16x16x32_bf16 v[82:85], v[138:141], v[178:181], v[82:85]
	v_mfma_f32_16x16x32_bf16 v[82:85], v[142:145], v[182:185], v[82:85]
	s_setprio 0
	s_setprio 1
	v_mfma_f32_16x16x32_bf16 v[74:77], v[138:141], v[170:173], v[74:77]
	v_mfma_f32_16x16x32_bf16 v[74:77], v[142:145], v[174:177], v[74:77]
	s_setprio 2
	s_barrier
	v_mfma_f32_16x16x32_bf16 v[66:69], v[138:141], v[162:165], v[66:69]
	v_mfma_f32_16x16x32_bf16 v[66:69], v[142:145], v[166:169], v[66:69]
	s_setprio 0
	s_nop 0
	ds_read_b128 v[186:189], v209 offset:16384
	ds_read_b128 v[190:193], v209 offset:17408
	ds_read_b128 v[178:181], v209 offset:18432
	ds_read_b128 v[182:185], v209 offset:19456
	ds_read_b128 v[170:173], v209 offset:20480
	ds_read_b128 v[174:177], v209 offset:21504
	ds_read_b128 v[162:165], v209 offset:22528
	ds_read_b128 v[166:169], v209 offset:23552
	s_mov_b32 m0, s58
	s_nop 0
	global_load_lds_dwordx4 v195, s[46:47]
	s_add_u32 m0, s58, 0x2000
	s_nop 0
	global_load_lds_dwordx4 v203, s[46:47]
	s_add_u32 s52, s46, 0x4000
	s_addc_u32 s53, s47, 0
	s_mov_b32 m0, s59
	s_nop 0
	global_load_lds_dwordx4 v195, s[52:53]
	s_add_u32 m0, s59, 0x2000
	s_nop 0
	global_load_lds_dwordx4 v203, s[52:53]
	s_andn2_b64 vcc, exec, s[50:51]
	s_mov_b32 m0, s11
	s_nop 0
	global_load_lds_dwordx4 v195, s[48:49]
	s_add_u32 m0, s11, 0x2000
	s_nop 0
	global_load_lds_dwordx4 v203, s[48:49]
	s_cbranch_vccnz .LBB0_1714
	v_mov_b32_e32 v2, 0
	v_mov_b32_e32 v3, v2
	v_mov_b32_e32 v4, v2
	v_mov_b32_e32 v5, v2
	v_mov_b32_e32 v6, v2
	v_mov_b32_e32 v7, v2
	v_mov_b32_e32 v8, v2
	v_mov_b32_e32 v9, v2
	v_mov_b32_e32 v10, v2
	v_mov_b32_e32 v11, v2
	v_mov_b32_e32 v12, v2
	v_mov_b32_e32 v13, v2
	v_mov_b32_e32 v14, v2
	v_mov_b32_e32 v15, v2
	v_mov_b32_e32 v16, v2
	v_mov_b32_e32 v17, v2
	v_mov_b32_e32 v18, v2
	v_mov_b32_e32 v19, v2
	v_mov_b32_e32 v20, v2
	v_mov_b32_e32 v21, v2
	v_mov_b32_e32 v22, v2
	v_mov_b32_e32 v23, v2
	v_mov_b32_e32 v24, v2
	v_mov_b32_e32 v25, v2
	v_mov_b32_e32 v26, v2
	v_mov_b32_e32 v27, v2
	v_mov_b32_e32 v28, v2
	v_mov_b32_e32 v29, v2
	v_mov_b32_e32 v30, v2
	v_mov_b32_e32 v31, v2
	v_mov_b32_e32 v32, v2
	v_mov_b32_e32 v33, v2
	v_mov_b32_e32 v34, v2
	v_mov_b32_e32 v35, v2
	v_mov_b32_e32 v36, v2
	v_mov_b32_e32 v37, v2
	v_mov_b32_e32 v38, v2
	v_mov_b32_e32 v39, v2
	v_mov_b32_e32 v40, v2
	v_mov_b32_e32 v41, v2
	v_mov_b32_e32 v42, v2
	v_mov_b32_e32 v43, v2
	v_mov_b32_e32 v44, v2
	v_mov_b32_e32 v45, v2
	v_mov_b32_e32 v46, v2
	v_mov_b32_e32 v47, v2
	v_mov_b32_e32 v48, v2
	v_mov_b32_e32 v49, v2
	v_mov_b32_e32 v50, v2
	v_mov_b32_e32 v51, v2
	v_mov_b32_e32 v52, v2
	v_mov_b32_e32 v53, v2
	v_mov_b32_e32 v54, v2
	v_mov_b32_e32 v55, v2
	v_mov_b32_e32 v56, v2
	v_mov_b32_e32 v57, v2
	v_mov_b32_e32 v58, v2
	v_mov_b32_e32 v59, v2
	v_mov_b32_e32 v60, v2
	v_mov_b32_e32 v61, v2
	v_mov_b32_e32 v62, v2
	v_mov_b32_e32 v63, v2
	v_mov_b32_e32 v64, v2
	v_mov_b32_e32 v65, v2
.LBB0_1714:
	s_waitcnt vmcnt(8)
	s_add_u32 s50, s48, 0x8000
	s_waitcnt lgkmcnt(0)
	s_addc_u32 s51, s49, 0
	s_add_u32 s52, s46, 0x8000
	s_addc_u32 s53, s47, 0
	s_setprio 1
	s_barrier
	v_mfma_f32_16x16x32_bf16 v[62:65], v[146:149], v[186:189], v[62:65]
	v_mfma_f32_16x16x32_bf16 v[62:65], v[150:153], v[190:193], v[62:65]
	s_waitcnt lgkmcnt(5)
	s_setprio 0
	s_setprio 1
	v_mfma_f32_16x16x32_bf16 v[54:57], v[146:149], v[178:181], v[54:57]
	v_mfma_f32_16x16x32_bf16 v[54:57], v[150:153], v[182:185], v[54:57]
	s_waitcnt lgkmcnt(3)
	s_setprio 0
	s_setprio 1
	v_mfma_f32_16x16x32_bf16 v[46:49], v[146:149], v[170:173], v[46:49]
	v_mfma_f32_16x16x32_bf16 v[46:49], v[150:153], v[174:177], v[46:49]
	s_waitcnt lgkmcnt(1)
	s_setprio 0
	s_setprio 1
	v_mfma_f32_16x16x32_bf16 v[38:41], v[146:149], v[162:165], v[38:41]
	v_mfma_f32_16x16x32_bf16 v[38:41], v[150:153], v[166:169], v[38:41]
	s_setprio 0
	s_setprio 1
	v_mfma_f32_16x16x32_bf16 v[58:61], v[154:157], v[186:189], v[58:61]
	v_mfma_f32_16x16x32_bf16 v[58:61], v[158:161], v[190:193], v[58:61]
	s_setprio 0
	s_setprio 1
	v_mfma_f32_16x16x32_bf16 v[50:53], v[154:157], v[178:181], v[50:53]
	v_mfma_f32_16x16x32_bf16 v[50:53], v[158:161], v[182:185], v[50:53]
	s_setprio 0
	s_setprio 1
	v_mfma_f32_16x16x32_bf16 v[42:45], v[154:157], v[170:173], v[42:45]
	v_mfma_f32_16x16x32_bf16 v[42:45], v[158:161], v[174:177], v[42:45]
	s_waitcnt lgkmcnt(0)
	s_setprio 0
	s_setprio 1
	v_mfma_f32_16x16x32_bf16 v[34:37], v[154:157], v[162:165], v[34:37]
	v_mfma_f32_16x16x32_bf16 v[34:37], v[158:161], v[166:169], v[34:37]
	s_setprio 0
	s_setprio 1
	v_mfma_f32_16x16x32_bf16 v[30:33], v[130:133], v[186:189], v[30:33]
	v_mfma_f32_16x16x32_bf16 v[30:33], v[134:137], v[190:193], v[30:33]
	s_setprio 0
	s_setprio 1
	v_mfma_f32_16x16x32_bf16 v[22:25], v[130:133], v[178:181], v[22:25]
	v_mfma_f32_16x16x32_bf16 v[22:25], v[134:137], v[182:185], v[22:25]
	s_setprio 0
	s_setprio 1
	v_mfma_f32_16x16x32_bf16 v[14:17], v[130:133], v[170:173], v[14:17]
	v_mfma_f32_16x16x32_bf16 v[14:17], v[134:137], v[174:177], v[14:17]
	s_setprio 0
	s_setprio 1
	v_mfma_f32_16x16x32_bf16 v[6:9], v[130:133], v[162:165], v[6:9]
	v_mfma_f32_16x16x32_bf16 v[6:9], v[134:137], v[166:169], v[6:9]
	s_setprio 0
	s_setprio 1
	v_mfma_f32_16x16x32_bf16 v[26:29], v[138:141], v[186:189], v[26:29]
	v_mfma_f32_16x16x32_bf16 v[26:29], v[142:145], v[190:193], v[26:29]
	s_setprio 0
	s_setprio 1
	v_mfma_f32_16x16x32_bf16 v[18:21], v[138:141], v[178:181], v[18:21]
	v_mfma_f32_16x16x32_bf16 v[18:21], v[142:145], v[182:185], v[18:21]
	s_setprio 0
	s_setprio 1
	v_mfma_f32_16x16x32_bf16 v[10:13], v[138:141], v[170:173], v[10:13]
	v_mfma_f32_16x16x32_bf16 v[10:13], v[142:145], v[174:177], v[10:13]
	s_setprio 2
	s_barrier
	v_mfma_f32_16x16x32_bf16 v[2:5], v[138:141], v[162:165], v[2:5]
	v_mfma_f32_16x16x32_bf16 v[2:5], v[142:145], v[166:169], v[2:5]
	s_setprio 0
	s_nop 0
	v_add_u32_e32 v142, 0x18000, v208
	v_add_u32_e32 v158, 0x1c000, v208
	ds_read_b128 v[130:133], v142
	ds_read_b128 v[134:137], v142 offset:1024
	ds_read_b128 v[138:141], v142 offset:2048
	ds_read_b128 v[142:145], v142 offset:3072
	ds_read_b128 v[146:149], v158
	ds_read_b128 v[150:153], v158 offset:1024
	ds_read_b128 v[154:157], v158 offset:2048
	ds_read_b128 v[158:161], v158 offset:3072
	ds_read_b128 v[162:165], v209 offset:32768
	ds_read_b128 v[166:169], v209 offset:33792
	ds_read_b128 v[170:173], v209 offset:34816
	ds_read_b128 v[174:177], v209 offset:35840
	ds_read_b128 v[178:181], v209 offset:36864
	ds_read_b128 v[182:185], v209 offset:37888
	ds_read_b128 v[186:189], v209 offset:38912
	ds_read_b128 v[190:193], v209 offset:39936
	s_add_u32 s48, s48, 0x4000
	s_addc_u32 s49, s49, 0
	s_mov_b32 m0, s60
	s_nop 0
	global_load_lds_dwordx4 v195, s[48:49]
	s_add_u32 m0, s60, 0x2000
	s_nop 0
	global_load_lds_dwordx4 v203, s[48:49]
	s_waitcnt vmcnt(8)
	s_waitcnt lgkmcnt(0)
	s_setprio 1
	s_barrier
	v_mfma_f32_16x16x32_bf16 v[126:129], v[130:133], v[162:165], v[126:129]
	v_mfma_f32_16x16x32_bf16 v[126:129], v[134:137], v[166:169], v[126:129]
	s_waitcnt lgkmcnt(5)
	s_setprio 0
	s_setprio 1
	v_mfma_f32_16x16x32_bf16 v[118:121], v[130:133], v[170:173], v[118:121]
	v_mfma_f32_16x16x32_bf16 v[118:121], v[134:137], v[174:177], v[118:121]
	s_waitcnt lgkmcnt(3)
	s_setprio 0
	s_setprio 1
	v_mfma_f32_16x16x32_bf16 v[110:113], v[130:133], v[178:181], v[110:113]
	v_mfma_f32_16x16x32_bf16 v[110:113], v[134:137], v[182:185], v[110:113]
	s_waitcnt lgkmcnt(1)
	s_setprio 0
	s_setprio 1
	v_mfma_f32_16x16x32_bf16 v[102:105], v[130:133], v[186:189], v[102:105]
	v_mfma_f32_16x16x32_bf16 v[102:105], v[134:137], v[190:193], v[102:105]
	s_setprio 0
	s_setprio 1
	v_mfma_f32_16x16x32_bf16 v[122:125], v[138:141], v[162:165], v[122:125]
	v_mfma_f32_16x16x32_bf16 v[122:125], v[142:145], v[166:169], v[122:125]
	s_setprio 0
	s_setprio 1
	v_mfma_f32_16x16x32_bf16 v[114:117], v[138:141], v[170:173], v[114:117]
	v_mfma_f32_16x16x32_bf16 v[114:117], v[142:145], v[174:177], v[114:117]
	s_setprio 0
	s_setprio 1
	v_mfma_f32_16x16x32_bf16 v[106:109], v[138:141], v[178:181], v[106:109]
	v_mfma_f32_16x16x32_bf16 v[106:109], v[142:145], v[182:185], v[106:109]
	s_waitcnt lgkmcnt(0)
	s_setprio 0
	s_setprio 1
	v_mfma_f32_16x16x32_bf16 v[98:101], v[138:141], v[186:189], v[98:101]
	v_mfma_f32_16x16x32_bf16 v[98:101], v[142:145], v[190:193], v[98:101]
	s_setprio 0
	s_setprio 1
	v_mfma_f32_16x16x32_bf16 v[94:97], v[146:149], v[162:165], v[94:97]
	v_mfma_f32_16x16x32_bf16 v[94:97], v[150:153], v[166:169], v[94:97]
	s_setprio 0
	s_setprio 1
	v_mfma_f32_16x16x32_bf16 v[86:89], v[146:149], v[170:173], v[86:89]
	v_mfma_f32_16x16x32_bf16 v[86:89], v[150:153], v[174:177], v[86:89]
	s_setprio 0
	s_setprio 1
	v_mfma_f32_16x16x32_bf16 v[78:81], v[146:149], v[178:181], v[78:81]
	v_mfma_f32_16x16x32_bf16 v[78:81], v[150:153], v[182:185], v[78:81]
	s_setprio 0
	s_setprio 1
	v_mfma_f32_16x16x32_bf16 v[70:73], v[146:149], v[186:189], v[70:73]
	v_mfma_f32_16x16x32_bf16 v[70:73], v[150:153], v[190:193], v[70:73]
	s_setprio 0
	s_setprio 1
	v_mfma_f32_16x16x32_bf16 v[90:93], v[154:157], v[162:165], v[90:93]
	v_mfma_f32_16x16x32_bf16 v[90:93], v[158:161], v[166:169], v[90:93]
	s_setprio 0
	s_setprio 1
	v_mfma_f32_16x16x32_bf16 v[82:85], v[154:157], v[170:173], v[82:85]
	v_mfma_f32_16x16x32_bf16 v[82:85], v[158:161], v[174:177], v[82:85]
	s_setprio 0
	s_setprio 1
	v_mfma_f32_16x16x32_bf16 v[74:77], v[154:157], v[178:181], v[74:77]
	v_mfma_f32_16x16x32_bf16 v[74:77], v[158:161], v[182:185], v[74:77]
	s_setprio 2
	s_barrier
	v_mfma_f32_16x16x32_bf16 v[66:69], v[154:157], v[186:189], v[66:69]
	v_mfma_f32_16x16x32_bf16 v[66:69], v[158:161], v[190:193], v[66:69]
	s_setprio 0
	s_nop 0
	ds_read_b128 v[162:165], v209 offset:49152
	ds_read_b128 v[166:169], v209 offset:50176
	ds_read_b128 v[170:173], v209 offset:51200
	ds_read_b128 v[174:177], v209 offset:52224
	ds_read_b128 v[178:181], v209 offset:53248
	ds_read_b128 v[182:185], v209 offset:54272
	ds_read_b128 v[186:189], v209 offset:55296
	ds_read_b128 v[190:193], v209 offset:56320
	s_mov_b32 m0, s64
	s_nop 0
	global_load_lds_dwordx4 v195, s[52:53]
	s_add_u32 m0, s64, 0x2000
	s_nop 0
	global_load_lds_dwordx4 v203, s[52:53]
	s_add_u32 s46, s46, 0xc000
	s_addc_u32 s47, s47, 0
	s_mov_b32 m0, s66
	s_nop 0
	global_load_lds_dwordx4 v195, s[46:47]
	s_add_u32 m0, s66, 0x2000
	s_nop 0
	global_load_lds_dwordx4 v203, s[46:47]
	s_nop 0
	s_mov_b32 m0, s65
	s_nop 0
	global_load_lds_dwordx4 v195, s[50:51]
	s_add_u32 m0, s65, 0x2000
	s_nop 0
	global_load_lds_dwordx4 v203, s[50:51]
	s_waitcnt vmcnt(8)
	s_waitcnt lgkmcnt(0)
	s_setprio 1
	s_barrier
	v_mfma_f32_16x16x32_bf16 v[62:65], v[130:133], v[162:165], v[62:65]
	v_mfma_f32_16x16x32_bf16 v[62:65], v[134:137], v[166:169], v[62:65]
	s_waitcnt lgkmcnt(5)
	s_setprio 0
	s_setprio 1
	v_mfma_f32_16x16x32_bf16 v[54:57], v[130:133], v[170:173], v[54:57]
	v_mfma_f32_16x16x32_bf16 v[54:57], v[134:137], v[174:177], v[54:57]
	s_waitcnt lgkmcnt(3)
	s_setprio 0
	s_setprio 1
	v_mfma_f32_16x16x32_bf16 v[46:49], v[130:133], v[178:181], v[46:49]
	v_mfma_f32_16x16x32_bf16 v[46:49], v[134:137], v[182:185], v[46:49]
	s_waitcnt lgkmcnt(1)
	s_setprio 0
	s_setprio 1
	v_mfma_f32_16x16x32_bf16 v[38:41], v[130:133], v[186:189], v[38:41]
	v_mfma_f32_16x16x32_bf16 v[38:41], v[134:137], v[190:193], v[38:41]
	s_setprio 0
	s_setprio 1
	v_mfma_f32_16x16x32_bf16 v[58:61], v[138:141], v[162:165], v[58:61]
	v_mfma_f32_16x16x32_bf16 v[58:61], v[142:145], v[166:169], v[58:61]
	s_setprio 0
	s_setprio 1
	v_mfma_f32_16x16x32_bf16 v[50:53], v[138:141], v[170:173], v[50:53]
	v_mfma_f32_16x16x32_bf16 v[50:53], v[142:145], v[174:177], v[50:53]
	s_setprio 0
	s_setprio 1
	v_mfma_f32_16x16x32_bf16 v[42:45], v[138:141], v[178:181], v[42:45]
	v_mfma_f32_16x16x32_bf16 v[42:45], v[142:145], v[182:185], v[42:45]
	s_waitcnt lgkmcnt(0)
	s_setprio 0
	s_setprio 1
	v_mfma_f32_16x16x32_bf16 v[34:37], v[138:141], v[186:189], v[34:37]
	v_mfma_f32_16x16x32_bf16 v[34:37], v[142:145], v[190:193], v[34:37]
	s_setprio 0
	s_setprio 1
	v_mfma_f32_16x16x32_bf16 v[30:33], v[146:149], v[162:165], v[30:33]
	v_mfma_f32_16x16x32_bf16 v[30:33], v[150:153], v[166:169], v[30:33]
	s_setprio 0
	s_setprio 1
	v_mfma_f32_16x16x32_bf16 v[22:25], v[146:149], v[170:173], v[22:25]
	v_mfma_f32_16x16x32_bf16 v[22:25], v[150:153], v[174:177], v[22:25]
	s_setprio 0
	s_setprio 1
	v_mfma_f32_16x16x32_bf16 v[14:17], v[146:149], v[178:181], v[14:17]
	v_mfma_f32_16x16x32_bf16 v[14:17], v[150:153], v[182:185], v[14:17]
	s_setprio 0
	s_setprio 1
	v_mfma_f32_16x16x32_bf16 v[6:9], v[146:149], v[186:189], v[6:9]
	v_mfma_f32_16x16x32_bf16 v[6:9], v[150:153], v[190:193], v[6:9]
	s_setprio 0
	s_setprio 1
	v_mfma_f32_16x16x32_bf16 v[26:29], v[154:157], v[162:165], v[26:29]
	v_mfma_f32_16x16x32_bf16 v[26:29], v[158:161], v[166:169], v[26:29]
	s_setprio 0
	s_setprio 1
	v_mfma_f32_16x16x32_bf16 v[18:21], v[154:157], v[170:173], v[18:21]
	v_mfma_f32_16x16x32_bf16 v[18:21], v[158:161], v[174:177], v[18:21]
	s_setprio 0
	s_setprio 1
	v_mfma_f32_16x16x32_bf16 v[10:13], v[154:157], v[178:181], v[10:13]
	v_mfma_f32_16x16x32_bf16 v[10:13], v[158:161], v[182:185], v[10:13]
	s_setprio 2
	s_barrier
	v_mfma_f32_16x16x32_bf16 v[2:5], v[154:157], v[186:189], v[2:5]
	v_mfma_f32_16x16x32_bf16 v[2:5], v[158:161], v[190:193], v[2:5]
	s_setprio 0
	s_nop 0
	s_add_i32 s13, s77, 2
	s_cmp_gt_u32 s77, 13
	s_cbranch_scc1 .LBB0_1716
	s_mov_b32 s77, s13
	s_branch .LBB0_1693

.LBB0_1919:
	s_or_b64 exec, exec, s[10:11]
	s_add_u32 s50, s16, s6
	ds_read_b128 v[134:137], v201
	ds_read_b128 v[138:141], v201 offset:1024
	ds_read_b128 v[142:145], v201 offset:2048
	ds_read_b128 v[146:149], v201 offset:3072
	ds_read_b128 v[150:153], v202
	ds_read_b128 v[154:157], v202 offset:1024
	ds_read_b128 v[162:165], v202 offset:2048
	ds_read_b128 v[166:169], v202 offset:3072
	s_addc_u32 s51, s17, s7
	s_add_u32 s10, s50, 0x20000
	s_addc_u32 s11, s51, 0
	s_add_u32 s42, s75, s6
	s_addc_u32 s43, s76, s7
	s_cmp_eq_u32 s6, 0x60000
	s_cselect_b32 s46, s29, s10
	s_cselect_b32 s47, s20, s11
	s_cselect_b32 s11, s27, s43
	s_cselect_b32 s10, s48, s42
	s_add_u32 s42, s46, 0x8000
	s_addc_u32 s43, s47, 0
	s_add_u32 s44, s10, 0x8000
	s_addc_u32 s45, s11, 0
	ds_read_b128 v[170:173], v203
	ds_read_b128 v[174:177], v203 offset:1024
	ds_read_b128 v[178:181], v203 offset:2048
	ds_read_b128 v[182:185], v203 offset:3072
	ds_read_b128 v[186:189], v203 offset:4096
	ds_read_b128 v[190:193], v203 offset:5120
	ds_read_b128 v[212:215], v203 offset:6144
	ds_read_b128 v[216:219], v203 offset:7168
	s_add_u32 s50, s50, 0x1c000
	s_addc_u32 s51, s51, 0
	s_mov_b32 m0, s65
	s_nop 0
	global_load_lds_dwordx4 v195, s[50:51]
	s_add_u32 m0, s65, 0x2000
	s_nop 0
	global_load_lds_dwordx4 v197, s[50:51]
	s_waitcnt vmcnt(8)
	s_waitcnt lgkmcnt(0)
	s_setprio 1
	s_barrier
	v_mfma_f32_16x16x32_bf16 v[130:133], v[134:137], v[170:173], v[130:133]
	v_mfma_f32_16x16x32_bf16 v[126:129], v[142:145], v[170:173], v[126:129]
	s_waitcnt lgkmcnt(5)
	v_mfma_f32_16x16x32_bf16 v[110:113], v[134:137], v[178:181], v[110:113]
	v_mfma_f32_16x16x32_bf16 v[106:109], v[142:145], v[178:181], v[106:109]
	s_waitcnt lgkmcnt(3)
	v_mfma_f32_16x16x32_bf16 v[94:97], v[134:137], v[186:189], v[94:97]
	v_mfma_f32_16x16x32_bf16 v[90:93], v[142:145], v[186:189], v[90:93]
	s_waitcnt lgkmcnt(1)
	v_mfma_f32_16x16x32_bf16 v[78:81], v[134:137], v[212:215], v[78:81]
	v_mfma_f32_16x16x32_bf16 v[74:77], v[142:145], v[212:215], v[74:77]
	v_mfma_f32_16x16x32_bf16 v[130:133], v[138:141], v[174:177], v[130:133]
	v_mfma_f32_16x16x32_bf16 v[126:129], v[146:149], v[174:177], v[126:129]
	v_mfma_f32_16x16x32_bf16 v[110:113], v[138:141], v[182:185], v[110:113]
	v_mfma_f32_16x16x32_bf16 v[106:109], v[146:149], v[182:185], v[106:109]
	v_mfma_f32_16x16x32_bf16 v[94:97], v[138:141], v[190:193], v[94:97]
	v_mfma_f32_16x16x32_bf16 v[90:93], v[146:149], v[190:193], v[90:93]
	s_waitcnt lgkmcnt(0)
	v_mfma_f32_16x16x32_bf16 v[78:81], v[138:141], v[216:219], v[78:81]
	v_mfma_f32_16x16x32_bf16 v[74:77], v[146:149], v[216:219], v[74:77]
	s_setprio 0
	s_setprio 1
	v_mfma_f32_16x16x32_bf16 v[122:125], v[150:153], v[170:173], v[122:125]
	v_mfma_f32_16x16x32_bf16 v[116:119], v[162:165], v[170:173], v[118:121]
	v_mfma_f32_16x16x32_bf16 v[102:105], v[150:153], v[178:181], v[102:105]
	v_mfma_f32_16x16x32_bf16 v[98:101], v[162:165], v[178:181], v[98:101]
	v_mfma_f32_16x16x32_bf16 v[86:89], v[150:153], v[186:189], v[86:89]
	v_mfma_f32_16x16x32_bf16 v[82:85], v[162:165], v[186:189], v[82:85]
	v_mfma_f32_16x16x32_bf16 v[70:73], v[150:153], v[212:215], v[70:73]
	v_mfma_f32_16x16x32_bf16 v[66:69], v[162:165], v[212:215], v[66:69]
	v_mfma_f32_16x16x32_bf16 v[122:125], v[154:157], v[174:177], v[122:125]
	v_mfma_f32_16x16x32_bf16 v[116:119], v[166:169], v[174:177], v[116:119]
	v_mfma_f32_16x16x32_bf16 v[102:105], v[154:157], v[182:185], v[102:105]
	v_mfma_f32_16x16x32_bf16 v[98:101], v[166:169], v[182:185], v[98:101]
	v_mfma_f32_16x16x32_bf16 v[86:89], v[154:157], v[190:193], v[86:89]
	v_mfma_f32_16x16x32_bf16 v[82:85], v[166:169], v[190:193], v[82:85]
	s_setprio 2
	s_barrier
	v_mfma_f32_16x16x32_bf16 v[70:73], v[154:157], v[216:219], v[70:73]
	v_mfma_f32_16x16x32_bf16 v[66:69], v[166:169], v[216:219], v[66:69]
	s_setprio 0
	s_nop 0
	ds_read_b128 v[170:173], v203 offset:16384
	ds_read_b128 v[174:177], v203 offset:17408
	ds_read_b128 v[178:181], v203 offset:18432
	ds_read_b128 v[182:185], v203 offset:19456
	ds_read_b128 v[186:189], v203 offset:20480
	ds_read_b128 v[190:193], v203 offset:21504
	ds_read_b128 v[212:215], v203 offset:22528
	ds_read_b128 v[216:219], v203 offset:23552
	s_mov_b32 m0, s13
	s_nop 0
	global_load_lds_dwordx4 v195, s[10:11]
	s_add_u32 m0, s13, 0x2000
	s_nop 0
	global_load_lds_dwordx4 v197, s[10:11]
	s_add_u32 s50, s10, 0x4000
	s_addc_u32 s51, s11, 0
	s_mov_b32 m0, s57
	s_nop 0
	global_load_lds_dwordx4 v195, s[50:51]
	s_add_u32 m0, s57, 0x2000
	s_nop 0
	global_load_lds_dwordx4 v197, s[50:51]
	s_nop 0
	s_mov_b32 m0, s56
	s_nop 0
	global_load_lds_dwordx4 v195, s[46:47]
	s_add_u32 m0, s56, 0x2000
	s_nop 0
	global_load_lds_dwordx4 v197, s[46:47]
	s_waitcnt vmcnt(8)
	s_waitcnt lgkmcnt(0)
	s_setprio 1
	s_barrier
	v_mfma_f32_16x16x32_bf16 v[62:65], v[134:137], v[170:173], v[62:65]
	v_mfma_f32_16x16x32_bf16 v[62:65], v[138:141], v[174:177], v[62:65]
	s_waitcnt lgkmcnt(5)
	s_setprio 0
	s_setprio 1
	v_mfma_f32_16x16x32_bf16 v[46:49], v[134:137], v[178:181], v[46:49]
	v_mfma_f32_16x16x32_bf16 v[46:49], v[138:141], v[182:185], v[46:49]
	s_waitcnt lgkmcnt(3)
	s_setprio 0
	s_setprio 1
	v_mfma_f32_16x16x32_bf16 v[30:33], v[134:137], v[186:189], v[30:33]
	v_mfma_f32_16x16x32_bf16 v[30:33], v[138:141], v[190:193], v[30:33]
	s_waitcnt lgkmcnt(1)
	s_setprio 0
	s_setprio 1
	v_mfma_f32_16x16x32_bf16 v[14:17], v[134:137], v[212:215], v[14:17]
	v_mfma_f32_16x16x32_bf16 v[14:17], v[138:141], v[216:219], v[14:17]
	s_setprio 0
	s_setprio 1
	v_mfma_f32_16x16x32_bf16 v[58:61], v[142:145], v[170:173], v[58:61]
	v_mfma_f32_16x16x32_bf16 v[58:61], v[146:149], v[174:177], v[58:61]
	s_setprio 0
	s_setprio 1
	v_mfma_f32_16x16x32_bf16 v[42:45], v[142:145], v[178:181], v[42:45]
	v_mfma_f32_16x16x32_bf16 v[42:45], v[146:149], v[182:185], v[42:45]
	s_setprio 0
	s_setprio 1
	v_mfma_f32_16x16x32_bf16 v[26:29], v[142:145], v[186:189], v[26:29]
	v_mfma_f32_16x16x32_bf16 v[26:29], v[146:149], v[190:193], v[26:29]
	s_waitcnt lgkmcnt(0)
	s_setprio 0
	s_setprio 1
	v_mfma_f32_16x16x32_bf16 v[10:13], v[142:145], v[212:215], v[10:13]
	v_mfma_f32_16x16x32_bf16 v[10:13], v[146:149], v[216:219], v[10:13]
	s_setprio 0
	s_setprio 1
	v_mfma_f32_16x16x32_bf16 v[54:57], v[150:153], v[170:173], v[54:57]
	v_mfma_f32_16x16x32_bf16 v[54:57], v[154:157], v[174:177], v[54:57]
	s_setprio 0
	s_setprio 1
	v_mfma_f32_16x16x32_bf16 v[38:41], v[150:153], v[178:181], v[38:41]
	v_mfma_f32_16x16x32_bf16 v[38:41], v[154:157], v[182:185], v[38:41]
	s_setprio 0
	s_setprio 1
	v_mfma_f32_16x16x32_bf16 v[22:25], v[150:153], v[186:189], v[22:25]
	v_mfma_f32_16x16x32_bf16 v[22:25], v[154:157], v[190:193], v[22:25]
	s_setprio 0
	s_setprio 1
	v_mfma_f32_16x16x32_bf16 v[6:9], v[150:153], v[212:215], v[6:9]
	v_mfma_f32_16x16x32_bf16 v[6:9], v[154:157], v[216:219], v[6:9]
	s_setprio 0
	s_setprio 1
	v_mfma_f32_16x16x32_bf16 v[50:53], v[162:165], v[170:173], v[50:53]
	v_mfma_f32_16x16x32_bf16 v[50:53], v[166:169], v[174:177], v[50:53]
	s_setprio 0
	s_setprio 1
	v_mfma_f32_16x16x32_bf16 v[34:37], v[162:165], v[178:181], v[34:37]
	v_mfma_f32_16x16x32_bf16 v[34:37], v[166:169], v[182:185], v[34:37]
	s_setprio 0
	s_setprio 1
	v_mfma_f32_16x16x32_bf16 v[18:21], v[162:165], v[186:189], v[18:21]
	v_mfma_f32_16x16x32_bf16 v[18:21], v[166:169], v[190:193], v[18:21]
	s_setprio 2
	s_barrier
	v_mfma_f32_16x16x32_bf16 v[2:5], v[162:165], v[212:215], v[2:5]
	v_mfma_f32_16x16x32_bf16 v[2:5], v[166:169], v[216:219], v[2:5]
	s_setprio 0
	s_nop 0
	ds_read_b128 v[134:137], v204
	ds_read_b128 v[138:141], v204 offset:1024
	ds_read_b128 v[142:145], v204 offset:2048
	ds_read_b128 v[146:149], v204 offset:3072
	ds_read_b128 v[150:153], v205
	ds_read_b128 v[154:157], v205 offset:1024
	ds_read_b128 v[162:165], v205 offset:2048
	ds_read_b128 v[166:169], v205 offset:3072
	ds_read_b128 v[170:173], v203 offset:32768
	ds_read_b128 v[174:177], v203 offset:33792
	ds_read_b128 v[178:181], v203 offset:34816
	ds_read_b128 v[182:185], v203 offset:35840
	ds_read_b128 v[186:189], v203 offset:36864
	ds_read_b128 v[190:193], v203 offset:37888
	ds_read_b128 v[212:215], v203 offset:38912
	ds_read_b128 v[216:219], v203 offset:39936
	s_add_u32 s46, s46, 0x4000
	s_addc_u32 s47, s47, 0
	s_mov_b32 m0, s58
	s_nop 0
	global_load_lds_dwordx4 v195, s[46:47]
	s_add_u32 m0, s58, 0x2000
	s_nop 0
	global_load_lds_dwordx4 v197, s[46:47]
	s_waitcnt vmcnt(8)
	s_waitcnt lgkmcnt(0)
	s_setprio 1
	s_barrier
	v_mfma_f32_16x16x32_bf16 v[130:133], v[134:137], v[170:173], v[130:133]
	v_mfma_f32_16x16x32_bf16 v[126:129], v[142:145], v[170:173], v[126:129]
	s_waitcnt lgkmcnt(5)
	v_mfma_f32_16x16x32_bf16 v[110:113], v[134:137], v[178:181], v[110:113]
	v_mfma_f32_16x16x32_bf16 v[106:109], v[142:145], v[178:181], v[106:109]
	s_waitcnt lgkmcnt(3)
	v_mfma_f32_16x16x32_bf16 v[94:97], v[134:137], v[186:189], v[94:97]
	v_mfma_f32_16x16x32_bf16 v[90:93], v[142:145], v[186:189], v[90:93]
	s_waitcnt lgkmcnt(1)
	v_mfma_f32_16x16x32_bf16 v[78:81], v[134:137], v[212:215], v[78:81]
	v_mfma_f32_16x16x32_bf16 v[74:77], v[142:145], v[212:215], v[74:77]
	v_mfma_f32_16x16x32_bf16 v[130:133], v[138:141], v[174:177], v[130:133]
	v_mfma_f32_16x16x32_bf16 v[126:129], v[146:149], v[174:177], v[126:129]
	v_mfma_f32_16x16x32_bf16 v[110:113], v[138:141], v[182:185], v[110:113]
	v_mfma_f32_16x16x32_bf16 v[106:109], v[146:149], v[182:185], v[106:109]
	v_mfma_f32_16x16x32_bf16 v[94:97], v[138:141], v[190:193], v[94:97]
	v_mfma_f32_16x16x32_bf16 v[90:93], v[146:149], v[190:193], v[90:93]
	s_waitcnt lgkmcnt(0)
	v_mfma_f32_16x16x32_bf16 v[78:81], v[138:141], v[216:219], v[78:81]
	v_mfma_f32_16x16x32_bf16 v[74:77], v[146:149], v[216:219], v[74:77]
	s_setprio 0
	s_setprio 1
	v_mfma_f32_16x16x32_bf16 v[120:123], v[150:153], v[170:173], v[122:125]
	v_mfma_f32_16x16x32_bf16 v[116:119], v[162:165], v[170:173], v[116:119]
	v_mfma_f32_16x16x32_bf16 v[102:105], v[150:153], v[178:181], v[102:105]
	v_mfma_f32_16x16x32_bf16 v[98:101], v[162:165], v[178:181], v[98:101]
	v_mfma_f32_16x16x32_bf16 v[86:89], v[150:153], v[186:189], v[86:89]
	v_mfma_f32_16x16x32_bf16 v[82:85], v[162:165], v[186:189], v[82:85]
	v_mfma_f32_16x16x32_bf16 v[70:73], v[150:153], v[212:215], v[70:73]
	v_mfma_f32_16x16x32_bf16 v[66:69], v[162:165], v[212:215], v[66:69]
	v_mfma_f32_16x16x32_bf16 v[122:125], v[154:157], v[174:177], v[120:123]
	v_mfma_f32_16x16x32_bf16 v[118:121], v[166:169], v[174:177], v[116:119]
	v_mfma_f32_16x16x32_bf16 v[102:105], v[154:157], v[182:185], v[102:105]
	v_mfma_f32_16x16x32_bf16 v[98:101], v[166:169], v[182:185], v[98:101]
	v_mfma_f32_16x16x32_bf16 v[86:89], v[154:157], v[190:193], v[86:89]
	v_mfma_f32_16x16x32_bf16 v[82:85], v[166:169], v[190:193], v[82:85]
	s_setprio 2
	s_barrier
	v_mfma_f32_16x16x32_bf16 v[70:73], v[154:157], v[216:219], v[70:73]
	v_mfma_f32_16x16x32_bf16 v[66:69], v[166:169], v[216:219], v[66:69]
	s_setprio 0
	s_nop 0
	ds_read_b128 v[170:173], v203 offset:49152
	ds_read_b128 v[174:177], v203 offset:50176
	ds_read_b128 v[178:181], v203 offset:51200
	ds_read_b128 v[182:185], v203 offset:52224
	ds_read_b128 v[186:189], v203 offset:53248
	ds_read_b128 v[190:193], v203 offset:54272
	ds_read_b128 v[212:215], v203 offset:55296
	ds_read_b128 v[216:219], v203 offset:56320
	s_mov_b32 m0, s62
	s_nop 0
	global_load_lds_dwordx4 v195, s[44:45]
	s_add_u32 m0, s62, 0x2000
	s_nop 0
	global_load_lds_dwordx4 v197, s[44:45]
	s_add_u32 s10, s10, 0xc000
	s_addc_u32 s11, s11, 0
	s_mov_b32 m0, s64
	s_nop 0
	global_load_lds_dwordx4 v195, s[10:11]
	s_add_u32 m0, s64, 0x2000
	s_nop 0
	global_load_lds_dwordx4 v197, s[10:11]
	s_nop 0
	s_mov_b32 m0, s63
	s_nop 0
	global_load_lds_dwordx4 v195, s[42:43]
	s_add_u32 m0, s63, 0x2000
	s_nop 0
	global_load_lds_dwordx4 v197, s[42:43]
	s_waitcnt vmcnt(8)
	s_waitcnt lgkmcnt(0)
	s_setprio 1
	s_barrier
	v_mfma_f32_16x16x32_bf16 v[62:65], v[134:137], v[170:173], v[62:65]
	v_mfma_f32_16x16x32_bf16 v[62:65], v[138:141], v[174:177], v[62:65]
	s_waitcnt lgkmcnt(5)
	s_setprio 0
	s_setprio 1
	v_mfma_f32_16x16x32_bf16 v[46:49], v[134:137], v[178:181], v[46:49]
	v_mfma_f32_16x16x32_bf16 v[46:49], v[138:141], v[182:185], v[46:49]
	s_waitcnt lgkmcnt(3)
	s_setprio 0
	s_setprio 1
	v_mfma_f32_16x16x32_bf16 v[30:33], v[134:137], v[186:189], v[30:33]
	v_mfma_f32_16x16x32_bf16 v[30:33], v[138:141], v[190:193], v[30:33]
	s_waitcnt lgkmcnt(1)
	s_setprio 0
	s_setprio 1
	v_mfma_f32_16x16x32_bf16 v[14:17], v[134:137], v[212:215], v[14:17]
	v_mfma_f32_16x16x32_bf16 v[14:17], v[138:141], v[216:219], v[14:17]
	s_setprio 0
	s_setprio 1
	v_mfma_f32_16x16x32_bf16 v[58:61], v[142:145], v[170:173], v[58:61]
	v_mfma_f32_16x16x32_bf16 v[58:61], v[146:149], v[174:177], v[58:61]
	s_setprio 0
	s_setprio 1
	v_mfma_f32_16x16x32_bf16 v[42:45], v[142:145], v[178:181], v[42:45]
	v_mfma_f32_16x16x32_bf16 v[42:45], v[146:149], v[182:185], v[42:45]
	s_setprio 0
	s_setprio 1
	v_mfma_f32_16x16x32_bf16 v[26:29], v[142:145], v[186:189], v[26:29]
	v_mfma_f32_16x16x32_bf16 v[26:29], v[146:149], v[190:193], v[26:29]
	s_waitcnt lgkmcnt(0)
	s_setprio 0
	s_setprio 1
	v_mfma_f32_16x16x32_bf16 v[10:13], v[142:145], v[212:215], v[10:13]
	v_mfma_f32_16x16x32_bf16 v[10:13], v[146:149], v[216:219], v[10:13]
	s_setprio 0
	s_setprio 1
	v_mfma_f32_16x16x32_bf16 v[54:57], v[150:153], v[170:173], v[54:57]
	v_mfma_f32_16x16x32_bf16 v[54:57], v[154:157], v[174:177], v[54:57]
	s_setprio 0
	s_setprio 1
	v_mfma_f32_16x16x32_bf16 v[38:41], v[150:153], v[178:181], v[38:41]
	v_mfma_f32_16x16x32_bf16 v[38:41], v[154:157], v[182:185], v[38:41]
	s_setprio 0
	s_setprio 1
	v_mfma_f32_16x16x32_bf16 v[22:25], v[150:153], v[186:189], v[22:25]
	v_mfma_f32_16x16x32_bf16 v[22:25], v[154:157], v[190:193], v[22:25]
	s_setprio 0
	s_setprio 1
	v_mfma_f32_16x16x32_bf16 v[6:9], v[150:153], v[212:215], v[6:9]
	v_mfma_f32_16x16x32_bf16 v[6:9], v[154:157], v[216:219], v[6:9]
	s_setprio 0
	s_setprio 1
	v_mfma_f32_16x16x32_bf16 v[50:53], v[162:165], v[170:173], v[50:53]
	v_mfma_f32_16x16x32_bf16 v[50:53], v[166:169], v[174:177], v[50:53]
	s_setprio 0
	s_setprio 1
	v_mfma_f32_16x16x32_bf16 v[34:37], v[162:165], v[178:181], v[34:37]
	v_mfma_f32_16x16x32_bf16 v[34:37], v[166:169], v[182:185], v[34:37]
	s_setprio 0
	s_setprio 1
	v_mfma_f32_16x16x32_bf16 v[18:21], v[162:165], v[186:189], v[18:21]
	v_mfma_f32_16x16x32_bf16 v[18:21], v[166:169], v[190:193], v[18:21]
	s_setprio 2
	s_barrier
	v_mfma_f32_16x16x32_bf16 v[2:5], v[162:165], v[212:215], v[2:5]
	v_mfma_f32_16x16x32_bf16 v[2:5], v[166:169], v[216:219], v[2:5]
	s_setprio 0
	s_nop 0
	s_add_i32 s49, s49, 2
	s_add_u32 s6, s6, 0x10000
	s_addc_u32 s7, s7, 0
	s_cmp_gt_u32 s49, 13
	v_mov_b32_e32 v115, v114
	s_cbranch_scc1 .LBB0_1922

.LBB0_2120:
	s_add_u32 s56, s52, 0x10000
	s_addc_u32 s57, s53, 0
	s_and_b64 s[52:53], s[50:51], exec
	s_cselect_b32 s53, s57, s43
	s_cselect_b32 s52, s56, s88
	s_add_u32 s15, s18, s15
	s_addc_u32 s56, s19, 0
	s_add_u32 s15, s15, 0x10000
	s_waitcnt vmcnt(8)
	s_addc_u32 s56, s56, 0
	s_waitcnt lgkmcnt(0)
	s_and_b64 s[50:51], s[50:51], exec
	s_cselect_b32 s51, s56, s41
	s_cselect_b32 s50, s15, s89
	s_setprio 1
	s_barrier
	v_mfma_f32_16x16x32_bf16 v[126:129], v[146:149], v[186:189], v[126:129]
	v_mfma_f32_16x16x32_bf16 v[126:129], v[150:153], v[190:193], v[126:129]
	s_waitcnt lgkmcnt(5)
	s_setprio 0
	s_setprio 1
	v_mfma_f32_16x16x32_bf16 v[118:121], v[146:149], v[178:181], v[118:121]
	v_mfma_f32_16x16x32_bf16 v[118:121], v[150:153], v[182:185], v[118:121]
	s_waitcnt lgkmcnt(3)
	s_setprio 0
	s_setprio 1
	v_mfma_f32_16x16x32_bf16 v[110:113], v[146:149], v[170:173], v[110:113]
	v_mfma_f32_16x16x32_bf16 v[110:113], v[150:153], v[174:177], v[110:113]
	s_waitcnt lgkmcnt(1)
	s_setprio 0
	s_setprio 1
	v_mfma_f32_16x16x32_bf16 v[102:105], v[146:149], v[162:165], v[102:105]
	v_mfma_f32_16x16x32_bf16 v[102:105], v[150:153], v[166:169], v[102:105]
	s_setprio 0
	s_setprio 1
	v_mfma_f32_16x16x32_bf16 v[122:125], v[154:157], v[186:189], v[122:125]
	v_mfma_f32_16x16x32_bf16 v[122:125], v[158:161], v[190:193], v[122:125]
	s_setprio 0
	s_setprio 1
	v_mfma_f32_16x16x32_bf16 v[114:117], v[154:157], v[178:181], v[114:117]
	v_mfma_f32_16x16x32_bf16 v[114:117], v[158:161], v[182:185], v[114:117]
	s_setprio 0
	s_setprio 1
	v_mfma_f32_16x16x32_bf16 v[106:109], v[154:157], v[170:173], v[106:109]
	v_mfma_f32_16x16x32_bf16 v[106:109], v[158:161], v[174:177], v[106:109]
	s_waitcnt lgkmcnt(0)
	s_setprio 0
	s_setprio 1
	v_mfma_f32_16x16x32_bf16 v[98:101], v[154:157], v[162:165], v[98:101]
	v_mfma_f32_16x16x32_bf16 v[98:101], v[158:161], v[166:169], v[98:101]
	s_setprio 0
	s_setprio 1
	v_mfma_f32_16x16x32_bf16 v[94:97], v[130:133], v[186:189], v[94:97]
	v_mfma_f32_16x16x32_bf16 v[94:97], v[134:137], v[190:193], v[94:97]
	s_setprio 0
	s_setprio 1
	v_mfma_f32_16x16x32_bf16 v[86:89], v[130:133], v[178:181], v[86:89]
	v_mfma_f32_16x16x32_bf16 v[86:89], v[134:137], v[182:185], v[86:89]
	s_setprio 0
	s_setprio 1
	v_mfma_f32_16x16x32_bf16 v[78:81], v[130:133], v[170:173], v[78:81]
	v_mfma_f32_16x16x32_bf16 v[78:81], v[134:137], v[174:177], v[78:81]
	s_setprio 0
	s_setprio 1
	v_mfma_f32_16x16x32_bf16 v[70:73], v[130:133], v[162:165], v[70:73]
	v_mfma_f32_16x16x32_bf16 v[70:73], v[134:137], v[166:169], v[70:73]
	s_setprio 0
	s_setprio 1
	v_mfma_f32_16x16x32_bf16 v[90:93], v[138:141], v[186:189], v[90:93]
	v_mfma_f32_16x16x32_bf16 v[90:93], v[142:145], v[190:193], v[90:93]
	s_setprio 0
	s_setprio 1
	v_mfma_f32_16x16x32_bf16 v[82:85], v[138:141], v[178:181], v[82:85]
	v_mfma_f32_16x16x32_bf16 v[82:85], v[142:145], v[182:185], v[82:85]
	s_setprio 0
	s_setprio 1
	v_mfma_f32_16x16x32_bf16 v[74:77], v[138:141], v[170:173], v[74:77]
	v_mfma_f32_16x16x32_bf16 v[74:77], v[142:145], v[174:177], v[74:77]
	s_setprio 2
	s_barrier
	v_mfma_f32_16x16x32_bf16 v[66:69], v[138:141], v[162:165], v[66:69]
	v_mfma_f32_16x16x32_bf16 v[66:69], v[142:145], v[166:169], v[66:69]
	s_setprio 0
	s_nop 0
	ds_read_b128 v[186:189], v207 offset:16384
	ds_read_b128 v[190:193], v207 offset:17408
	ds_read_b128 v[178:181], v207 offset:18432
	ds_read_b128 v[182:185], v207 offset:19456
	ds_read_b128 v[170:173], v207 offset:20480
	ds_read_b128 v[174:177], v207 offset:21504
	ds_read_b128 v[162:165], v207 offset:22528
	ds_read_b128 v[166:169], v207 offset:23552
	s_mov_b32 m0, s62
	s_nop 0
	global_load_lds_dwordx4 v195, s[50:51]
	s_add_u32 m0, s62, 0x2000
	s_nop 0
	global_load_lds_dwordx4 v197, s[50:51]
	s_add_u32 s56, s50, 0x4000
	s_addc_u32 s57, s51, 0
	s_mov_b32 m0, s63
	s_nop 0
	global_load_lds_dwordx4 v195, s[56:57]
	s_add_u32 m0, s63, 0x2000
	s_nop 0
	global_load_lds_dwordx4 v197, s[56:57]
	s_andn2_b64 vcc, exec, s[54:55]
	s_mov_b32 m0, s61
	s_nop 0
	global_load_lds_dwordx4 v195, s[52:53]
	s_add_u32 m0, s61, 0x2000
	s_nop 0
	global_load_lds_dwordx4 v197, s[52:53]
	s_cbranch_vccnz .LBB0_2122
	v_mov_b32_e32 v2, 0
	v_mov_b32_e32 v3, v2
	v_mov_b32_e32 v4, v2
	v_mov_b32_e32 v5, v2
	v_mov_b32_e32 v6, v2
	v_mov_b32_e32 v7, v2
	v_mov_b32_e32 v8, v2
	v_mov_b32_e32 v9, v2
	v_mov_b32_e32 v10, v2
	v_mov_b32_e32 v11, v2
	v_mov_b32_e32 v12, v2
	v_mov_b32_e32 v13, v2
	v_mov_b32_e32 v14, v2
	v_mov_b32_e32 v15, v2
	v_mov_b32_e32 v16, v2
	v_mov_b32_e32 v17, v2
	v_mov_b32_e32 v18, v2
	v_mov_b32_e32 v19, v2
	v_mov_b32_e32 v20, v2
	v_mov_b32_e32 v21, v2
	v_mov_b32_e32 v22, v2
	v_mov_b32_e32 v23, v2
	v_mov_b32_e32 v24, v2
	v_mov_b32_e32 v25, v2
	v_mov_b32_e32 v26, v2
	v_mov_b32_e32 v27, v2
	v_mov_b32_e32 v28, v2
	v_mov_b32_e32 v29, v2
	v_mov_b32_e32 v30, v2
	v_mov_b32_e32 v31, v2
	v_mov_b32_e32 v32, v2
	v_mov_b32_e32 v33, v2
	v_mov_b32_e32 v34, v2
	v_mov_b32_e32 v35, v2
	v_mov_b32_e32 v36, v2
	v_mov_b32_e32 v37, v2
	v_mov_b32_e32 v38, v2
	v_mov_b32_e32 v39, v2
	v_mov_b32_e32 v40, v2
	v_mov_b32_e32 v41, v2
	v_mov_b32_e32 v42, v2
	v_mov_b32_e32 v43, v2
	v_mov_b32_e32 v44, v2
	v_mov_b32_e32 v45, v2
	v_mov_b32_e32 v46, v2
	v_mov_b32_e32 v47, v2
	v_mov_b32_e32 v48, v2
	v_mov_b32_e32 v49, v2
	v_mov_b32_e32 v50, v2
	v_mov_b32_e32 v51, v2
	v_mov_b32_e32 v52, v2
	v_mov_b32_e32 v53, v2
	v_mov_b32_e32 v54, v2
	v_mov_b32_e32 v55, v2
	v_mov_b32_e32 v56, v2
	v_mov_b32_e32 v57, v2
	v_mov_b32_e32 v58, v2
	v_mov_b32_e32 v59, v2
	v_mov_b32_e32 v60, v2
	v_mov_b32_e32 v61, v2
	v_mov_b32_e32 v62, v2
	v_mov_b32_e32 v63, v2
	v_mov_b32_e32 v64, v2
	v_mov_b32_e32 v65, v2
.LBB0_2122:
	s_waitcnt vmcnt(8)
	s_add_u32 s54, s52, 0x8000
	s_waitcnt lgkmcnt(0)
	s_addc_u32 s55, s53, 0
	s_add_u32 s56, s50, 0x8000
	s_addc_u32 s57, s51, 0
	s_setprio 1
	s_barrier
	v_mfma_f32_16x16x32_bf16 v[62:65], v[146:149], v[186:189], v[62:65]
	v_mfma_f32_16x16x32_bf16 v[62:65], v[150:153], v[190:193], v[62:65]
	s_waitcnt lgkmcnt(5)
	s_setprio 0
	s_setprio 1
	v_mfma_f32_16x16x32_bf16 v[54:57], v[146:149], v[178:181], v[54:57]
	v_mfma_f32_16x16x32_bf16 v[54:57], v[150:153], v[182:185], v[54:57]
	s_waitcnt lgkmcnt(3)
	s_setprio 0
	s_setprio 1
	v_mfma_f32_16x16x32_bf16 v[46:49], v[146:149], v[170:173], v[46:49]
	v_mfma_f32_16x16x32_bf16 v[46:49], v[150:153], v[174:177], v[46:49]
	s_waitcnt lgkmcnt(1)
	s_setprio 0
	s_setprio 1
	v_mfma_f32_16x16x32_bf16 v[38:41], v[146:149], v[162:165], v[38:41]
	v_mfma_f32_16x16x32_bf16 v[38:41], v[150:153], v[166:169], v[38:41]
	s_setprio 0
	s_setprio 1
	v_mfma_f32_16x16x32_bf16 v[58:61], v[154:157], v[186:189], v[58:61]
	v_mfma_f32_16x16x32_bf16 v[58:61], v[158:161], v[190:193], v[58:61]
	s_setprio 0
	s_setprio 1
	v_mfma_f32_16x16x32_bf16 v[50:53], v[154:157], v[178:181], v[50:53]
	v_mfma_f32_16x16x32_bf16 v[50:53], v[158:161], v[182:185], v[50:53]
	s_setprio 0
	s_setprio 1
	v_mfma_f32_16x16x32_bf16 v[42:45], v[154:157], v[170:173], v[42:45]
	v_mfma_f32_16x16x32_bf16 v[42:45], v[158:161], v[174:177], v[42:45]
	s_waitcnt lgkmcnt(0)
	s_setprio 0
	s_setprio 1
	v_mfma_f32_16x16x32_bf16 v[34:37], v[154:157], v[162:165], v[34:37]
	v_mfma_f32_16x16x32_bf16 v[34:37], v[158:161], v[166:169], v[34:37]
	s_setprio 0
	s_setprio 1
	v_mfma_f32_16x16x32_bf16 v[30:33], v[130:133], v[186:189], v[30:33]
	v_mfma_f32_16x16x32_bf16 v[30:33], v[134:137], v[190:193], v[30:33]
	s_setprio 0
	s_setprio 1
	v_mfma_f32_16x16x32_bf16 v[22:25], v[130:133], v[178:181], v[22:25]
	v_mfma_f32_16x16x32_bf16 v[22:25], v[134:137], v[182:185], v[22:25]
	s_setprio 0
	s_setprio 1
	v_mfma_f32_16x16x32_bf16 v[14:17], v[130:133], v[170:173], v[14:17]
	v_mfma_f32_16x16x32_bf16 v[14:17], v[134:137], v[174:177], v[14:17]
	s_setprio 0
	s_setprio 1
	v_mfma_f32_16x16x32_bf16 v[6:9], v[130:133], v[162:165], v[6:9]
	v_mfma_f32_16x16x32_bf16 v[6:9], v[134:137], v[166:169], v[6:9]
	s_setprio 0
	s_setprio 1
	v_mfma_f32_16x16x32_bf16 v[26:29], v[138:141], v[186:189], v[26:29]
	v_mfma_f32_16x16x32_bf16 v[26:29], v[142:145], v[190:193], v[26:29]
	s_setprio 0
	s_setprio 1
	v_mfma_f32_16x16x32_bf16 v[18:21], v[138:141], v[178:181], v[18:21]
	v_mfma_f32_16x16x32_bf16 v[18:21], v[142:145], v[182:185], v[18:21]
	s_setprio 0
	s_setprio 1
	v_mfma_f32_16x16x32_bf16 v[10:13], v[138:141], v[170:173], v[10:13]
	v_mfma_f32_16x16x32_bf16 v[10:13], v[142:145], v[174:177], v[10:13]
	s_setprio 2
	s_barrier
	v_mfma_f32_16x16x32_bf16 v[2:5], v[138:141], v[162:165], v[2:5]
	v_mfma_f32_16x16x32_bf16 v[2:5], v[142:145], v[166:169], v[2:5]
	s_setprio 0
	s_nop 0
	v_add_u32_e32 v142, 0x18000, v206
	v_add_u32_e32 v158, 0x1c000, v206
	ds_read_b128 v[130:133], v142
	ds_read_b128 v[134:137], v142 offset:1024
	ds_read_b128 v[138:141], v142 offset:2048
	ds_read_b128 v[142:145], v142 offset:3072
	ds_read_b128 v[146:149], v158
	ds_read_b128 v[150:153], v158 offset:1024
	ds_read_b128 v[154:157], v158 offset:2048
	ds_read_b128 v[158:161], v158 offset:3072
	ds_read_b128 v[162:165], v207 offset:32768
	ds_read_b128 v[166:169], v207 offset:33792
	ds_read_b128 v[170:173], v207 offset:34816
	ds_read_b128 v[174:177], v207 offset:35840
	ds_read_b128 v[178:181], v207 offset:36864
	ds_read_b128 v[182:185], v207 offset:37888
	ds_read_b128 v[186:189], v207 offset:38912
	ds_read_b128 v[190:193], v207 offset:39936
	s_add_u32 s52, s52, 0x4000
	s_addc_u32 s53, s53, 0
	s_mov_b32 m0, s64
	s_nop 0
	global_load_lds_dwordx4 v195, s[52:53]
	s_add_u32 m0, s64, 0x2000
	s_nop 0
	global_load_lds_dwordx4 v197, s[52:53]
	s_waitcnt vmcnt(8)
	s_waitcnt lgkmcnt(0)
	s_setprio 1
	s_barrier
	v_mfma_f32_16x16x32_bf16 v[126:129], v[130:133], v[162:165], v[126:129]
	v_mfma_f32_16x16x32_bf16 v[126:129], v[134:137], v[166:169], v[126:129]
	s_waitcnt lgkmcnt(5)
	s_setprio 0
	s_setprio 1
	v_mfma_f32_16x16x32_bf16 v[118:121], v[130:133], v[170:173], v[118:121]
	v_mfma_f32_16x16x32_bf16 v[118:121], v[134:137], v[174:177], v[118:121]
	s_waitcnt lgkmcnt(3)
	s_setprio 0
	s_setprio 1
	v_mfma_f32_16x16x32_bf16 v[110:113], v[130:133], v[178:181], v[110:113]
	v_mfma_f32_16x16x32_bf16 v[110:113], v[134:137], v[182:185], v[110:113]
	s_waitcnt lgkmcnt(1)
	s_setprio 0
	s_setprio 1
	v_mfma_f32_16x16x32_bf16 v[102:105], v[130:133], v[186:189], v[102:105]
	v_mfma_f32_16x16x32_bf16 v[102:105], v[134:137], v[190:193], v[102:105]
	s_setprio 0
	s_setprio 1
	v_mfma_f32_16x16x32_bf16 v[122:125], v[138:141], v[162:165], v[122:125]
	v_mfma_f32_16x16x32_bf16 v[122:125], v[142:145], v[166:169], v[122:125]
	s_setprio 0
	s_setprio 1
	v_mfma_f32_16x16x32_bf16 v[114:117], v[138:141], v[170:173], v[114:117]
	v_mfma_f32_16x16x32_bf16 v[114:117], v[142:145], v[174:177], v[114:117]
	s_setprio 0
	s_setprio 1
	v_mfma_f32_16x16x32_bf16 v[106:109], v[138:141], v[178:181], v[106:109]
	v_mfma_f32_16x16x32_bf16 v[106:109], v[142:145], v[182:185], v[106:109]
	s_waitcnt lgkmcnt(0)
	s_setprio 0
	s_setprio 1
	v_mfma_f32_16x16x32_bf16 v[98:101], v[138:141], v[186:189], v[98:101]
	v_mfma_f32_16x16x32_bf16 v[98:101], v[142:145], v[190:193], v[98:101]
	s_setprio 0
	s_setprio 1
	v_mfma_f32_16x16x32_bf16 v[94:97], v[146:149], v[162:165], v[94:97]
	v_mfma_f32_16x16x32_bf16 v[94:97], v[150:153], v[166:169], v[94:97]
	s_setprio 0
	s_setprio 1
	v_mfma_f32_16x16x32_bf16 v[86:89], v[146:149], v[170:173], v[86:89]
	v_mfma_f32_16x16x32_bf16 v[86:89], v[150:153], v[174:177], v[86:89]
	s_setprio 0
	s_setprio 1
	v_mfma_f32_16x16x32_bf16 v[78:81], v[146:149], v[178:181], v[78:81]
	v_mfma_f32_16x16x32_bf16 v[78:81], v[150:153], v[182:185], v[78:81]
	s_setprio 0
	s_setprio 1
	v_mfma_f32_16x16x32_bf16 v[70:73], v[146:149], v[186:189], v[70:73]
	v_mfma_f32_16x16x32_bf16 v[70:73], v[150:153], v[190:193], v[70:73]
	s_setprio 0
	s_setprio 1
	v_mfma_f32_16x16x32_bf16 v[90:93], v[154:157], v[162:165], v[90:93]
	v_mfma_f32_16x16x32_bf16 v[90:93], v[158:161], v[166:169], v[90:93]
	s_setprio 0
	s_setprio 1
	v_mfma_f32_16x16x32_bf16 v[82:85], v[154:157], v[170:173], v[82:85]
	v_mfma_f32_16x16x32_bf16 v[82:85], v[158:161], v[174:177], v[82:85]
	s_setprio 0
	s_setprio 1
	v_mfma_f32_16x16x32_bf16 v[74:77], v[154:157], v[178:181], v[74:77]
	v_mfma_f32_16x16x32_bf16 v[74:77], v[158:161], v[182:185], v[74:77]
	s_setprio 2
	s_barrier
	v_mfma_f32_16x16x32_bf16 v[66:69], v[154:157], v[186:189], v[66:69]
	v_mfma_f32_16x16x32_bf16 v[66:69], v[158:161], v[190:193], v[66:69]
	s_setprio 0
	s_nop 0
	ds_read_b128 v[162:165], v207 offset:49152
	ds_read_b128 v[166:169], v207 offset:50176
	ds_read_b128 v[170:173], v207 offset:51200
	ds_read_b128 v[174:177], v207 offset:52224
	ds_read_b128 v[178:181], v207 offset:53248
	ds_read_b128 v[182:185], v207 offset:54272
	ds_read_b128 v[186:189], v207 offset:55296
	ds_read_b128 v[190:193], v207 offset:56320
	s_mov_b32 m0, s70
	s_nop 0
	global_load_lds_dwordx4 v195, s[56:57]
	s_add_u32 m0, s70, 0x2000
	s_nop 0
	global_load_lds_dwordx4 v197, s[56:57]
	s_add_u32 s50, s50, 0xc000
	s_addc_u32 s51, s51, 0
	s_mov_b32 m0, s72
	s_nop 0
	global_load_lds_dwordx4 v195, s[50:51]
	s_add_u32 m0, s72, 0x2000
	s_nop 0
	global_load_lds_dwordx4 v197, s[50:51]
	s_nop 0
	s_mov_b32 m0, s71
	s_nop 0
	global_load_lds_dwordx4 v195, s[54:55]
	s_add_u32 m0, s71, 0x2000
	s_nop 0
	global_load_lds_dwordx4 v197, s[54:55]
	s_waitcnt vmcnt(8)
	s_waitcnt lgkmcnt(0)
	s_setprio 1
	s_barrier
	v_mfma_f32_16x16x32_bf16 v[62:65], v[130:133], v[162:165], v[62:65]
	v_mfma_f32_16x16x32_bf16 v[62:65], v[134:137], v[166:169], v[62:65]
	s_waitcnt lgkmcnt(5)
	s_setprio 0
	s_setprio 1
	v_mfma_f32_16x16x32_bf16 v[54:57], v[130:133], v[170:173], v[54:57]
	v_mfma_f32_16x16x32_bf16 v[54:57], v[134:137], v[174:177], v[54:57]
	s_waitcnt lgkmcnt(3)
	s_setprio 0
	s_setprio 1
	v_mfma_f32_16x16x32_bf16 v[46:49], v[130:133], v[178:181], v[46:49]
	v_mfma_f32_16x16x32_bf16 v[46:49], v[134:137], v[182:185], v[46:49]
	s_waitcnt lgkmcnt(1)
	s_setprio 0
	s_setprio 1
	v_mfma_f32_16x16x32_bf16 v[38:41], v[130:133], v[186:189], v[38:41]
	v_mfma_f32_16x16x32_bf16 v[38:41], v[134:137], v[190:193], v[38:41]
	s_setprio 0
	s_setprio 1
	v_mfma_f32_16x16x32_bf16 v[58:61], v[138:141], v[162:165], v[58:61]
	v_mfma_f32_16x16x32_bf16 v[58:61], v[142:145], v[166:169], v[58:61]
	s_setprio 0
	s_setprio 1
	v_mfma_f32_16x16x32_bf16 v[50:53], v[138:141], v[170:173], v[50:53]
	v_mfma_f32_16x16x32_bf16 v[50:53], v[142:145], v[174:177], v[50:53]
	s_setprio 0
	s_setprio 1
	v_mfma_f32_16x16x32_bf16 v[42:45], v[138:141], v[178:181], v[42:45]
	v_mfma_f32_16x16x32_bf16 v[42:45], v[142:145], v[182:185], v[42:45]
	s_waitcnt lgkmcnt(0)
	s_setprio 0
	s_setprio 1
	v_mfma_f32_16x16x32_bf16 v[34:37], v[138:141], v[186:189], v[34:37]
	v_mfma_f32_16x16x32_bf16 v[34:37], v[142:145], v[190:193], v[34:37]
	s_setprio 0
	s_setprio 1
	v_mfma_f32_16x16x32_bf16 v[30:33], v[146:149], v[162:165], v[30:33]
	v_mfma_f32_16x16x32_bf16 v[30:33], v[150:153], v[166:169], v[30:33]
	s_setprio 0
	s_setprio 1
	v_mfma_f32_16x16x32_bf16 v[22:25], v[146:149], v[170:173], v[22:25]
	v_mfma_f32_16x16x32_bf16 v[22:25], v[150:153], v[174:177], v[22:25]
	s_setprio 0
	s_setprio 1
	v_mfma_f32_16x16x32_bf16 v[14:17], v[146:149], v[178:181], v[14:17]
	v_mfma_f32_16x16x32_bf16 v[14:17], v[150:153], v[182:185], v[14:17]
	s_setprio 0
	s_setprio 1
	v_mfma_f32_16x16x32_bf16 v[6:9], v[146:149], v[186:189], v[6:9]
	v_mfma_f32_16x16x32_bf16 v[6:9], v[150:153], v[190:193], v[6:9]
	s_setprio 0
	s_setprio 1
	v_mfma_f32_16x16x32_bf16 v[26:29], v[154:157], v[162:165], v[26:29]
	v_mfma_f32_16x16x32_bf16 v[26:29], v[158:161], v[166:169], v[26:29]
	s_setprio 0
	s_setprio 1
	v_mfma_f32_16x16x32_bf16 v[18:21], v[154:157], v[170:173], v[18:21]
	v_mfma_f32_16x16x32_bf16 v[18:21], v[158:161], v[174:177], v[18:21]
	s_setprio 0
	s_setprio 1
	v_mfma_f32_16x16x32_bf16 v[10:13], v[154:157], v[178:181], v[10:13]
	v_mfma_f32_16x16x32_bf16 v[10:13], v[158:161], v[182:185], v[10:13]
	s_setprio 2
	s_barrier
	v_mfma_f32_16x16x32_bf16 v[2:5], v[154:157], v[186:189], v[2:5]
	v_mfma_f32_16x16x32_bf16 v[2:5], v[158:161], v[190:193], v[2:5]
	s_setprio 0
	s_nop 0
	s_add_i32 s15, s90, 2
	s_cmp_gt_u32 s90, 13
	s_cbranch_scc1 .LBB0_2124
	v_mov_b32_e32 v130, v198
	s_mov_b32 s90, s15
	s_branch .LBB0_2099

.LBB0_2229:
	s_add_i32 s22, s46, 2
	s_lshl_b64 s[42:43], s[22:23], 15
	s_add_u32 s44, s2, s42
	s_addc_u32 s45, s3, s43
	s_and_b64 s[38:39], s[14:15], exec
	s_cselect_b32 s39, s45, s29
	s_cselect_b32 s38, s44, s28
	s_add_u32 s42, s16, s42
	s_waitcnt vmcnt(8)
	s_addc_u32 s43, s17, s43
	s_waitcnt lgkmcnt(0)
	s_and_b64 s[14:15], s[14:15], exec
	s_cselect_b32 s15, s43, s31
	s_cselect_b32 s14, s42, s30
	s_setprio 1
	s_barrier
	v_mfma_f32_16x16x32_bf16 v[126:129], v[146:149], v[186:189], v[126:129]
	v_mfma_f32_16x16x32_bf16 v[126:129], v[150:153], v[190:193], v[126:129]
	s_waitcnt lgkmcnt(5)
	s_setprio 0
	s_setprio 1
	v_mfma_f32_16x16x32_bf16 v[118:121], v[146:149], v[178:181], v[118:121]
	v_mfma_f32_16x16x32_bf16 v[118:121], v[150:153], v[182:185], v[118:121]
	s_waitcnt lgkmcnt(3)
	s_setprio 0
	s_setprio 1
	v_mfma_f32_16x16x32_bf16 v[110:113], v[146:149], v[170:173], v[110:113]
	v_mfma_f32_16x16x32_bf16 v[110:113], v[150:153], v[174:177], v[110:113]
	s_waitcnt lgkmcnt(1)
	s_setprio 0
	s_setprio 1
	v_mfma_f32_16x16x32_bf16 v[102:105], v[146:149], v[162:165], v[102:105]
	v_mfma_f32_16x16x32_bf16 v[102:105], v[150:153], v[166:169], v[102:105]
	s_setprio 0
	s_setprio 1
	v_mfma_f32_16x16x32_bf16 v[122:125], v[154:157], v[186:189], v[122:125]
	v_mfma_f32_16x16x32_bf16 v[122:125], v[158:161], v[190:193], v[122:125]
	s_setprio 0
	s_setprio 1
	v_mfma_f32_16x16x32_bf16 v[114:117], v[154:157], v[178:181], v[114:117]
	v_mfma_f32_16x16x32_bf16 v[114:117], v[158:161], v[182:185], v[114:117]
	s_setprio 0
	s_setprio 1
	v_mfma_f32_16x16x32_bf16 v[106:109], v[154:157], v[170:173], v[106:109]
	v_mfma_f32_16x16x32_bf16 v[106:109], v[158:161], v[174:177], v[106:109]
	s_waitcnt lgkmcnt(0)
	s_setprio 0
	s_setprio 1
	v_mfma_f32_16x16x32_bf16 v[98:101], v[154:157], v[162:165], v[98:101]
	v_mfma_f32_16x16x32_bf16 v[98:101], v[158:161], v[166:169], v[98:101]
	s_setprio 0
	s_setprio 1
	v_mfma_f32_16x16x32_bf16 v[94:97], v[130:133], v[186:189], v[94:97]
	v_mfma_f32_16x16x32_bf16 v[94:97], v[134:137], v[190:193], v[94:97]
	s_setprio 0
	s_setprio 1
	v_mfma_f32_16x16x32_bf16 v[86:89], v[130:133], v[178:181], v[86:89]
	v_mfma_f32_16x16x32_bf16 v[86:89], v[134:137], v[182:185], v[86:89]
	s_setprio 0
	s_setprio 1
	v_mfma_f32_16x16x32_bf16 v[78:81], v[130:133], v[170:173], v[78:81]
	v_mfma_f32_16x16x32_bf16 v[78:81], v[134:137], v[174:177], v[78:81]
	s_setprio 0
	s_setprio 1
	v_mfma_f32_16x16x32_bf16 v[70:73], v[130:133], v[162:165], v[70:73]
	v_mfma_f32_16x16x32_bf16 v[70:73], v[134:137], v[166:169], v[70:73]
	s_setprio 0
	s_setprio 1
	v_mfma_f32_16x16x32_bf16 v[90:93], v[138:141], v[186:189], v[90:93]
	v_mfma_f32_16x16x32_bf16 v[90:93], v[142:145], v[190:193], v[90:93]
	s_setprio 0
	s_setprio 1
	v_mfma_f32_16x16x32_bf16 v[82:85], v[138:141], v[178:181], v[82:85]
	v_mfma_f32_16x16x32_bf16 v[82:85], v[142:145], v[182:185], v[82:85]
	s_setprio 0
	s_setprio 1
	v_mfma_f32_16x16x32_bf16 v[74:77], v[138:141], v[170:173], v[74:77]
	v_mfma_f32_16x16x32_bf16 v[74:77], v[142:145], v[174:177], v[74:77]
	s_setprio 2
	s_barrier
	v_mfma_f32_16x16x32_bf16 v[66:69], v[138:141], v[162:165], v[66:69]
	v_mfma_f32_16x16x32_bf16 v[66:69], v[142:145], v[166:169], v[66:69]
	s_setprio 0
	s_nop 0
	ds_read_b128 v[186:189], v215 offset:16384
	ds_read_b128 v[190:193], v215 offset:17408
	ds_read_b128 v[178:181], v215 offset:18432
	ds_read_b128 v[182:185], v215 offset:19456
	ds_read_b128 v[170:173], v215 offset:20480
	ds_read_b128 v[174:177], v215 offset:21504
	ds_read_b128 v[162:165], v215 offset:22528
	ds_read_b128 v[166:169], v215 offset:23552
	s_mov_b32 m0, s57
	s_nop 0
	global_load_lds_dwordx4 v195, s[14:15]
	s_add_u32 m0, s57, 0x2000
	s_nop 0
	global_load_lds_dwordx4 v208, s[14:15]
	s_add_u32 s42, s14, 0x4000
	s_addc_u32 s43, s15, 0
	s_mov_b32 m0, s58
	s_nop 0
	global_load_lds_dwordx4 v195, s[42:43]
	s_add_u32 m0, s58, 0x2000
	s_nop 0
	global_load_lds_dwordx4 v208, s[42:43]
	s_andn2_b64 vcc, exec, s[40:41]
	s_mov_b32 m0, s56
	s_nop 0
	global_load_lds_dwordx4 v195, s[38:39]
	s_add_u32 m0, s56, 0x2000
	s_nop 0
	global_load_lds_dwordx4 v208, s[38:39]
	s_cbranch_vccnz .LBB0_2231
	v_mov_b32_e32 v2, 0
	v_mov_b32_e32 v3, v2
	v_mov_b32_e32 v4, v2
	v_mov_b32_e32 v5, v2
	v_mov_b32_e32 v6, v2
	v_mov_b32_e32 v7, v2
	v_mov_b32_e32 v8, v2
	v_mov_b32_e32 v9, v2
	v_mov_b32_e32 v10, v2
	v_mov_b32_e32 v11, v2
	v_mov_b32_e32 v12, v2
	v_mov_b32_e32 v13, v2
	v_mov_b32_e32 v14, v2
	v_mov_b32_e32 v15, v2
	v_mov_b32_e32 v16, v2
	v_mov_b32_e32 v17, v2
	v_mov_b32_e32 v18, v2
	v_mov_b32_e32 v19, v2
	v_mov_b32_e32 v20, v2
	v_mov_b32_e32 v21, v2
	v_mov_b32_e32 v22, v2
	v_mov_b32_e32 v23, v2
	v_mov_b32_e32 v24, v2
	v_mov_b32_e32 v25, v2
	v_mov_b32_e32 v26, v2
	v_mov_b32_e32 v27, v2
	v_mov_b32_e32 v28, v2
	v_mov_b32_e32 v29, v2
	v_mov_b32_e32 v30, v2
	v_mov_b32_e32 v31, v2
	v_mov_b32_e32 v32, v2
	v_mov_b32_e32 v33, v2
	v_mov_b32_e32 v34, v2
	v_mov_b32_e32 v35, v2
	v_mov_b32_e32 v36, v2
	v_mov_b32_e32 v37, v2
	v_mov_b32_e32 v38, v2
	v_mov_b32_e32 v39, v2
	v_mov_b32_e32 v40, v2
	v_mov_b32_e32 v41, v2
	v_mov_b32_e32 v42, v2
	v_mov_b32_e32 v43, v2
	v_mov_b32_e32 v44, v2
	v_mov_b32_e32 v45, v2
	v_mov_b32_e32 v46, v2
	v_mov_b32_e32 v47, v2
	v_mov_b32_e32 v48, v2
	v_mov_b32_e32 v49, v2
	v_mov_b32_e32 v50, v2
	v_mov_b32_e32 v51, v2
	v_mov_b32_e32 v52, v2
	v_mov_b32_e32 v53, v2
	v_mov_b32_e32 v54, v2
	v_mov_b32_e32 v55, v2
	v_mov_b32_e32 v56, v2
	v_mov_b32_e32 v57, v2
	v_mov_b32_e32 v58, v2
	v_mov_b32_e32 v59, v2
	v_mov_b32_e32 v60, v2
	v_mov_b32_e32 v61, v2
	v_mov_b32_e32 v62, v2
	v_mov_b32_e32 v63, v2
	v_mov_b32_e32 v64, v2
	v_mov_b32_e32 v65, v2
.LBB0_2231:
	s_waitcnt vmcnt(8)
	s_add_u32 s40, s38, 0x8000
	s_waitcnt lgkmcnt(0)
	s_addc_u32 s41, s39, 0
	s_add_u32 s42, s14, 0x8000
	s_addc_u32 s43, s15, 0
	s_setprio 1
	s_barrier
	v_mfma_f32_16x16x32_bf16 v[62:65], v[146:149], v[186:189], v[62:65]
	v_mfma_f32_16x16x32_bf16 v[62:65], v[150:153], v[190:193], v[62:65]
	s_waitcnt lgkmcnt(5)
	s_setprio 0
	s_setprio 1
	v_mfma_f32_16x16x32_bf16 v[54:57], v[146:149], v[178:181], v[54:57]
	v_mfma_f32_16x16x32_bf16 v[54:57], v[150:153], v[182:185], v[54:57]
	s_waitcnt lgkmcnt(3)
	s_setprio 0
	s_setprio 1
	v_mfma_f32_16x16x32_bf16 v[46:49], v[146:149], v[170:173], v[46:49]
	v_mfma_f32_16x16x32_bf16 v[46:49], v[150:153], v[174:177], v[46:49]
	s_waitcnt lgkmcnt(1)
	s_setprio 0
	s_setprio 1
	v_mfma_f32_16x16x32_bf16 v[38:41], v[146:149], v[162:165], v[38:41]
	v_mfma_f32_16x16x32_bf16 v[38:41], v[150:153], v[166:169], v[38:41]
	s_setprio 0
	s_setprio 1
	v_mfma_f32_16x16x32_bf16 v[58:61], v[154:157], v[186:189], v[58:61]
	v_mfma_f32_16x16x32_bf16 v[58:61], v[158:161], v[190:193], v[58:61]
	s_setprio 0
	s_setprio 1
	v_mfma_f32_16x16x32_bf16 v[50:53], v[154:157], v[178:181], v[50:53]
	v_mfma_f32_16x16x32_bf16 v[50:53], v[158:161], v[182:185], v[50:53]
	s_setprio 0
	s_setprio 1
	v_mfma_f32_16x16x32_bf16 v[42:45], v[154:157], v[170:173], v[42:45]
	v_mfma_f32_16x16x32_bf16 v[42:45], v[158:161], v[174:177], v[42:45]
	s_waitcnt lgkmcnt(0)
	s_setprio 0
	s_setprio 1
	v_mfma_f32_16x16x32_bf16 v[34:37], v[154:157], v[162:165], v[34:37]
	v_mfma_f32_16x16x32_bf16 v[34:37], v[158:161], v[166:169], v[34:37]
	s_setprio 0
	s_setprio 1
	v_mfma_f32_16x16x32_bf16 v[30:33], v[130:133], v[186:189], v[30:33]
	v_mfma_f32_16x16x32_bf16 v[30:33], v[134:137], v[190:193], v[30:33]
	s_setprio 0
	s_setprio 1
	v_mfma_f32_16x16x32_bf16 v[22:25], v[130:133], v[178:181], v[22:25]
	v_mfma_f32_16x16x32_bf16 v[22:25], v[134:137], v[182:185], v[22:25]
	s_setprio 0
	s_setprio 1
	v_mfma_f32_16x16x32_bf16 v[14:17], v[130:133], v[170:173], v[14:17]
	v_mfma_f32_16x16x32_bf16 v[14:17], v[134:137], v[174:177], v[14:17]
	s_setprio 0
	s_setprio 1
	v_mfma_f32_16x16x32_bf16 v[6:9], v[130:133], v[162:165], v[6:9]
	v_mfma_f32_16x16x32_bf16 v[6:9], v[134:137], v[166:169], v[6:9]
	s_setprio 0
	s_setprio 1
	v_mfma_f32_16x16x32_bf16 v[26:29], v[138:141], v[186:189], v[26:29]
	v_mfma_f32_16x16x32_bf16 v[26:29], v[142:145], v[190:193], v[26:29]
	s_setprio 0
	s_setprio 1
	v_mfma_f32_16x16x32_bf16 v[18:21], v[138:141], v[178:181], v[18:21]
	v_mfma_f32_16x16x32_bf16 v[18:21], v[142:145], v[182:185], v[18:21]
	s_setprio 0
	s_setprio 1
	v_mfma_f32_16x16x32_bf16 v[10:13], v[138:141], v[170:173], v[10:13]
	v_mfma_f32_16x16x32_bf16 v[10:13], v[142:145], v[174:177], v[10:13]
	s_setprio 2
	s_barrier
	v_mfma_f32_16x16x32_bf16 v[2:5], v[138:141], v[162:165], v[2:5]
	v_mfma_f32_16x16x32_bf16 v[2:5], v[142:145], v[166:169], v[2:5]
	s_setprio 0
	s_nop 0
	v_add_u32_e32 v142, 0x18000, v214
	v_add_u32_e32 v158, 0x1c000, v214
	ds_read_b128 v[130:133], v142
	ds_read_b128 v[134:137], v142 offset:1024
	ds_read_b128 v[138:141], v142 offset:2048
	ds_read_b128 v[142:145], v142 offset:3072
	ds_read_b128 v[146:149], v158
	ds_read_b128 v[150:153], v158 offset:1024
	ds_read_b128 v[154:157], v158 offset:2048
	ds_read_b128 v[158:161], v158 offset:3072
	ds_read_b128 v[162:165], v215 offset:32768
	ds_read_b128 v[166:169], v215 offset:33792
	ds_read_b128 v[170:173], v215 offset:34816
	ds_read_b128 v[174:177], v215 offset:35840
	ds_read_b128 v[178:181], v215 offset:36864
	ds_read_b128 v[182:185], v215 offset:37888
	ds_read_b128 v[186:189], v215 offset:38912
	ds_read_b128 v[190:193], v215 offset:39936
	s_add_u32 s38, s38, 0x4000
	s_addc_u32 s39, s39, 0
	s_mov_b32 m0, s59
	s_nop 0
	global_load_lds_dwordx4 v195, s[38:39]
	s_add_u32 m0, s59, 0x2000
	s_nop 0
	global_load_lds_dwordx4 v208, s[38:39]
	s_waitcnt vmcnt(8)
	s_waitcnt lgkmcnt(0)
	s_setprio 1
	s_barrier
	v_mfma_f32_16x16x32_bf16 v[126:129], v[130:133], v[162:165], v[126:129]
	v_mfma_f32_16x16x32_bf16 v[126:129], v[134:137], v[166:169], v[126:129]
	s_waitcnt lgkmcnt(5)
	s_setprio 0
	s_setprio 1
	v_mfma_f32_16x16x32_bf16 v[118:121], v[130:133], v[170:173], v[118:121]
	v_mfma_f32_16x16x32_bf16 v[118:121], v[134:137], v[174:177], v[118:121]
	s_waitcnt lgkmcnt(3)
	s_setprio 0
	s_setprio 1
	v_mfma_f32_16x16x32_bf16 v[110:113], v[130:133], v[178:181], v[110:113]
	v_mfma_f32_16x16x32_bf16 v[110:113], v[134:137], v[182:185], v[110:113]
	s_waitcnt lgkmcnt(1)
	s_setprio 0
	s_setprio 1
	v_mfma_f32_16x16x32_bf16 v[102:105], v[130:133], v[186:189], v[102:105]
	v_mfma_f32_16x16x32_bf16 v[102:105], v[134:137], v[190:193], v[102:105]
	s_setprio 0
	s_setprio 1
	v_mfma_f32_16x16x32_bf16 v[122:125], v[138:141], v[162:165], v[122:125]
	v_mfma_f32_16x16x32_bf16 v[122:125], v[142:145], v[166:169], v[122:125]
	s_setprio 0
	s_setprio 1
	v_mfma_f32_16x16x32_bf16 v[114:117], v[138:141], v[170:173], v[114:117]
	v_mfma_f32_16x16x32_bf16 v[114:117], v[142:145], v[174:177], v[114:117]
	s_setprio 0
	s_setprio 1
	v_mfma_f32_16x16x32_bf16 v[106:109], v[138:141], v[178:181], v[106:109]
	v_mfma_f32_16x16x32_bf16 v[106:109], v[142:145], v[182:185], v[106:109]
	s_waitcnt lgkmcnt(0)
	s_setprio 0
	s_setprio 1
	v_mfma_f32_16x16x32_bf16 v[98:101], v[138:141], v[186:189], v[98:101]
	v_mfma_f32_16x16x32_bf16 v[98:101], v[142:145], v[190:193], v[98:101]
	s_setprio 0
	s_setprio 1
	v_mfma_f32_16x16x32_bf16 v[94:97], v[146:149], v[162:165], v[94:97]
	v_mfma_f32_16x16x32_bf16 v[94:97], v[150:153], v[166:169], v[94:97]
	s_setprio 0
	s_setprio 1
	v_mfma_f32_16x16x32_bf16 v[86:89], v[146:149], v[170:173], v[86:89]
	v_mfma_f32_16x16x32_bf16 v[86:89], v[150:153], v[174:177], v[86:89]
	s_setprio 0
	s_setprio 1
	v_mfma_f32_16x16x32_bf16 v[78:81], v[146:149], v[178:181], v[78:81]
	v_mfma_f32_16x16x32_bf16 v[78:81], v[150:153], v[182:185], v[78:81]
	s_setprio 0
	s_setprio 1
	v_mfma_f32_16x16x32_bf16 v[70:73], v[146:149], v[186:189], v[70:73]
	v_mfma_f32_16x16x32_bf16 v[70:73], v[150:153], v[190:193], v[70:73]
	s_setprio 0
	s_setprio 1
	v_mfma_f32_16x16x32_bf16 v[90:93], v[154:157], v[162:165], v[90:93]
	v_mfma_f32_16x16x32_bf16 v[90:93], v[158:161], v[166:169], v[90:93]
	s_setprio 0
	s_setprio 1
	v_mfma_f32_16x16x32_bf16 v[82:85], v[154:157], v[170:173], v[82:85]
	v_mfma_f32_16x16x32_bf16 v[82:85], v[158:161], v[174:177], v[82:85]
	s_setprio 0
	s_setprio 1
	v_mfma_f32_16x16x32_bf16 v[74:77], v[154:157], v[178:181], v[74:77]
	v_mfma_f32_16x16x32_bf16 v[74:77], v[158:161], v[182:185], v[74:77]
	s_setprio 2
	s_barrier
	v_mfma_f32_16x16x32_bf16 v[66:69], v[154:157], v[186:189], v[66:69]
	v_mfma_f32_16x16x32_bf16 v[66:69], v[158:161], v[190:193], v[66:69]
	s_setprio 0
	s_nop 0
	ds_read_b128 v[162:165], v215 offset:49152
	ds_read_b128 v[166:169], v215 offset:50176
	ds_read_b128 v[170:173], v215 offset:51200
	ds_read_b128 v[174:177], v215 offset:52224
	ds_read_b128 v[178:181], v215 offset:53248
	ds_read_b128 v[182:185], v215 offset:54272
	ds_read_b128 v[186:189], v215 offset:55296
	ds_read_b128 v[190:193], v215 offset:56320
	s_mov_b32 m0, s63
	s_nop 0
	global_load_lds_dwordx4 v195, s[42:43]
	s_add_u32 m0, s63, 0x2000
	s_nop 0
	global_load_lds_dwordx4 v208, s[42:43]
	s_add_u32 s14, s14, 0xc000
	s_addc_u32 s15, s15, 0
	s_mov_b32 m0, s65
	s_nop 0
	global_load_lds_dwordx4 v195, s[14:15]
	s_add_u32 m0, s65, 0x2000
	s_nop 0
	global_load_lds_dwordx4 v208, s[14:15]
	s_nop 0
	s_mov_b32 m0, s64
	s_nop 0
	global_load_lds_dwordx4 v195, s[40:41]
	s_add_u32 m0, s64, 0x2000
	s_nop 0
	global_load_lds_dwordx4 v208, s[40:41]
	s_waitcnt vmcnt(8)
	s_waitcnt lgkmcnt(0)
	s_setprio 1
	s_barrier
	v_mfma_f32_16x16x32_bf16 v[62:65], v[130:133], v[162:165], v[62:65]
	v_mfma_f32_16x16x32_bf16 v[62:65], v[134:137], v[166:169], v[62:65]
	s_waitcnt lgkmcnt(5)
	s_setprio 0
	s_setprio 1
	v_mfma_f32_16x16x32_bf16 v[54:57], v[130:133], v[170:173], v[54:57]
	v_mfma_f32_16x16x32_bf16 v[54:57], v[134:137], v[174:177], v[54:57]
	s_waitcnt lgkmcnt(3)
	s_setprio 0
	s_setprio 1
	v_mfma_f32_16x16x32_bf16 v[46:49], v[130:133], v[178:181], v[46:49]
	v_mfma_f32_16x16x32_bf16 v[46:49], v[134:137], v[182:185], v[46:49]
	s_waitcnt lgkmcnt(1)
	s_setprio 0
	s_setprio 1
	v_mfma_f32_16x16x32_bf16 v[38:41], v[130:133], v[186:189], v[38:41]
	v_mfma_f32_16x16x32_bf16 v[38:41], v[134:137], v[190:193], v[38:41]
	s_setprio 0
	s_setprio 1
	v_mfma_f32_16x16x32_bf16 v[58:61], v[138:141], v[162:165], v[58:61]
	v_mfma_f32_16x16x32_bf16 v[58:61], v[142:145], v[166:169], v[58:61]
	s_setprio 0
	s_setprio 1
	v_mfma_f32_16x16x32_bf16 v[50:53], v[138:141], v[170:173], v[50:53]
	v_mfma_f32_16x16x32_bf16 v[50:53], v[142:145], v[174:177], v[50:53]
	s_setprio 0
	s_setprio 1
	v_mfma_f32_16x16x32_bf16 v[42:45], v[138:141], v[178:181], v[42:45]
	v_mfma_f32_16x16x32_bf16 v[42:45], v[142:145], v[182:185], v[42:45]
	s_waitcnt lgkmcnt(0)
	s_setprio 0
	s_setprio 1
	v_mfma_f32_16x16x32_bf16 v[34:37], v[138:141], v[186:189], v[34:37]
	v_mfma_f32_16x16x32_bf16 v[34:37], v[142:145], v[190:193], v[34:37]
	s_setprio 0
	s_setprio 1
	v_mfma_f32_16x16x32_bf16 v[30:33], v[146:149], v[162:165], v[30:33]
	v_mfma_f32_16x16x32_bf16 v[30:33], v[150:153], v[166:169], v[30:33]
	s_setprio 0
	s_setprio 1
	v_mfma_f32_16x16x32_bf16 v[22:25], v[146:149], v[170:173], v[22:25]
	v_mfma_f32_16x16x32_bf16 v[22:25], v[150:153], v[174:177], v[22:25]
	s_setprio 0
	s_setprio 1
	v_mfma_f32_16x16x32_bf16 v[14:17], v[146:149], v[178:181], v[14:17]
	v_mfma_f32_16x16x32_bf16 v[14:17], v[150:153], v[182:185], v[14:17]
	s_setprio 0
	s_setprio 1
	v_mfma_f32_16x16x32_bf16 v[6:9], v[146:149], v[186:189], v[6:9]
	v_mfma_f32_16x16x32_bf16 v[6:9], v[150:153], v[190:193], v[6:9]
	s_setprio 0
	s_setprio 1
	v_mfma_f32_16x16x32_bf16 v[26:29], v[154:157], v[162:165], v[26:29]
	v_mfma_f32_16x16x32_bf16 v[26:29], v[158:161], v[166:169], v[26:29]
	s_setprio 0
	s_setprio 1
	v_mfma_f32_16x16x32_bf16 v[18:21], v[154:157], v[170:173], v[18:21]
	v_mfma_f32_16x16x32_bf16 v[18:21], v[158:161], v[174:177], v[18:21]
	s_setprio 0
	s_setprio 1
	v_mfma_f32_16x16x32_bf16 v[10:13], v[154:157], v[178:181], v[10:13]
	v_mfma_f32_16x16x32_bf16 v[10:13], v[158:161], v[182:185], v[10:13]
	s_setprio 2
	s_barrier
	v_mfma_f32_16x16x32_bf16 v[2:5], v[154:157], v[186:189], v[2:5]
	v_mfma_f32_16x16x32_bf16 v[2:5], v[158:161], v[190:193], v[2:5]
	s_setprio 0
	s_nop 0
	s_cmp_gt_u32 s46, 41
	s_cbranch_scc1 .LBB0_2233
	v_mov_b32_e32 v130, v196
	s_mov_b32 s46, s22
	s_branch .LBB0_2208
